# fused row-norm tails: paired butterfly sums via DPP adds + permlane32 swap instead of ds_bpermute hops
# speedup vs baseline: 1.0047x; 1.0047x over previous
.LBB0_425:
	s_or_b64 exec, exec, s[38:39]
	s_mul_hi_i32 s53, s49, 0x9000
	s_mul_i32 s52, s49, 0x9000
	s_mul_hi_i32 s51, s50, 0x9000
	s_add_i32 s50, s52, 0x48000
	v_lshl_add_u64 v[4:5], v[134:135], 0, s[52:53]
	s_mul_hi_i32 s49, s48, 0x9000
	s_add_i32 s48, s52, 0x90000
	s_barrier
	global_load_dwordx4 v[0:3], v[132:133], off
	v_lshl_add_u64 v[8:9], v[134:135], 0, s[50:51]
	global_load_dwordx4 v[4:7], v[4:5], off
	s_mul_hi_i32 s47, s47, 0x9000
	s_add_i32 s46, s52, 0xd8000
	global_load_dwordx4 v[8:11], v[8:9], off
	v_lshl_add_u64 v[12:13], v[134:135], 0, s[48:49]
	s_mul_hi_i32 s45, s81, 0x9000
	s_add_i32 s44, s52, 0x120000
	global_load_dwordx4 v[12:15], v[12:13], off
	v_lshl_add_u64 v[16:17], v[134:135], 0, s[46:47]
	s_mul_hi_i32 s43, s80, 0x9000
	s_add_i32 s42, s52, 0x168000
	global_load_dwordx4 v[16:19], v[16:17], off
	v_lshl_add_u64 v[20:21], v[134:135], 0, s[44:45]
	s_mul_hi_i32 s41, s79, 0x9000
	s_add_i32 s40, s52, 0x1b0000
	global_load_dwordx4 v[20:23], v[20:21], off
	v_lshl_add_u64 v[24:25], v[134:135], 0, s[42:43]
	s_mul_hi_i32 s39, s78, 0x9000
	s_add_i32 s38, s52, 0x1f8000
	global_load_dwordx4 v[24:27], v[24:25], off
	v_lshl_add_u64 v[28:29], v[134:135], 0, s[40:41]
	global_load_dwordx4 v[28:31], v[28:29], off
	v_lshl_add_u64 v[32:33], v[134:135], 0, s[38:39]
	global_load_dwordx4 v[32:35], v[32:33], off
	s_lshl_b32 s38, s76, 6
	s_ashr_i32 s39, s82, 3
	s_add_i32 s38, s77, s38
	s_and_b32 s39, s39, -8
	s_add_i32 s38, s38, s39
	s_ashr_i32 s39, s38, 31
	s_lshl_b64 s[40:41], s[38:39], 12
	v_lshl_add_u64 v[36:37], v[136:137], 0, s[40:41]
	s_or_b32 s44, s38, 1
	s_ashr_i32 s45, s44, 31
	s_lshl_b64 s[40:41], s[44:45], 12
	v_mov_b64_e32 v[88:89], s[34:35]
	s_or_b32 s42, s38, 2
	s_ashr_i32 s43, s42, 31
	s_lshl_b64 s[48:49], s[42:43], 12
	s_lshl_b64 s[46:47], s[38:39], 11
	s_waitcnt vmcnt(7)
	v_pk_add_f32 v[2:3], v[2:3], v[6:7]
	v_pk_add_f32 v[0:1], v[0:1], v[4:5]
	s_waitcnt vmcnt(6)
	v_pk_add_f32 v[2:3], v[2:3], v[10:11]
	v_pk_add_f32 v[0:1], v[0:1], v[8:9]
	v_lshl_add_u64 v[8:9], v[136:137], 0, s[40:41]
	s_or_b32 s40, s38, 3
	s_waitcnt vmcnt(5)
	v_pk_add_f32 v[2:3], v[2:3], v[14:15]
	v_pk_add_f32 v[0:1], v[0:1], v[12:13]
	s_ashr_i32 s41, s40, 31
	s_lshl_b64 s[50:51], s[40:41], 12
	s_waitcnt vmcnt(4)
	v_pk_add_f32 v[2:3], v[2:3], v[18:19]
	v_pk_add_f32 v[0:1], v[0:1], v[16:17]
	s_waitcnt vmcnt(3)
	v_pk_add_f32 v[2:3], v[2:3], v[22:23]
	v_pk_add_f32 v[0:1], v[0:1], v[20:21]
	s_waitcnt vmcnt(2)
	v_pk_add_f32 v[2:3], v[2:3], v[26:27]
	v_pk_add_f32 v[0:1], v[0:1], v[24:25]
	s_waitcnt vmcnt(1)
	v_pk_add_f32 v[2:3], v[2:3], v[30:31]
	v_pk_add_f32 v[0:1], v[0:1], v[28:29]
	s_waitcnt vmcnt(0)
	v_pk_add_f32 v[2:3], v[2:3], v[34:35]
	v_pk_add_f32 v[0:1], v[0:1], v[32:33]
	v_pk_add_f32 v[4:5], v[2:3], 1.0 op_sel_hi:[1,0]
	v_pk_add_f32 v[6:7], v[0:1], 1.0 op_sel_hi:[1,0]
	v_cndmask_b32_e64 v3, v5, v3, s[6:7]
	v_cndmask_b32_e64 v2, v4, v2, s[6:7]
	v_cndmask_b32_e64 v1, v7, v1, s[6:7]
	v_cndmask_b32_e64 v0, v6, v0, s[6:7]
	ds_write_b128 v183, v[0:3]
	s_waitcnt lgkmcnt(0)
	s_barrier
	global_load_dwordx4 v[108:111], v[138:139], off
	global_load_dwordx4 v[112:115], v[142:143], off
	global_load_dwordx4 v[116:119], v[144:145], off
	global_load_dwordx4 v[120:123], v[146:147], off
	global_load_dwordx4 v[16:19], v[36:37], off
	global_load_dwordx4 v[4:7], v[36:37], off offset:1024
	global_load_dwordx4 v[80:83], v[36:37], off offset:3072
	global_load_dwordx4 v[0:3], v[36:37], off offset:2048
	global_load_dwordx4 v[76:79], v[8:9], off
	global_load_dwordx4 v[68:71], v[8:9], off offset:1024
	s_nop 0
	global_load_dwordx4 v[36:39], v[8:9], off offset:3072
	global_load_dwordx4 v[64:67], v[8:9], off offset:2048
	s_waitcnt vmcnt(3)
	v_pk_mul_f32 v[28:29], v[78:79], v[78:79]
	v_pk_mul_f32 v[8:9], v[18:19], v[18:19]
	v_pk_mul_f32 v[10:11], v[16:17], v[16:17]
	v_pk_mul_f32 v[12:13], v[6:7], v[6:7]
	v_pk_mul_f32 v[14:15], v[4:5], v[4:5]
	v_mul_f32_e32 v24, v1, v1
	v_mul_f32_e32 v26, v3, v3
	v_pk_mul_f32 v[30:31], v[76:77], v[76:77]
	s_waitcnt vmcnt(2)
	v_pk_mul_f32 v[32:33], v[70:71], v[70:71]
	v_pk_mul_f32 v[34:35], v[68:69], v[68:69]
	v_mul_f32_e32 v47, v82, v82
	v_mul_f32_e32 v48, v83, v83
	v_pk_mov_b32 v[44:45], v[10:11], v[8:9] op_sel:[1, 0]
	v_mov_b32_e32 v11, v9
	v_pk_mov_b32 v[8:9], v[14:15], v[12:13] op_sel:[1, 0]
	v_mov_b32_e32 v15, v13
	v_pk_fma_f32 v[12:13], v[0:1], v[0:1], v[24:25] op_sel_hi:[1, 1, 0]
	v_pk_fma_f32 v[24:25], v[2:3], v[2:3], v[26:27] op_sel_hi:[1, 1, 0]
	v_pk_mov_b32 v[26:27], v[30:31], v[28:29] op_sel:[1, 0]
	v_mov_b32_e32 v31, v29
	v_pk_mov_b32 v[28:29], v[34:35], v[32:33] op_sel:[1, 0]
	v_mov_b32_e32 v35, v33
	v_mul_f32_e32 v43, v80, v80
	s_waitcnt vmcnt(0)
	v_mul_f32_e32 v40, v65, v65
	v_mul_f32_e32 v42, v67, v67
	v_pk_add_f32 v[10:11], v[44:45], v[10:11]
	v_pk_add_f32 v[8:9], v[8:9], v[14:15]
	v_mov_b32_e32 v13, v47
	v_mov_b32_e32 v25, v48
	v_pk_add_f32 v[14:15], v[26:27], v[30:31]
	v_pk_add_f32 v[26:27], v[28:29], v[34:35]
	v_mul_f32_e32 v46, v81, v81
	v_mul_f32_e32 v49, v36, v36
	v_mul_f32_e32 v50, v37, v37
	v_mul_f32_e32 v51, v38, v38
	v_mul_f32_e32 v52, v39, v39
	v_pk_fma_f32 v[32:33], v[64:65], v[64:65], v[40:41] op_sel_hi:[1, 1, 0]
	v_pk_fma_f32 v[40:41], v[66:67], v[66:67], v[42:43] op_sel_hi:[1, 1, 0]
	v_pk_add_f32 v[10:11], v[10:11], v[10:11] op_sel:[0, 1] op_sel_hi:[1, 0]
	v_pk_add_f32 v[8:9], v[8:9], v[8:9] op_sel:[0, 1] op_sel_hi:[1, 0]
	v_pk_add_f32 v[12:13], v[12:13], v[24:25]
	v_pk_add_f32 v[14:15], v[14:15], v[14:15] op_sel:[0, 1] op_sel_hi:[1, 0]
	v_pk_add_f32 v[24:25], v[26:27], v[26:27] op_sel:[0, 1] op_sel_hi:[1, 0]
	v_mov_b32_e32 v33, v51
	v_mov_b32_e32 v41, v52
	v_mov_b32_e32 v11, v43
	v_mov_b32_e32 v9, v46
	v_mov_b32_e32 v15, v49
	v_mov_b32_e32 v25, v50
	v_pk_add_f32 v[26:27], v[32:33], v[40:41]
	v_pk_add_f32 v[8:9], v[10:11], v[8:9]
	v_pk_add_f32 v[10:11], v[14:15], v[24:25]
	v_pk_add_f32 v[8:9], v[8:9], v[12:13]
	v_pk_add_f32 v[10:11], v[10:11], v[26:27]
	v_mov_b32_e32 v13, v8
	v_mov_b32_e32 v12, v10
	v_mov_b32_e32 v8, v11
	v_pk_add_f32 v[8:9], v[12:13], v[8:9]
	v_lshl_add_u64 v[12:13], v[136:137], 0, s[48:49]
	v_lshl_add_u64 v[14:15], v[136:137], 0, s[50:51]
	global_load_dwordx4 v[72:75], v[12:13], off
	global_load_dwordx4 v[60:63], v[12:13], off offset:1024
	global_load_dwordx4 v[56:59], v[12:13], off offset:2048
	global_load_dwordx4 v[52:55], v[12:13], off offset:3072
	global_load_dwordx4 v[48:51], v[14:15], off
	global_load_dwordx4 v[44:47], v[14:15], off offset:1024
	s_waitcnt lgkmcnt(0)
	s_nop 1
	v_add_f32_dpp v8, v8, v8 quad_perm:[1,0,3,2] row_mask:0xf bank_mask:0xf
	v_add_f32_dpp v9, v9, v9 quad_perm:[1,0,3,2] row_mask:0xf bank_mask:0xf
	global_load_dwordx4 v[40:43], v[14:15], off offset:2048
	global_load_dwordx4 v[32:35], v[14:15], off offset:3072
	v_lshl_add_u64 v[24:25], v[140:141], 0, s[46:47]
	s_add_u32 s46, s20, s46
	s_addc_u32 s47, s21, s47
	s_waitcnt lgkmcnt(0)
	s_nop 1
	v_add_f32_dpp v8, v8, v8 quad_perm:[2,3,0,1] row_mask:0xf bank_mask:0xf
	v_add_f32_dpp v9, v9, v9 quad_perm:[2,3,0,1] row_mask:0xf bank_mask:0xf
	s_lshl_b64 s[44:45], s[44:45], 11
	s_waitcnt lgkmcnt(0)
	s_nop 1
	v_add_f32_dpp v8, v8, v8 row_half_mirror row_mask:0xf bank_mask:0xf
	v_add_f32_dpp v9, v9, v9 row_half_mirror row_mask:0xf bank_mask:0xf
	s_waitcnt lgkmcnt(0)
	s_nop 1
	v_add_f32_dpp v8, v8, v8 row_mirror row_mask:0xf bank_mask:0xf
	v_add_f32_dpp v9, v9, v9 row_mirror row_mask:0xf bank_mask:0xf
	ds_bpermute_b32 v11, v188, v9
	ds_bpermute_b32 v10, v188, v8
	s_waitcnt lgkmcnt(0)
	v_pk_add_f32 v[8:9], v[8:9], v[10:11]
	s_waitcnt lgkmcnt(0)
	v_mov_b32_e32 v10, v8
	v_mov_b32_e32 v11, v9
	s_nop 1
	v_permlane32_swap_b32_e32 v10, v8
	v_permlane32_swap_b32_e32 v11, v9
	v_pk_add_f32 v[8:9], v[8:9], v[10:11]
	s_nop 0
	v_pk_fma_f32 v[90:91], v[8:9], s[30:31], v[88:89] op_sel_hi:[1, 0, 0]
	s_waitcnt vmcnt(4)
	v_mul_f32_e32 v99, v53, v53
	v_mul_f32_e32 v8, 0x4b800000, v91
	v_cmp_gt_f32_e32 vcc, s73, v91
	s_waitcnt vmcnt(2)
	v_pk_mul_f32 v[94:95], v[44:45], v[44:45]
	v_mul_f32_e32 v102, v54, v54
	v_cndmask_b32_e32 v8, v91, v8, vcc
	v_rsq_f32_e32 v26, v8
	ds_read_b128 v[8:11], v190
	ds_read_b128 v[12:15], v191
	s_waitcnt vmcnt(1)
	v_mul_f32_e32 v96, v41, v41
	v_mul_f32_e32 v98, v43, v43
	v_mul_f32_e32 v27, 0x45800000, v26
	v_cndmask_b32_e32 v92, v26, v27, vcc
	v_pk_mul_f32 v[18:19], v[18:19], v[92:93] op_sel_hi:[1, 0]
	v_pk_mul_f32 v[16:17], v[16:17], v[92:93] op_sel_hi:[1, 0]
	v_pk_mul_f32 v[18:19], v[110:111], v[18:19]
	v_pk_mul_f32 v[16:17], v[108:109], v[16:17]
	s_waitcnt lgkmcnt(0)
	v_pk_fma_f32 v[18:19], v[14:15], v[18:19], v[10:11]
	v_pk_fma_f32 v[16:17], v[12:13], v[16:17], v[8:9]
	v_pk_mul_f32 v[6:7], v[6:7], v[92:93] op_sel_hi:[1, 0]
	v_cvt_pk_bf16_f32 v16, v16, v17
	v_cvt_pk_bf16_f32 v17, v18, v19
	global_store_dwordx2 v[24:25], v[16:17], off
	ds_read_b128 v[16:19], v192
	ds_read_b128 v[20:23], v193
	v_pk_mul_f32 v[4:5], v[4:5], v[92:93] op_sel_hi:[1, 0]
	v_pk_mul_f32 v[2:3], v[2:3], v[92:93] op_sel_hi:[1, 0]
	v_pk_mul_f32 v[0:1], v[0:1], v[92:93] op_sel_hi:[1, 0]
	v_pk_mul_f32 v[82:83], v[82:83], v[92:93] op_sel_hi:[1, 0]
	v_pk_mul_f32 v[80:81], v[80:81], v[92:93] op_sel_hi:[1, 0]
	v_cmp_gt_f32_e32 vcc, s73, v90
	v_pk_mul_f32 v[92:93], v[46:47], v[46:47]
	v_mul_f32_e32 v103, v55, v55
	s_waitcnt vmcnt(1)
	v_mul_f32_e32 v104, v32, v32
	v_mul_f32_e32 v105, v33, v33
	v_mul_f32_e32 v106, v34, v34
	v_mul_f32_e32 v107, v35, v35
	v_pk_mul_f32 v[4:5], v[112:113], v[4:5]
	v_pk_mul_f32 v[6:7], v[114:115], v[6:7]
	s_waitcnt lgkmcnt(0)
	v_pk_fma_f32 v[4:5], v[20:21], v[4:5], v[16:17]
	v_pk_fma_f32 v[6:7], v[22:23], v[6:7], v[18:19]
	v_cvt_pk_bf16_f32 v4, v4, v5
	v_cvt_pk_bf16_f32 v5, v6, v7
	global_store_dwordx2 v200, v[4:5], s[46:47]
	ds_read_b128 v[24:27], v194
	ds_read_b128 v[28:31], v195
	v_pk_mul_f32 v[0:1], v[116:117], v[0:1]
	v_pk_mul_f32 v[2:3], v[118:119], v[2:3]
	s_waitcnt lgkmcnt(0)
	v_pk_fma_f32 v[0:1], v[28:29], v[0:1], v[24:25]
	v_pk_fma_f32 v[2:3], v[30:31], v[2:3], v[26:27]
	v_cvt_pk_bf16_f32 v0, v0, v1
	v_cvt_pk_bf16_f32 v1, v2, v3
	global_store_dwordx2 v201, v[0:1], s[46:47]
	ds_read_b128 v[0:3], v196
	ds_read_b128 v[4:7], v197
	v_pk_mul_f32 v[80:81], v[80:81], v[120:121]
	v_pk_mul_f32 v[82:83], v[82:83], v[122:123]
	s_waitcnt lgkmcnt(0)
	v_pk_fma_f32 v[80:81], v[80:81], v[4:5], v[0:1]
	v_pk_fma_f32 v[82:83], v[82:83], v[6:7], v[2:3]
	v_cvt_pk_bf16_f32 v80, v80, v81
	v_cvt_pk_bf16_f32 v81, v82, v83
	global_store_dwordx2 v210, v[80:81], s[46:47]
	v_mul_f32_e32 v84, 0x4b800000, v90
	v_cndmask_b32_e32 v84, v90, v84, vcc
	v_rsq_f32_e32 v86, v84
	v_lshl_add_u64 v[84:85], v[140:141], 0, s[44:45]
	s_add_u32 s44, s20, s44
	s_addc_u32 s45, s21, s45
	v_mul_f32_e32 v87, 0x45800000, v86
	v_cndmask_b32_e32 v86, v86, v87, vcc
	v_pk_mul_f32 v[78:79], v[78:79], v[86:87] op_sel_hi:[1, 0]
	v_pk_mul_f32 v[76:77], v[76:77], v[86:87] op_sel_hi:[1, 0]
	v_pk_mul_f32 v[70:71], v[70:71], v[86:87] op_sel_hi:[1, 0]
	v_pk_mul_f32 v[68:69], v[68:69], v[86:87] op_sel_hi:[1, 0]
	v_pk_mul_f32 v[66:67], v[66:67], v[86:87] op_sel_hi:[1, 0]
	v_pk_mul_f32 v[64:65], v[64:65], v[86:87] op_sel_hi:[1, 0]
	v_mul_f32_e32 v87, v52, v52
	v_pk_mul_f32 v[38:39], v[38:39], v[86:87] op_sel_hi:[1, 0]
	v_pk_mul_f32 v[36:37], v[36:37], v[86:87] op_sel_hi:[1, 0]
	v_pk_mul_f32 v[90:91], v[48:49], v[48:49]
	s_lshl_b64 s[42:43], s[42:43], 11
	v_pk_mul_f32 v[76:77], v[108:109], v[76:77]
	v_pk_mul_f32 v[78:79], v[110:111], v[78:79]
	v_pk_fma_f32 v[76:77], v[12:13], v[76:77], v[8:9]
	v_pk_fma_f32 v[78:79], v[14:15], v[78:79], v[10:11]
	v_cvt_pk_bf16_f32 v76, v76, v77
	v_cvt_pk_bf16_f32 v77, v78, v79
	global_store_dwordx2 v[84:85], v[76:77], off
	v_mul_f32_e32 v80, v57, v57
	v_mul_f32_e32 v82, v59, v59
	v_pk_mul_f32 v[84:85], v[50:51], v[50:51]
	v_pk_mul_f32 v[68:69], v[112:113], v[68:69]
	v_pk_mul_f32 v[70:71], v[114:115], v[70:71]
	v_pk_fma_f32 v[68:69], v[20:21], v[68:69], v[16:17]
	v_pk_fma_f32 v[70:71], v[22:23], v[70:71], v[18:19]
	v_cvt_pk_bf16_f32 v68, v68, v69
	v_cvt_pk_bf16_f32 v69, v70, v71
	global_store_dwordx2 v200, v[68:69], s[44:45]
	v_pk_mul_f32 v[76:77], v[62:63], v[62:63]
	v_pk_mul_f32 v[78:79], v[60:61], v[60:61]
	v_pk_mul_f32 v[64:65], v[116:117], v[64:65]
	v_pk_mul_f32 v[66:67], v[118:119], v[66:67]
	v_pk_fma_f32 v[64:65], v[28:29], v[64:65], v[24:25]
	v_pk_fma_f32 v[66:67], v[30:31], v[66:67], v[26:27]
	v_cvt_pk_bf16_f32 v64, v64, v65
	v_cvt_pk_bf16_f32 v65, v66, v67
	global_store_dwordx2 v201, v[64:65], s[44:45]
	v_pk_mul_f32 v[68:69], v[74:75], v[74:75]
	v_pk_mul_f32 v[70:71], v[72:73], v[72:73]
	v_pk_mul_f32 v[36:37], v[120:121], v[36:37]
	v_pk_mul_f32 v[38:39], v[122:123], v[38:39]
	v_pk_fma_f32 v[36:37], v[4:5], v[36:37], v[0:1]
	v_pk_fma_f32 v[38:39], v[6:7], v[38:39], v[2:3]
	v_cvt_pk_bf16_f32 v36, v36, v37
	v_cvt_pk_bf16_f32 v37, v38, v39
	global_store_dwordx2 v210, v[36:37], s[44:45]
	v_pk_mov_b32 v[100:101], v[70:71], v[68:69] op_sel:[1, 0]
	v_mov_b32_e32 v71, v69
	v_pk_mov_b32 v[68:69], v[78:79], v[76:77] op_sel:[1, 0]
	v_mov_b32_e32 v79, v77
	v_pk_fma_f32 v[76:77], v[56:57], v[56:57], v[80:81] op_sel_hi:[1, 1, 0]
	v_pk_fma_f32 v[80:81], v[58:59], v[58:59], v[82:83] op_sel_hi:[1, 1, 0]
	v_pk_mov_b32 v[82:83], v[90:91], v[84:85] op_sel:[1, 0]
	v_mov_b32_e32 v91, v85
	v_pk_mov_b32 v[84:85], v[94:95], v[92:93] op_sel:[1, 0]
	v_mov_b32_e32 v95, v93
	v_pk_add_f32 v[70:71], v[100:101], v[70:71]
	v_pk_add_f32 v[64:65], v[68:69], v[78:79]
	v_pk_add_f32 v[66:67], v[82:83], v[90:91]
	v_pk_add_f32 v[68:69], v[84:85], v[94:95]
	v_pk_fma_f32 v[92:93], v[40:41], v[40:41], v[96:97] op_sel_hi:[1, 1, 0]
	v_pk_fma_f32 v[96:97], v[42:43], v[42:43], v[98:99] op_sel_hi:[1, 1, 0]
	v_pk_add_f32 v[70:71], v[70:71], v[70:71] op_sel:[0, 1] op_sel_hi:[1, 0]
	v_pk_add_f32 v[64:65], v[64:65], v[64:65] op_sel:[0, 1] op_sel_hi:[1, 0]
	v_pk_add_f32 v[66:67], v[66:67], v[66:67] op_sel:[0, 1] op_sel_hi:[1, 0]
	v_pk_add_f32 v[68:69], v[68:69], v[68:69] op_sel:[0, 1] op_sel_hi:[1, 0]
	v_mov_b32_e32 v77, v102
	v_mov_b32_e32 v81, v103
	v_mov_b32_e32 v93, v106
	v_mov_b32_e32 v97, v107
	v_mov_b32_e32 v71, v87
	v_mov_b32_e32 v65, v99
	v_mov_b32_e32 v67, v104
	v_mov_b32_e32 v69, v105
	v_pk_add_f32 v[76:77], v[76:77], v[80:81]
	v_pk_add_f32 v[78:79], v[92:93], v[96:97]
	v_pk_add_f32 v[64:65], v[70:71], v[64:65]
	v_pk_add_f32 v[66:67], v[66:67], v[68:69]
	v_pk_add_f32 v[64:65], v[64:65], v[76:77]
	v_pk_add_f32 v[66:67], v[66:67], v[78:79]
	v_mov_b32_e32 v69, v64
	v_mov_b32_e32 v68, v66
	v_mov_b32_e32 v64, v67
	v_pk_add_f32 v[64:65], v[68:69], v[64:65]
	s_waitcnt lgkmcnt(0)
	s_nop 1
	v_add_f32_dpp v64, v64, v64 quad_perm:[1,0,3,2] row_mask:0xf bank_mask:0xf
	v_add_f32_dpp v65, v65, v65 quad_perm:[1,0,3,2] row_mask:0xf bank_mask:0xf
	s_waitcnt lgkmcnt(0)
	s_nop 1
	v_add_f32_dpp v64, v64, v64 quad_perm:[2,3,0,1] row_mask:0xf bank_mask:0xf
	v_add_f32_dpp v65, v65, v65 quad_perm:[2,3,0,1] row_mask:0xf bank_mask:0xf
	s_waitcnt lgkmcnt(0)
	s_nop 1
	v_add_f32_dpp v64, v64, v64 row_half_mirror row_mask:0xf bank_mask:0xf
	v_add_f32_dpp v65, v65, v65 row_half_mirror row_mask:0xf bank_mask:0xf
	s_waitcnt lgkmcnt(0)
	s_nop 1
	v_add_f32_dpp v64, v64, v64 row_mirror row_mask:0xf bank_mask:0xf
	v_add_f32_dpp v65, v65, v65 row_mirror row_mask:0xf bank_mask:0xf
	ds_bpermute_b32 v67, v188, v65
	ds_bpermute_b32 v66, v188, v64
	s_waitcnt lgkmcnt(0)
	v_pk_add_f32 v[64:65], v[64:65], v[66:67]
	s_waitcnt lgkmcnt(0)
	v_mov_b32_e32 v66, v64
	v_mov_b32_e32 v67, v65
	s_nop 1
	v_permlane32_swap_b32_e32 v66, v64
	v_permlane32_swap_b32_e32 v67, v65
	v_pk_add_f32 v[64:65], v[64:65], v[66:67]
	s_nop 0
	v_pk_fma_f32 v[64:65], v[64:65], s[30:31], v[88:89] op_sel_hi:[1, 0, 0]
	s_nop 0
	v_mul_f32_e32 v66, 0x4b800000, v65
	v_cmp_gt_f32_e32 vcc, s73, v65
	s_nop 1
	v_cndmask_b32_e32 v65, v65, v66, vcc
	v_rsq_f32_e32 v65, v65
	v_lshl_add_u64 v[66:67], v[140:141], 0, s[42:43]
	s_add_u32 s42, s20, s42
	s_addc_u32 s43, s21, s43
	v_mul_f32_e32 v68, 0x45800000, v65
	v_cndmask_b32_e32 v68, v65, v68, vcc
	v_pk_mul_f32 v[70:71], v[74:75], v[68:69] op_sel_hi:[1, 0]
	v_pk_mul_f32 v[72:73], v[72:73], v[68:69] op_sel_hi:[1, 0]
	v_pk_mul_f32 v[38:39], v[110:111], v[70:71]
	v_pk_mul_f32 v[36:37], v[108:109], v[72:73]
	v_pk_fma_f32 v[38:39], v[14:15], v[38:39], v[10:11]
	v_pk_fma_f32 v[36:37], v[12:13], v[36:37], v[8:9]
	v_pk_mul_f32 v[62:63], v[62:63], v[68:69] op_sel_hi:[1, 0]
	v_cvt_pk_bf16_f32 v36, v36, v37
	v_cvt_pk_bf16_f32 v37, v38, v39
	global_store_dwordx2 v[66:67], v[36:37], off
	v_pk_mul_f32 v[60:61], v[60:61], v[68:69] op_sel_hi:[1, 0]
	v_pk_mul_f32 v[58:59], v[58:59], v[68:69] op_sel_hi:[1, 0]
	v_pk_mul_f32 v[56:57], v[56:57], v[68:69] op_sel_hi:[1, 0]
	v_pk_mul_f32 v[54:55], v[54:55], v[68:69] op_sel_hi:[1, 0]
	v_pk_mul_f32 v[52:53], v[52:53], v[68:69] op_sel_hi:[1, 0]
	v_cmp_gt_f32_e32 vcc, s73, v64
	s_lshl_b64 s[40:41], s[40:41], 11
	v_pk_mul_f32 v[36:37], v[112:113], v[60:61]
	v_pk_mul_f32 v[38:39], v[114:115], v[62:63]
	v_pk_fma_f32 v[36:37], v[20:21], v[36:37], v[16:17]
	v_pk_fma_f32 v[38:39], v[22:23], v[38:39], v[18:19]
	v_cvt_pk_bf16_f32 v36, v36, v37
	v_cvt_pk_bf16_f32 v37, v38, v39
	global_store_dwordx2 v200, v[36:37], s[42:43]
	v_pk_mul_f32 v[36:37], v[116:117], v[56:57]
	v_pk_mul_f32 v[38:39], v[118:119], v[58:59]
	v_pk_fma_f32 v[36:37], v[28:29], v[36:37], v[24:25]
	v_pk_fma_f32 v[38:39], v[30:31], v[38:39], v[26:27]
	v_cvt_pk_bf16_f32 v36, v36, v37
	v_cvt_pk_bf16_f32 v37, v38, v39
	global_store_dwordx2 v201, v[36:37], s[42:43]
	v_pk_mul_f32 v[36:37], v[120:121], v[52:53]
	v_pk_mul_f32 v[38:39], v[122:123], v[54:55]
	v_pk_fma_f32 v[36:37], v[4:5], v[36:37], v[0:1]
	v_pk_fma_f32 v[38:39], v[6:7], v[38:39], v[2:3]
	v_cvt_pk_bf16_f32 v36, v36, v37
	v_cvt_pk_bf16_f32 v37, v38, v39
	global_store_dwordx2 v210, v[36:37], s[42:43]
	v_mul_f32_e32 v52, 0x4b800000, v64
	v_cndmask_b32_e32 v52, v64, v52, vcc
	v_rsq_f32_e32 v54, v52
	v_lshl_add_u64 v[52:53], v[140:141], 0, s[40:41]
	s_add_u32 s40, s20, s40
	s_addc_u32 s41, s21, s41
	v_mul_f32_e32 v55, 0x45800000, v54
	v_cndmask_b32_e32 v54, v54, v55, vcc
	v_pk_mul_f32 v[50:51], v[50:51], v[54:55] op_sel_hi:[1, 0]
	v_pk_mul_f32 v[48:49], v[48:49], v[54:55] op_sel_hi:[1, 0]
	v_pk_mul_f32 v[46:47], v[46:47], v[54:55] op_sel_hi:[1, 0]
	v_pk_mul_f32 v[44:45], v[44:45], v[54:55] op_sel_hi:[1, 0]
	v_pk_mul_f32 v[42:43], v[42:43], v[54:55] op_sel_hi:[1, 0]
	v_pk_mul_f32 v[40:41], v[40:41], v[54:55] op_sel_hi:[1, 0]
	v_pk_mul_f32 v[34:35], v[34:35], v[54:55] op_sel_hi:[1, 0]
	v_pk_mul_f32 v[32:33], v[32:33], v[54:55] op_sel_hi:[1, 0]
	s_or_b32 s44, s38, 4
	s_ashr_i32 s45, s44, 31
	s_lshl_b64 s[42:43], s[44:45], 12
	s_lshl_b64 s[44:45], s[44:45], 11
	v_lshl_add_u64 v[104:105], v[140:141], 0, s[44:45]
	v_pk_mul_f32 v[36:37], v[108:109], v[48:49]
	v_pk_mul_f32 v[38:39], v[110:111], v[50:51]
	v_pk_fma_f32 v[36:37], v[12:13], v[36:37], v[8:9]
	v_pk_fma_f32 v[38:39], v[14:15], v[38:39], v[10:11]
	v_cvt_pk_bf16_f32 v36, v36, v37
	v_cvt_pk_bf16_f32 v37, v38, v39
	global_store_dwordx2 v[52:53], v[36:37], off
	v_pk_mul_f32 v[36:37], v[112:113], v[44:45]
	v_pk_mul_f32 v[38:39], v[114:115], v[46:47]
	v_pk_fma_f32 v[36:37], v[20:21], v[36:37], v[16:17]
	v_pk_fma_f32 v[38:39], v[22:23], v[38:39], v[18:19]
	v_cvt_pk_bf16_f32 v36, v36, v37
	v_cvt_pk_bf16_f32 v37, v38, v39
	global_store_dwordx2 v200, v[36:37], s[40:41]
	v_pk_mul_f32 v[36:37], v[116:117], v[40:41]
	v_pk_mul_f32 v[38:39], v[118:119], v[42:43]
	v_pk_fma_f32 v[36:37], v[28:29], v[36:37], v[24:25]
	v_pk_fma_f32 v[38:39], v[30:31], v[38:39], v[26:27]
	v_cvt_pk_bf16_f32 v36, v36, v37
	v_cvt_pk_bf16_f32 v37, v38, v39
	global_store_dwordx2 v201, v[36:37], s[40:41]
	v_lshl_add_u64 v[40:41], v[136:137], 0, s[42:43]
	s_or_b32 s42, s38, 5
	s_ashr_i32 s43, s42, 31
	v_pk_mul_f32 v[32:33], v[120:121], v[32:33]
	v_pk_mul_f32 v[34:35], v[122:123], v[34:35]
	v_pk_fma_f32 v[32:33], v[4:5], v[32:33], v[0:1]
	v_pk_fma_f32 v[34:35], v[6:7], v[34:35], v[2:3]
	v_cvt_pk_bf16_f32 v32, v32, v33
	v_cvt_pk_bf16_f32 v33, v34, v35
	global_store_dwordx2 v210, v[32:33], s[40:41]
	global_load_dwordx4 v[90:93], v[40:41], off
	global_load_dwordx4 v[94:97], v[40:41], off offset:1024
	global_load_dwordx4 v[80:83], v[40:41], off offset:3072
	global_load_dwordx4 v[84:87], v[40:41], off offset:2048
	s_lshl_b64 s[40:41], s[42:43], 12
	v_lshl_add_u64 v[32:33], v[136:137], 0, s[40:41]
	global_load_dwordx4 v[76:79], v[32:33], off
	global_load_dwordx4 v[72:75], v[32:33], off offset:1024
	global_load_dwordx4 v[36:39], v[32:33], off offset:3072
	global_load_dwordx4 v[68:71], v[32:33], off offset:2048
	s_or_b32 s40, s38, 6
	s_or_b32 s38, s38, 7
	s_ashr_i32 s41, s40, 31
	s_ashr_i32 s39, s38, 31
	s_lshl_b64 s[46:47], s[40:41], 12
	s_lshl_b64 s[48:49], s[38:39], 12
	s_add_u32 s44, s20, s44
	s_addc_u32 s45, s21, s45
	s_lshl_b64 s[42:43], s[42:43], 11
	s_waitcnt vmcnt(7)
	v_pk_mul_f32 v[32:33], v[92:93], v[92:93]
	v_pk_mul_f32 v[34:35], v[90:91], v[90:91]
	s_waitcnt vmcnt(6)
	v_pk_mul_f32 v[40:41], v[96:97], v[96:97]
	v_pk_mul_f32 v[42:43], v[94:95], v[94:95]
	s_waitcnt vmcnt(4)
	v_mul_f32_e32 v44, v85, v85
	v_mul_f32_e32 v46, v87, v87
	s_waitcnt vmcnt(3)
	v_pk_mul_f32 v[48:49], v[78:79], v[78:79]
	v_pk_mul_f32 v[50:51], v[76:77], v[76:77]
	s_waitcnt vmcnt(2)
	v_pk_mul_f32 v[52:53], v[74:75], v[74:75]
	v_pk_mul_f32 v[54:55], v[72:73], v[72:73]
	v_mul_f32_e32 v63, v82, v82
	v_mul_f32_e32 v64, v83, v83
	v_pk_mov_b32 v[60:61], v[34:35], v[32:33] op_sel:[1, 0]
	v_mov_b32_e32 v35, v33
	v_pk_mov_b32 v[32:33], v[42:43], v[40:41] op_sel:[1, 0]
	v_mov_b32_e32 v43, v41
	v_pk_fma_f32 v[40:41], v[84:85], v[84:85], v[44:45] op_sel_hi:[1, 1, 0]
	v_pk_fma_f32 v[44:45], v[86:87], v[86:87], v[46:47] op_sel_hi:[1, 1, 0]
	v_pk_mov_b32 v[46:47], v[50:51], v[48:49] op_sel:[1, 0]
	v_mov_b32_e32 v51, v49
	v_pk_mov_b32 v[48:49], v[54:55], v[52:53] op_sel:[1, 0]
	v_mov_b32_e32 v55, v53
	v_mul_f32_e32 v59, v80, v80
	s_waitcnt vmcnt(0)
	v_mul_f32_e32 v56, v69, v69
	v_mul_f32_e32 v58, v71, v71
	v_pk_add_f32 v[34:35], v[60:61], v[34:35]
	v_pk_add_f32 v[32:33], v[32:33], v[42:43]
	v_mov_b32_e32 v41, v63
	v_mov_b32_e32 v45, v64
	v_pk_add_f32 v[42:43], v[46:47], v[50:51]
	v_pk_add_f32 v[46:47], v[48:49], v[54:55]
	v_mul_f32_e32 v62, v81, v81
	v_mul_f32_e32 v65, v36, v36
	v_mul_f32_e32 v66, v37, v37
	v_mul_f32_e32 v67, v38, v38
	v_mul_f32_e32 v102, v39, v39
	v_pk_fma_f32 v[52:53], v[68:69], v[68:69], v[56:57] op_sel_hi:[1, 1, 0]
	v_pk_fma_f32 v[56:57], v[70:71], v[70:71], v[58:59] op_sel_hi:[1, 1, 0]
	v_pk_add_f32 v[34:35], v[34:35], v[34:35] op_sel:[0, 1] op_sel_hi:[1, 0]
	v_pk_add_f32 v[32:33], v[32:33], v[32:33] op_sel:[0, 1] op_sel_hi:[1, 0]
	v_pk_add_f32 v[40:41], v[40:41], v[44:45]
	v_pk_add_f32 v[42:43], v[42:43], v[42:43] op_sel:[0, 1] op_sel_hi:[1, 0]
	v_pk_add_f32 v[44:45], v[46:47], v[46:47] op_sel:[0, 1] op_sel_hi:[1, 0]
	v_mov_b32_e32 v53, v67
	v_mov_b32_e32 v57, v102
	v_mov_b32_e32 v35, v59
	v_mov_b32_e32 v33, v62
	v_mov_b32_e32 v43, v65
	v_mov_b32_e32 v45, v66
	v_pk_add_f32 v[46:47], v[52:53], v[56:57]
	v_pk_add_f32 v[32:33], v[34:35], v[32:33]
	v_pk_add_f32 v[34:35], v[42:43], v[44:45]
	v_pk_add_f32 v[32:33], v[32:33], v[40:41]
	v_pk_add_f32 v[34:35], v[34:35], v[46:47]
	v_mov_b32_e32 v41, v32
	v_mov_b32_e32 v40, v34
	v_mov_b32_e32 v32, v35
	v_pk_add_f32 v[32:33], v[40:41], v[32:33]
	v_lshl_add_u64 v[40:41], v[136:137], 0, s[46:47]
	v_lshl_add_u64 v[102:103], v[136:137], 0, s[48:49]
	global_load_dwordx4 v[64:67], v[40:41], off
	global_load_dwordx4 v[60:63], v[40:41], off offset:1024
	global_load_dwordx4 v[56:59], v[40:41], off offset:2048
	global_load_dwordx4 v[52:55], v[40:41], off offset:3072
	s_waitcnt lgkmcnt(0)
	s_nop 1
	v_add_f32_dpp v32, v32, v32 quad_perm:[1,0,3,2] row_mask:0xf bank_mask:0xf
	v_add_f32_dpp v33, v33, v33 quad_perm:[1,0,3,2] row_mask:0xf bank_mask:0xf
	s_waitcnt lgkmcnt(0)
	s_nop 1
	v_add_f32_dpp v32, v32, v32 quad_perm:[2,3,0,1] row_mask:0xf bank_mask:0xf
	v_add_f32_dpp v33, v33, v33 quad_perm:[2,3,0,1] row_mask:0xf bank_mask:0xf
	s_waitcnt lgkmcnt(0)
	s_nop 1
	v_add_f32_dpp v32, v32, v32 row_half_mirror row_mask:0xf bank_mask:0xf
	v_add_f32_dpp v33, v33, v33 row_half_mirror row_mask:0xf bank_mask:0xf
	s_waitcnt lgkmcnt(0)
	s_nop 1
	v_add_f32_dpp v32, v32, v32 row_mirror row_mask:0xf bank_mask:0xf
	v_add_f32_dpp v33, v33, v33 row_mirror row_mask:0xf bank_mask:0xf
	ds_bpermute_b32 v35, v188, v33
	ds_bpermute_b32 v34, v188, v32
	s_waitcnt lgkmcnt(0)
	v_pk_add_f32 v[32:33], v[32:33], v[34:35]
	s_waitcnt lgkmcnt(0)
	v_mov_b32_e32 v34, v32
	v_mov_b32_e32 v35, v33
	s_nop 1
	v_permlane32_swap_b32_e32 v34, v32
	v_permlane32_swap_b32_e32 v35, v33
	v_pk_add_f32 v[32:33], v[32:33], v[34:35]
	s_nop 0
	v_pk_fma_f32 v[106:107], v[32:33], s[30:31], v[88:89] op_sel_hi:[1, 0, 0]
	s_nop 0
	v_mul_f32_e32 v32, 0x4b800000, v107
	v_cmp_gt_f32_e32 vcc, s73, v107
	s_nop 1
	v_cndmask_b32_e32 v32, v107, v32, vcc
	v_rsq_f32_e32 v107, v32
	global_load_dwordx4 v[48:51], v[102:103], off
	global_load_dwordx4 v[44:47], v[102:103], off offset:1024
	global_load_dwordx4 v[40:43], v[102:103], off offset:2048
	global_load_dwordx4 v[32:35], v[102:103], off offset:3072
	v_mul_f32_e32 v102, 0x45800000, v107
	v_cndmask_b32_e32 v102, v107, v102, vcc
	v_pk_mul_f32 v[92:93], v[92:93], v[102:103] op_sel_hi:[1, 0]
	v_pk_mul_f32 v[90:91], v[90:91], v[102:103] op_sel_hi:[1, 0]
	v_pk_mul_f32 v[92:93], v[110:111], v[92:93]
	v_pk_mul_f32 v[90:91], v[108:109], v[90:91]
	v_pk_fma_f32 v[92:93], v[14:15], v[92:93], v[10:11]
	v_pk_fma_f32 v[90:91], v[12:13], v[90:91], v[8:9]
	v_pk_mul_f32 v[96:97], v[96:97], v[102:103] op_sel_hi:[1, 0]
	v_cvt_pk_bf16_f32 v90, v90, v91
	v_cvt_pk_bf16_f32 v91, v92, v93
	global_store_dwordx2 v[104:105], v[90:91], off
	v_pk_mul_f32 v[94:95], v[94:95], v[102:103] op_sel_hi:[1, 0]
	v_pk_mul_f32 v[86:87], v[86:87], v[102:103] op_sel_hi:[1, 0]
	v_pk_mul_f32 v[84:85], v[84:85], v[102:103] op_sel_hi:[1, 0]
	v_pk_mul_f32 v[82:83], v[82:83], v[102:103] op_sel_hi:[1, 0]
	v_pk_mul_f32 v[80:81], v[80:81], v[102:103] op_sel_hi:[1, 0]
	v_cmp_gt_f32_e32 vcc, s73, v106
	s_waitcnt vmcnt(5)
	v_mul_f32_e32 v99, v53, v53
	v_mul_f32_e32 v102, v54, v54
	v_mul_f32_e32 v103, v55, v55
	s_waitcnt vmcnt(2)
	v_mul_f32_e32 v98, v43, v43
	s_waitcnt vmcnt(1)
	v_mul_f32_e32 v104, v32, v32
	v_mul_f32_e32 v105, v33, v33
	v_mul_f32_e32 v107, v35, v35
	v_pk_mul_f32 v[90:91], v[112:113], v[94:95]
	v_pk_mul_f32 v[92:93], v[114:115], v[96:97]
	v_pk_fma_f32 v[90:91], v[20:21], v[90:91], v[16:17]
	v_pk_fma_f32 v[92:93], v[22:23], v[92:93], v[18:19]
	v_cvt_pk_bf16_f32 v90, v90, v91
	v_cvt_pk_bf16_f32 v91, v92, v93
	global_store_dwordx2 v200, v[90:91], s[44:45]
	v_pk_mul_f32 v[94:95], v[44:45], v[44:45]
	v_mul_f32_e32 v96, v41, v41
	v_pk_mul_f32 v[84:85], v[116:117], v[84:85]
	v_pk_mul_f32 v[86:87], v[118:119], v[86:87]
	v_pk_fma_f32 v[84:85], v[28:29], v[84:85], v[24:25]
	v_pk_fma_f32 v[86:87], v[30:31], v[86:87], v[26:27]
	v_cvt_pk_bf16_f32 v84, v84, v85
	v_cvt_pk_bf16_f32 v85, v86, v87
	global_store_dwordx2 v201, v[84:85], s[44:45]
	v_pk_mul_f32 v[90:91], v[48:49], v[48:49]
	v_pk_mul_f32 v[92:93], v[46:47], v[46:47]
	v_pk_mul_f32 v[80:81], v[120:121], v[80:81]
	v_pk_mul_f32 v[82:83], v[122:123], v[82:83]
	v_pk_fma_f32 v[80:81], v[4:5], v[80:81], v[0:1]
	v_pk_fma_f32 v[82:83], v[6:7], v[82:83], v[2:3]
	v_cvt_pk_bf16_f32 v80, v80, v81
	v_cvt_pk_bf16_f32 v81, v82, v83
	global_store_dwordx2 v210, v[80:81], s[44:45]
	v_mul_f32_e32 v84, 0x4b800000, v106
	v_cndmask_b32_e32 v84, v106, v84, vcc
	v_rsq_f32_e32 v86, v84
	v_lshl_add_u64 v[84:85], v[140:141], 0, s[42:43]
	s_add_u32 s42, s20, s42
	s_addc_u32 s43, s21, s43
	v_mul_f32_e32 v87, 0x45800000, v86
	v_cndmask_b32_e32 v86, v86, v87, vcc
	v_pk_mul_f32 v[78:79], v[78:79], v[86:87] op_sel_hi:[1, 0]
	v_pk_mul_f32 v[76:77], v[76:77], v[86:87] op_sel_hi:[1, 0]
	v_pk_mul_f32 v[74:75], v[74:75], v[86:87] op_sel_hi:[1, 0]
	v_pk_mul_f32 v[72:73], v[72:73], v[86:87] op_sel_hi:[1, 0]
	v_pk_mul_f32 v[70:71], v[70:71], v[86:87] op_sel_hi:[1, 0]
	v_pk_mul_f32 v[68:69], v[68:69], v[86:87] op_sel_hi:[1, 0]
	v_mul_f32_e32 v87, v52, v52
	v_pk_mul_f32 v[38:39], v[38:39], v[86:87] op_sel_hi:[1, 0]
	v_pk_mul_f32 v[36:37], v[36:37], v[86:87] op_sel_hi:[1, 0]
	v_mul_f32_e32 v106, v34, v34
	s_lshl_b64 s[40:41], s[40:41], 11
	v_pk_mul_f32 v[76:77], v[108:109], v[76:77]
	v_pk_mul_f32 v[78:79], v[110:111], v[78:79]
	v_pk_fma_f32 v[76:77], v[12:13], v[76:77], v[8:9]
	v_pk_fma_f32 v[78:79], v[14:15], v[78:79], v[10:11]
	v_cvt_pk_bf16_f32 v76, v76, v77
	v_cvt_pk_bf16_f32 v77, v78, v79
	global_store_dwordx2 v[84:85], v[76:77], off
	v_mul_f32_e32 v80, v57, v57
	v_mul_f32_e32 v82, v59, v59
	v_pk_mul_f32 v[84:85], v[50:51], v[50:51]
	v_pk_mul_f32 v[72:73], v[112:113], v[72:73]
	v_pk_mul_f32 v[74:75], v[114:115], v[74:75]
	v_pk_fma_f32 v[72:73], v[20:21], v[72:73], v[16:17]
	v_pk_fma_f32 v[74:75], v[22:23], v[74:75], v[18:19]
	v_cvt_pk_bf16_f32 v72, v72, v73
	v_cvt_pk_bf16_f32 v73, v74, v75
	global_store_dwordx2 v200, v[72:73], s[42:43]
	v_pk_mul_f32 v[76:77], v[62:63], v[62:63]
	v_pk_mul_f32 v[78:79], v[60:61], v[60:61]
	v_pk_mul_f32 v[68:69], v[116:117], v[68:69]
	v_pk_mul_f32 v[70:71], v[118:119], v[70:71]
	v_pk_fma_f32 v[68:69], v[28:29], v[68:69], v[24:25]
	v_pk_fma_f32 v[70:71], v[30:31], v[70:71], v[26:27]
	v_cvt_pk_bf16_f32 v68, v68, v69
	v_cvt_pk_bf16_f32 v69, v70, v71
	global_store_dwordx2 v201, v[68:69], s[42:43]
	v_pk_mul_f32 v[72:73], v[66:67], v[66:67]
	v_pk_mul_f32 v[74:75], v[64:65], v[64:65]
	v_pk_mul_f32 v[36:37], v[120:121], v[36:37]
	v_pk_mul_f32 v[38:39], v[122:123], v[38:39]
	v_pk_fma_f32 v[36:37], v[4:5], v[36:37], v[0:1]
	v_pk_fma_f32 v[38:39], v[6:7], v[38:39], v[2:3]
	v_cvt_pk_bf16_f32 v36, v36, v37
	v_cvt_pk_bf16_f32 v37, v38, v39
	global_store_dwordx2 v210, v[36:37], s[42:43]
	v_pk_mov_b32 v[100:101], v[74:75], v[72:73] op_sel:[1, 0]
	v_mov_b32_e32 v75, v73
	v_pk_mov_b32 v[72:73], v[78:79], v[76:77] op_sel:[1, 0]
	v_mov_b32_e32 v79, v77
	v_pk_fma_f32 v[76:77], v[56:57], v[56:57], v[80:81] op_sel_hi:[1, 1, 0]
	v_pk_fma_f32 v[80:81], v[58:59], v[58:59], v[82:83] op_sel_hi:[1, 1, 0]
	v_pk_mov_b32 v[82:83], v[90:91], v[84:85] op_sel:[1, 0]
	v_mov_b32_e32 v91, v85
	v_pk_mov_b32 v[84:85], v[94:95], v[92:93] op_sel:[1, 0]
	v_mov_b32_e32 v95, v93
	v_pk_add_f32 v[74:75], v[100:101], v[74:75]
	v_pk_add_f32 v[68:69], v[72:73], v[78:79]
	v_pk_add_f32 v[70:71], v[82:83], v[90:91]
	v_pk_add_f32 v[72:73], v[84:85], v[94:95]
	v_pk_fma_f32 v[92:93], v[40:41], v[40:41], v[96:97] op_sel_hi:[1, 1, 0]
	v_pk_fma_f32 v[96:97], v[42:43], v[42:43], v[98:99] op_sel_hi:[1, 1, 0]
	v_pk_add_f32 v[74:75], v[74:75], v[74:75] op_sel:[0, 1] op_sel_hi:[1, 0]
	v_pk_add_f32 v[68:69], v[68:69], v[68:69] op_sel:[0, 1] op_sel_hi:[1, 0]
	v_pk_add_f32 v[70:71], v[70:71], v[70:71] op_sel:[0, 1] op_sel_hi:[1, 0]
	v_pk_add_f32 v[72:73], v[72:73], v[72:73] op_sel:[0, 1] op_sel_hi:[1, 0]
	v_mov_b32_e32 v77, v102
	v_mov_b32_e32 v81, v103
	v_mov_b32_e32 v93, v106
	v_mov_b32_e32 v97, v107
	v_mov_b32_e32 v75, v87
	v_mov_b32_e32 v69, v99
	v_mov_b32_e32 v71, v104
	v_mov_b32_e32 v73, v105
	v_pk_add_f32 v[76:77], v[76:77], v[80:81]
	v_pk_add_f32 v[78:79], v[92:93], v[96:97]
	v_pk_add_f32 v[68:69], v[74:75], v[68:69]
	v_pk_add_f32 v[70:71], v[70:71], v[72:73]
	v_pk_add_f32 v[68:69], v[68:69], v[76:77]
	v_pk_add_f32 v[70:71], v[70:71], v[78:79]
	v_mov_b32_e32 v73, v68
	v_mov_b32_e32 v72, v70
	v_mov_b32_e32 v68, v71
	v_pk_add_f32 v[68:69], v[72:73], v[68:69]
	s_waitcnt lgkmcnt(0)
	s_nop 1
	v_add_f32_dpp v68, v68, v68 quad_perm:[1,0,3,2] row_mask:0xf bank_mask:0xf
	v_add_f32_dpp v69, v69, v69 quad_perm:[1,0,3,2] row_mask:0xf bank_mask:0xf
	s_waitcnt lgkmcnt(0)
	s_nop 1
	v_add_f32_dpp v68, v68, v68 quad_perm:[2,3,0,1] row_mask:0xf bank_mask:0xf
	v_add_f32_dpp v69, v69, v69 quad_perm:[2,3,0,1] row_mask:0xf bank_mask:0xf
	s_waitcnt lgkmcnt(0)
	s_nop 1
	v_add_f32_dpp v68, v68, v68 row_half_mirror row_mask:0xf bank_mask:0xf
	v_add_f32_dpp v69, v69, v69 row_half_mirror row_mask:0xf bank_mask:0xf
	s_waitcnt lgkmcnt(0)
	s_nop 1
	v_add_f32_dpp v68, v68, v68 row_mirror row_mask:0xf bank_mask:0xf
	v_add_f32_dpp v69, v69, v69 row_mirror row_mask:0xf bank_mask:0xf
	ds_bpermute_b32 v71, v188, v69
	ds_bpermute_b32 v70, v188, v68
	s_waitcnt lgkmcnt(0)
	v_pk_add_f32 v[68:69], v[68:69], v[70:71]
	s_waitcnt lgkmcnt(0)
	v_mov_b32_e32 v70, v68
	v_mov_b32_e32 v71, v69
	s_nop 1
	v_permlane32_swap_b32_e32 v70, v68
	v_permlane32_swap_b32_e32 v71, v69
	v_pk_add_f32 v[68:69], v[68:69], v[70:71]
	s_nop 0
	v_pk_fma_f32 v[68:69], v[68:69], s[30:31], v[88:89] op_sel_hi:[1, 0, 0]
	s_nop 0
	v_mul_f32_e32 v70, 0x4b800000, v69
	v_cmp_gt_f32_e32 vcc, s73, v69
	s_nop 1
	v_cndmask_b32_e32 v69, v69, v70, vcc
	v_rsq_f32_e32 v69, v69
	v_lshl_add_u64 v[70:71], v[140:141], 0, s[40:41]
	s_add_u32 s40, s20, s40
	s_addc_u32 s41, s21, s41
	v_mul_f32_e32 v72, 0x45800000, v69
	v_cndmask_b32_e32 v72, v69, v72, vcc
	v_pk_mul_f32 v[66:67], v[66:67], v[72:73] op_sel_hi:[1, 0]
	v_pk_mul_f32 v[64:65], v[64:65], v[72:73] op_sel_hi:[1, 0]
	v_pk_mul_f32 v[38:39], v[110:111], v[66:67]
	v_pk_mul_f32 v[36:37], v[108:109], v[64:65]
	v_pk_fma_f32 v[38:39], v[14:15], v[38:39], v[10:11]
	v_pk_fma_f32 v[36:37], v[12:13], v[36:37], v[8:9]
	v_pk_mul_f32 v[62:63], v[62:63], v[72:73] op_sel_hi:[1, 0]
	v_cvt_pk_bf16_f32 v36, v36, v37
	v_cvt_pk_bf16_f32 v37, v38, v39
	global_store_dwordx2 v[70:71], v[36:37], off
	v_pk_mul_f32 v[60:61], v[60:61], v[72:73] op_sel_hi:[1, 0]
	v_pk_mul_f32 v[58:59], v[58:59], v[72:73] op_sel_hi:[1, 0]
	v_pk_mul_f32 v[56:57], v[56:57], v[72:73] op_sel_hi:[1, 0]
	v_pk_mul_f32 v[54:55], v[54:55], v[72:73] op_sel_hi:[1, 0]
	v_pk_mul_f32 v[52:53], v[52:53], v[72:73] op_sel_hi:[1, 0]
	v_cmp_gt_f32_e32 vcc, s73, v68
	s_lshl_b64 s[38:39], s[38:39], 11
	v_pk_mul_f32 v[36:37], v[112:113], v[60:61]
	v_pk_mul_f32 v[38:39], v[114:115], v[62:63]
	v_pk_fma_f32 v[36:37], v[20:21], v[36:37], v[16:17]
	v_pk_fma_f32 v[38:39], v[22:23], v[38:39], v[18:19]
	v_cvt_pk_bf16_f32 v36, v36, v37
	v_cvt_pk_bf16_f32 v37, v38, v39
	global_store_dwordx2 v200, v[36:37], s[40:41]
	v_pk_mul_f32 v[36:37], v[116:117], v[56:57]
	v_pk_mul_f32 v[38:39], v[118:119], v[58:59]
	v_pk_fma_f32 v[36:37], v[28:29], v[36:37], v[24:25]
	v_pk_fma_f32 v[38:39], v[30:31], v[38:39], v[26:27]
	v_cvt_pk_bf16_f32 v36, v36, v37
	v_cvt_pk_bf16_f32 v37, v38, v39
	global_store_dwordx2 v201, v[36:37], s[40:41]
	v_pk_mul_f32 v[36:37], v[120:121], v[52:53]
	v_pk_mul_f32 v[38:39], v[122:123], v[54:55]
	v_pk_fma_f32 v[36:37], v[4:5], v[36:37], v[0:1]
	v_pk_fma_f32 v[38:39], v[6:7], v[38:39], v[2:3]
	v_cvt_pk_bf16_f32 v36, v36, v37
	v_cvt_pk_bf16_f32 v37, v38, v39
	global_store_dwordx2 v210, v[36:37], s[40:41]
	v_mul_f32_e32 v52, 0x4b800000, v68
	v_cndmask_b32_e32 v52, v68, v52, vcc
	v_rsq_f32_e32 v54, v52
	v_lshl_add_u64 v[52:53], v[140:141], 0, s[38:39]
	s_add_u32 s38, s20, s38
	s_addc_u32 s39, s21, s39
	v_mul_f32_e32 v55, 0x45800000, v54
	v_cndmask_b32_e32 v54, v54, v55, vcc
	v_pk_mul_f32 v[50:51], v[50:51], v[54:55] op_sel_hi:[1, 0]
	v_pk_mul_f32 v[48:49], v[48:49], v[54:55] op_sel_hi:[1, 0]
	s_and_b64 vcc, exec, s[8:9]
	s_mov_b64 s[8:9], -1
	v_pk_mul_f32 v[36:37], v[108:109], v[48:49]
	v_pk_mul_f32 v[38:39], v[110:111], v[50:51]
	v_pk_fma_f32 v[8:9], v[12:13], v[36:37], v[8:9]
	v_pk_fma_f32 v[10:11], v[14:15], v[38:39], v[10:11]
	v_cvt_pk_bf16_f32 v8, v8, v9
	v_cvt_pk_bf16_f32 v9, v10, v11
	global_store_dwordx2 v[52:53], v[8:9], off
	v_pk_mul_f32 v[12:13], v[46:47], v[54:55] op_sel_hi:[1, 0]
	v_pk_mul_f32 v[14:15], v[44:45], v[54:55] op_sel_hi:[1, 0]
	v_pk_mul_f32 v[10:11], v[114:115], v[12:13]
	v_pk_mul_f32 v[8:9], v[112:113], v[14:15]
	v_pk_fma_f32 v[10:11], v[22:23], v[10:11], v[18:19]
	v_pk_fma_f32 v[8:9], v[20:21], v[8:9], v[16:17]
	v_pk_mul_f32 v[12:13], v[42:43], v[54:55] op_sel_hi:[1, 0]
	v_cvt_pk_bf16_f32 v8, v8, v9
	v_cvt_pk_bf16_f32 v9, v10, v11
	global_store_dwordx2 v200, v[8:9], s[38:39]
	v_pk_mul_f32 v[14:15], v[40:41], v[54:55] op_sel_hi:[1, 0]
	v_pk_mul_f32 v[10:11], v[118:119], v[12:13]
	v_pk_mul_f32 v[8:9], v[116:117], v[14:15]
	v_pk_fma_f32 v[10:11], v[30:31], v[10:11], v[26:27]
	v_pk_fma_f32 v[8:9], v[28:29], v[8:9], v[24:25]
	v_pk_mul_f32 v[12:13], v[34:35], v[54:55] op_sel_hi:[1, 0]
	v_cvt_pk_bf16_f32 v8, v8, v9
	v_cvt_pk_bf16_f32 v9, v10, v11
	global_store_dwordx2 v201, v[8:9], s[38:39]
	v_pk_mul_f32 v[14:15], v[32:33], v[54:55] op_sel_hi:[1, 0]
	v_pk_mul_f32 v[10:11], v[122:123], v[12:13]
	v_pk_mul_f32 v[8:9], v[120:121], v[14:15]
	v_pk_fma_f32 v[2:3], v[6:7], v[10:11], v[2:3]
	v_pk_fma_f32 v[0:1], v[4:5], v[8:9], v[0:1]
	s_nop 0
	v_cvt_pk_bf16_f32 v0, v0, v1
	v_cvt_pk_bf16_f32 v1, v2, v3
	global_store_dwordx2 v210, v[0:1], s[38:39]
	s_cbranch_vccnz .LBB0_396
	s_andn2_b64 vcc, exec, s[10:11]
	s_cbranch_vccnz .LBB0_395
	s_barrier
	s_branch .LBB0_395

.LBB0_1188:
	s_or_b64 exec, exec, s[46:47]
	s_mul_hi_i32 s59, s54, 0x9000
	s_mul_i32 s58, s54, 0x9000
	s_mul_hi_i32 s57, s55, 0x9000
	s_add_i32 s56, s58, 0x48000
	v_lshl_add_u64 v[4:5], v[138:139], 0, s[58:59]
	s_mul_hi_i32 s55, s53, 0x9000
	s_add_i32 s54, s58, 0x90000
	s_barrier
	global_load_dwordx4 v[0:3], v[136:137], off
	v_lshl_add_u64 v[8:9], v[138:139], 0, s[56:57]
	global_load_dwordx4 v[4:7], v[4:5], off
	s_mul_hi_i32 s53, s52, 0x9000
	s_add_i32 s52, s58, 0xd8000
	global_load_dwordx4 v[8:11], v[8:9], off
	v_lshl_add_u64 v[12:13], v[138:139], 0, s[54:55]
	s_mul_hi_i32 s51, s81, 0x9000
	s_add_i32 s50, s58, 0x120000
	global_load_dwordx4 v[12:15], v[12:13], off
	v_lshl_add_u64 v[16:17], v[138:139], 0, s[52:53]
	s_mul_hi_i32 s49, s80, 0x9000
	s_add_i32 s48, s58, 0x168000
	global_load_dwordx4 v[16:19], v[16:17], off
	v_lshl_add_u64 v[20:21], v[138:139], 0, s[50:51]
	s_mul_hi_i32 s47, s43, 0x9000
	s_add_i32 s46, s58, 0x1b0000
	global_load_dwordx4 v[20:23], v[20:21], off
	v_lshl_add_u64 v[24:25], v[138:139], 0, s[48:49]
	s_mul_hi_i32 s45, s37, 0x9000
	s_add_i32 s44, s58, 0x1f8000
	global_load_dwordx4 v[24:27], v[24:25], off
	v_lshl_add_u64 v[28:29], v[138:139], 0, s[46:47]
	global_load_dwordx4 v[28:31], v[28:29], off
	v_lshl_add_u64 v[32:33], v[138:139], 0, s[44:45]
	global_load_dwordx4 v[32:35], v[32:33], off
	s_lshl_b32 s37, s42, 6
	s_ashr_i32 s42, s82, 3
	s_add_i32 s35, s35, s37
	s_and_b32 s37, s42, -8
	s_add_i32 s42, s35, s37
	s_ashr_i32 s43, s42, 31
	s_lshl_b64 s[44:45], s[42:43], 12
	v_lshl_add_u64 v[36:37], v[140:141], 0, s[44:45]
	s_or_b32 s48, s42, 1
	s_ashr_i32 s49, s48, 31
	s_lshl_b64 s[44:45], s[48:49], 12
	v_mov_b64_e32 v[84:85], s[30:31]
	s_or_b32 s46, s42, 2
	s_ashr_i32 s47, s46, 31
	s_lshl_b64 s[52:53], s[46:47], 12
	s_lshl_b64 s[50:51], s[42:43], 11
	s_waitcnt vmcnt(7)
	v_pk_add_f32 v[2:3], v[2:3], v[6:7]
	v_pk_add_f32 v[0:1], v[0:1], v[4:5]
	s_waitcnt vmcnt(6)
	v_pk_add_f32 v[2:3], v[2:3], v[10:11]
	v_pk_add_f32 v[0:1], v[0:1], v[8:9]
	v_lshl_add_u64 v[8:9], v[140:141], 0, s[44:45]
	s_or_b32 s44, s42, 3
	s_waitcnt vmcnt(5)
	v_pk_add_f32 v[2:3], v[2:3], v[14:15]
	v_pk_add_f32 v[0:1], v[0:1], v[12:13]
	s_ashr_i32 s45, s44, 31
	s_lshl_b64 s[54:55], s[44:45], 12
	s_waitcnt vmcnt(4)
	v_pk_add_f32 v[2:3], v[2:3], v[18:19]
	v_pk_add_f32 v[0:1], v[0:1], v[16:17]
	s_waitcnt vmcnt(3)
	v_pk_add_f32 v[2:3], v[2:3], v[22:23]
	v_pk_add_f32 v[0:1], v[0:1], v[20:21]
	s_waitcnt vmcnt(2)
	v_pk_add_f32 v[2:3], v[2:3], v[26:27]
	v_pk_add_f32 v[0:1], v[0:1], v[24:25]
	s_waitcnt vmcnt(1)
	v_pk_add_f32 v[2:3], v[2:3], v[30:31]
	v_pk_add_f32 v[0:1], v[0:1], v[28:29]
	s_waitcnt vmcnt(0)
	v_pk_add_f32 v[2:3], v[2:3], v[34:35]
	v_pk_add_f32 v[0:1], v[0:1], v[32:33]
	v_pk_add_f32 v[4:5], v[2:3], 1.0 op_sel_hi:[1,0]
	v_pk_add_f32 v[6:7], v[0:1], 1.0 op_sel_hi:[1,0]
	v_cndmask_b32_e64 v3, v5, v3, s[6:7]
	v_cndmask_b32_e64 v2, v4, v2, s[6:7]
	v_cndmask_b32_e64 v1, v7, v1, s[6:7]
	v_cndmask_b32_e64 v0, v6, v0, s[6:7]
	ds_write_b128 v183, v[0:3]
	s_waitcnt lgkmcnt(0)
	s_barrier
	global_load_dwordx4 v[108:111], v[142:143], off
	global_load_dwordx4 v[112:115], v[146:147], off
	global_load_dwordx4 v[116:119], v[148:149], off
	global_load_dwordx4 v[120:123], v[150:151], off
	global_load_dwordx4 v[16:19], v[36:37], off
	global_load_dwordx4 v[4:7], v[36:37], off offset:1024
	global_load_dwordx4 v[80:83], v[36:37], off offset:3072
	global_load_dwordx4 v[0:3], v[36:37], off offset:2048
	global_load_dwordx4 v[76:79], v[8:9], off
	global_load_dwordx4 v[68:71], v[8:9], off offset:1024
	s_nop 0
	global_load_dwordx4 v[36:39], v[8:9], off offset:3072
	global_load_dwordx4 v[64:67], v[8:9], off offset:2048
	s_waitcnt vmcnt(3)
	v_pk_mul_f32 v[28:29], v[78:79], v[78:79]
	v_pk_mul_f32 v[8:9], v[18:19], v[18:19]
	v_pk_mul_f32 v[10:11], v[16:17], v[16:17]
	v_pk_mul_f32 v[12:13], v[6:7], v[6:7]
	v_pk_mul_f32 v[14:15], v[4:5], v[4:5]
	v_mul_f32_e32 v24, v1, v1
	v_mul_f32_e32 v26, v3, v3
	v_pk_mul_f32 v[30:31], v[76:77], v[76:77]
	s_waitcnt vmcnt(2)
	v_pk_mul_f32 v[32:33], v[70:71], v[70:71]
	v_pk_mul_f32 v[34:35], v[68:69], v[68:69]
	v_mul_f32_e32 v47, v82, v82
	v_mul_f32_e32 v48, v83, v83
	v_pk_mov_b32 v[44:45], v[10:11], v[8:9] op_sel:[1, 0]
	v_mov_b32_e32 v11, v9
	v_pk_mov_b32 v[8:9], v[14:15], v[12:13] op_sel:[1, 0]
	v_mov_b32_e32 v15, v13
	v_pk_fma_f32 v[12:13], v[0:1], v[0:1], v[24:25] op_sel_hi:[1, 1, 0]
	v_pk_fma_f32 v[24:25], v[2:3], v[2:3], v[26:27] op_sel_hi:[1, 1, 0]
	v_pk_mov_b32 v[26:27], v[30:31], v[28:29] op_sel:[1, 0]
	v_mov_b32_e32 v31, v29
	v_pk_mov_b32 v[28:29], v[34:35], v[32:33] op_sel:[1, 0]
	v_mov_b32_e32 v35, v33
	v_mul_f32_e32 v43, v80, v80
	s_waitcnt vmcnt(0)
	v_mul_f32_e32 v40, v65, v65
	v_mul_f32_e32 v42, v67, v67
	v_pk_add_f32 v[10:11], v[44:45], v[10:11]
	v_pk_add_f32 v[8:9], v[8:9], v[14:15]
	v_mov_b32_e32 v13, v47
	v_mov_b32_e32 v25, v48
	v_pk_add_f32 v[14:15], v[26:27], v[30:31]
	v_pk_add_f32 v[26:27], v[28:29], v[34:35]
	v_mul_f32_e32 v46, v81, v81
	v_mul_f32_e32 v49, v36, v36
	v_mul_f32_e32 v50, v37, v37
	v_mul_f32_e32 v51, v38, v38
	v_mul_f32_e32 v52, v39, v39
	v_pk_fma_f32 v[32:33], v[64:65], v[64:65], v[40:41] op_sel_hi:[1, 1, 0]
	v_pk_fma_f32 v[40:41], v[66:67], v[66:67], v[42:43] op_sel_hi:[1, 1, 0]
	v_pk_add_f32 v[10:11], v[10:11], v[10:11] op_sel:[0, 1] op_sel_hi:[1, 0]
	v_pk_add_f32 v[8:9], v[8:9], v[8:9] op_sel:[0, 1] op_sel_hi:[1, 0]
	v_pk_add_f32 v[12:13], v[12:13], v[24:25]
	v_pk_add_f32 v[14:15], v[14:15], v[14:15] op_sel:[0, 1] op_sel_hi:[1, 0]
	v_pk_add_f32 v[24:25], v[26:27], v[26:27] op_sel:[0, 1] op_sel_hi:[1, 0]
	v_mov_b32_e32 v33, v51
	v_mov_b32_e32 v41, v52
	v_mov_b32_e32 v11, v43
	v_mov_b32_e32 v9, v46
	v_mov_b32_e32 v15, v49
	v_mov_b32_e32 v25, v50
	v_pk_add_f32 v[26:27], v[32:33], v[40:41]
	v_pk_add_f32 v[8:9], v[10:11], v[8:9]
	v_pk_add_f32 v[10:11], v[14:15], v[24:25]
	v_pk_add_f32 v[8:9], v[8:9], v[12:13]
	v_pk_add_f32 v[10:11], v[10:11], v[26:27]
	v_mov_b32_e32 v13, v8
	v_mov_b32_e32 v12, v10
	v_mov_b32_e32 v8, v11
	v_pk_add_f32 v[8:9], v[12:13], v[8:9]
	v_lshl_add_u64 v[12:13], v[140:141], 0, s[52:53]
	v_lshl_add_u64 v[14:15], v[140:141], 0, s[54:55]
	global_load_dwordx4 v[72:75], v[12:13], off
	global_load_dwordx4 v[60:63], v[12:13], off offset:1024
	global_load_dwordx4 v[56:59], v[12:13], off offset:2048
	global_load_dwordx4 v[52:55], v[12:13], off offset:3072
	global_load_dwordx4 v[48:51], v[14:15], off
	global_load_dwordx4 v[44:47], v[14:15], off offset:1024
	s_waitcnt lgkmcnt(0)
	s_nop 1
	v_add_f32_dpp v8, v8, v8 quad_perm:[1,0,3,2] row_mask:0xf bank_mask:0xf
	v_add_f32_dpp v9, v9, v9 quad_perm:[1,0,3,2] row_mask:0xf bank_mask:0xf
	global_load_dwordx4 v[40:43], v[14:15], off offset:2048
	global_load_dwordx4 v[32:35], v[14:15], off offset:3072
	v_lshl_add_u64 v[24:25], v[144:145], 0, s[50:51]
	s_add_u32 s50, s16, s50
	s_addc_u32 s51, s17, s51
	s_waitcnt lgkmcnt(0)
	s_nop 1
	v_add_f32_dpp v8, v8, v8 quad_perm:[2,3,0,1] row_mask:0xf bank_mask:0xf
	v_add_f32_dpp v9, v9, v9 quad_perm:[2,3,0,1] row_mask:0xf bank_mask:0xf
	s_lshl_b64 s[48:49], s[48:49], 11
	s_waitcnt lgkmcnt(0)
	s_nop 1
	v_add_f32_dpp v8, v8, v8 row_half_mirror row_mask:0xf bank_mask:0xf
	v_add_f32_dpp v9, v9, v9 row_half_mirror row_mask:0xf bank_mask:0xf
	s_waitcnt lgkmcnt(0)
	s_nop 1
	v_add_f32_dpp v8, v8, v8 row_mirror row_mask:0xf bank_mask:0xf
	v_add_f32_dpp v9, v9, v9 row_mirror row_mask:0xf bank_mask:0xf
	ds_bpermute_b32 v11, v188, v9
	ds_bpermute_b32 v10, v188, v8
	s_waitcnt lgkmcnt(0)
	v_pk_add_f32 v[8:9], v[8:9], v[10:11]
	s_waitcnt lgkmcnt(0)
	v_mov_b32_e32 v10, v8
	v_mov_b32_e32 v11, v9
	s_nop 1
	v_permlane32_swap_b32_e32 v10, v8
	v_permlane32_swap_b32_e32 v11, v9
	v_pk_add_f32 v[8:9], v[8:9], v[10:11]
	s_nop 0
	v_pk_fma_f32 v[90:91], v[8:9], s[28:29], v[84:85] op_sel_hi:[1, 0, 0]
	s_waitcnt vmcnt(4)
	v_mul_f32_e32 v99, v53, v53
	v_mul_f32_e32 v8, 0x4b800000, v91
	v_cmp_gt_f32_e32 vcc, s79, v91
	s_waitcnt vmcnt(2)
	v_pk_mul_f32 v[94:95], v[44:45], v[44:45]
	v_mul_f32_e32 v102, v54, v54
	v_cndmask_b32_e32 v8, v91, v8, vcc
	v_rsq_f32_e32 v26, v8
	ds_read_b128 v[8:11], v190
	ds_read_b128 v[12:15], v191
	s_waitcnt vmcnt(1)
	v_mul_f32_e32 v96, v41, v41
	v_mul_f32_e32 v98, v43, v43
	v_mul_f32_e32 v27, 0x45800000, v26
	v_cndmask_b32_e32 v92, v26, v27, vcc
	v_pk_mul_f32 v[18:19], v[18:19], v[92:93] op_sel_hi:[1, 0]
	v_pk_mul_f32 v[16:17], v[16:17], v[92:93] op_sel_hi:[1, 0]
	v_pk_mul_f32 v[18:19], v[110:111], v[18:19]
	v_pk_mul_f32 v[16:17], v[108:109], v[16:17]
	s_waitcnt lgkmcnt(0)
	v_pk_fma_f32 v[18:19], v[14:15], v[18:19], v[10:11]
	v_pk_fma_f32 v[16:17], v[12:13], v[16:17], v[8:9]
	v_pk_mul_f32 v[6:7], v[6:7], v[92:93] op_sel_hi:[1, 0]
	v_cvt_pk_bf16_f32 v16, v16, v17
	v_cvt_pk_bf16_f32 v17, v18, v19
	global_store_dwordx2 v[24:25], v[16:17], off
	ds_read_b128 v[16:19], v192
	ds_read_b128 v[20:23], v193
	v_pk_mul_f32 v[4:5], v[4:5], v[92:93] op_sel_hi:[1, 0]
	v_pk_mul_f32 v[2:3], v[2:3], v[92:93] op_sel_hi:[1, 0]
	v_pk_mul_f32 v[0:1], v[0:1], v[92:93] op_sel_hi:[1, 0]
	v_pk_mul_f32 v[82:83], v[82:83], v[92:93] op_sel_hi:[1, 0]
	v_pk_mul_f32 v[80:81], v[80:81], v[92:93] op_sel_hi:[1, 0]
	v_cmp_gt_f32_e32 vcc, s79, v90
	v_pk_mul_f32 v[92:93], v[46:47], v[46:47]
	v_mul_f32_e32 v103, v55, v55
	s_waitcnt vmcnt(1)
	v_mul_f32_e32 v104, v32, v32
	v_mul_f32_e32 v105, v33, v33
	v_mul_f32_e32 v106, v34, v34
	v_mul_f32_e32 v107, v35, v35
	v_pk_mul_f32 v[4:5], v[112:113], v[4:5]
	v_pk_mul_f32 v[6:7], v[114:115], v[6:7]
	s_waitcnt lgkmcnt(0)
	v_pk_fma_f32 v[4:5], v[20:21], v[4:5], v[16:17]
	v_pk_fma_f32 v[6:7], v[22:23], v[6:7], v[18:19]
	v_cvt_pk_bf16_f32 v4, v4, v5
	v_cvt_pk_bf16_f32 v5, v6, v7
	global_store_dwordx2 v200, v[4:5], s[50:51]
	ds_read_b128 v[24:27], v194
	ds_read_b128 v[28:31], v195
	v_pk_mul_f32 v[0:1], v[116:117], v[0:1]
	v_pk_mul_f32 v[2:3], v[118:119], v[2:3]
	s_waitcnt lgkmcnt(0)
	v_pk_fma_f32 v[0:1], v[28:29], v[0:1], v[24:25]
	v_pk_fma_f32 v[2:3], v[30:31], v[2:3], v[26:27]
	v_cvt_pk_bf16_f32 v0, v0, v1
	v_cvt_pk_bf16_f32 v1, v2, v3
	global_store_dwordx2 v201, v[0:1], s[50:51]
	ds_read_b128 v[0:3], v196
	ds_read_b128 v[4:7], v197
	v_pk_mul_f32 v[80:81], v[80:81], v[120:121]
	v_pk_mul_f32 v[82:83], v[82:83], v[122:123]
	s_waitcnt lgkmcnt(0)
	v_pk_fma_f32 v[80:81], v[80:81], v[4:5], v[0:1]
	v_pk_fma_f32 v[82:83], v[82:83], v[6:7], v[2:3]
	v_cvt_pk_bf16_f32 v80, v80, v81
	v_cvt_pk_bf16_f32 v81, v82, v83
	global_store_dwordx2 v210, v[80:81], s[50:51]
	v_mul_f32_e32 v86, 0x4b800000, v90
	v_cndmask_b32_e32 v86, v90, v86, vcc
	v_rsq_f32_e32 v88, v86
	v_lshl_add_u64 v[86:87], v[144:145], 0, s[48:49]
	s_add_u32 s48, s16, s48
	s_addc_u32 s49, s17, s49
	v_mul_f32_e32 v89, 0x45800000, v88
	v_cndmask_b32_e32 v88, v88, v89, vcc
	v_pk_mul_f32 v[78:79], v[78:79], v[88:89] op_sel_hi:[1, 0]
	v_pk_mul_f32 v[76:77], v[76:77], v[88:89] op_sel_hi:[1, 0]
	v_pk_mul_f32 v[70:71], v[70:71], v[88:89] op_sel_hi:[1, 0]
	v_pk_mul_f32 v[68:69], v[68:69], v[88:89] op_sel_hi:[1, 0]
	v_pk_mul_f32 v[66:67], v[66:67], v[88:89] op_sel_hi:[1, 0]
	v_pk_mul_f32 v[64:65], v[64:65], v[88:89] op_sel_hi:[1, 0]
	v_mul_f32_e32 v89, v52, v52
	v_pk_mul_f32 v[38:39], v[38:39], v[88:89] op_sel_hi:[1, 0]
	v_pk_mul_f32 v[36:37], v[36:37], v[88:89] op_sel_hi:[1, 0]
	v_pk_mul_f32 v[90:91], v[48:49], v[48:49]
	s_lshl_b64 s[46:47], s[46:47], 11
	v_pk_mul_f32 v[76:77], v[108:109], v[76:77]
	v_pk_mul_f32 v[78:79], v[110:111], v[78:79]
	v_pk_fma_f32 v[76:77], v[12:13], v[76:77], v[8:9]
	v_pk_fma_f32 v[78:79], v[14:15], v[78:79], v[10:11]
	v_cvt_pk_bf16_f32 v76, v76, v77
	v_cvt_pk_bf16_f32 v77, v78, v79
	global_store_dwordx2 v[86:87], v[76:77], off
	v_mul_f32_e32 v80, v57, v57
	v_mul_f32_e32 v82, v59, v59
	v_pk_mul_f32 v[86:87], v[50:51], v[50:51]
	v_pk_mul_f32 v[68:69], v[112:113], v[68:69]
	v_pk_mul_f32 v[70:71], v[114:115], v[70:71]
	v_pk_fma_f32 v[68:69], v[20:21], v[68:69], v[16:17]
	v_pk_fma_f32 v[70:71], v[22:23], v[70:71], v[18:19]
	v_cvt_pk_bf16_f32 v68, v68, v69
	v_cvt_pk_bf16_f32 v69, v70, v71
	global_store_dwordx2 v200, v[68:69], s[48:49]
	v_pk_mul_f32 v[76:77], v[62:63], v[62:63]
	v_pk_mul_f32 v[78:79], v[60:61], v[60:61]
	v_pk_mul_f32 v[64:65], v[116:117], v[64:65]
	v_pk_mul_f32 v[66:67], v[118:119], v[66:67]
	v_pk_fma_f32 v[64:65], v[28:29], v[64:65], v[24:25]
	v_pk_fma_f32 v[66:67], v[30:31], v[66:67], v[26:27]
	v_cvt_pk_bf16_f32 v64, v64, v65
	v_cvt_pk_bf16_f32 v65, v66, v67
	global_store_dwordx2 v201, v[64:65], s[48:49]
	v_pk_mul_f32 v[68:69], v[74:75], v[74:75]
	v_pk_mul_f32 v[70:71], v[72:73], v[72:73]
	v_pk_mul_f32 v[36:37], v[120:121], v[36:37]
	v_pk_mul_f32 v[38:39], v[122:123], v[38:39]
	v_pk_fma_f32 v[36:37], v[4:5], v[36:37], v[0:1]
	v_pk_fma_f32 v[38:39], v[6:7], v[38:39], v[2:3]
	v_cvt_pk_bf16_f32 v36, v36, v37
	v_cvt_pk_bf16_f32 v37, v38, v39
	global_store_dwordx2 v210, v[36:37], s[48:49]
	v_pk_mov_b32 v[100:101], v[70:71], v[68:69] op_sel:[1, 0]
	v_mov_b32_e32 v71, v69
	v_pk_mov_b32 v[68:69], v[78:79], v[76:77] op_sel:[1, 0]
	v_mov_b32_e32 v79, v77
	v_pk_fma_f32 v[76:77], v[56:57], v[56:57], v[80:81] op_sel_hi:[1, 1, 0]
	v_pk_fma_f32 v[80:81], v[58:59], v[58:59], v[82:83] op_sel_hi:[1, 1, 0]
	v_pk_mov_b32 v[82:83], v[90:91], v[86:87] op_sel:[1, 0]
	v_mov_b32_e32 v91, v87
	v_pk_mov_b32 v[86:87], v[94:95], v[92:93] op_sel:[1, 0]
	v_mov_b32_e32 v95, v93
	v_pk_add_f32 v[70:71], v[100:101], v[70:71]
	v_pk_add_f32 v[64:65], v[68:69], v[78:79]
	v_pk_add_f32 v[66:67], v[82:83], v[90:91]
	v_pk_add_f32 v[68:69], v[86:87], v[94:95]
	v_pk_fma_f32 v[92:93], v[40:41], v[40:41], v[96:97] op_sel_hi:[1, 1, 0]
	v_pk_fma_f32 v[96:97], v[42:43], v[42:43], v[98:99] op_sel_hi:[1, 1, 0]
	v_pk_add_f32 v[70:71], v[70:71], v[70:71] op_sel:[0, 1] op_sel_hi:[1, 0]
	v_pk_add_f32 v[64:65], v[64:65], v[64:65] op_sel:[0, 1] op_sel_hi:[1, 0]
	v_pk_add_f32 v[66:67], v[66:67], v[66:67] op_sel:[0, 1] op_sel_hi:[1, 0]
	v_pk_add_f32 v[68:69], v[68:69], v[68:69] op_sel:[0, 1] op_sel_hi:[1, 0]
	v_mov_b32_e32 v77, v102
	v_mov_b32_e32 v81, v103
	v_mov_b32_e32 v93, v106
	v_mov_b32_e32 v97, v107
	v_mov_b32_e32 v71, v89
	v_mov_b32_e32 v65, v99
	v_mov_b32_e32 v67, v104
	v_mov_b32_e32 v69, v105
	v_pk_add_f32 v[76:77], v[76:77], v[80:81]
	v_pk_add_f32 v[78:79], v[92:93], v[96:97]
	v_pk_add_f32 v[64:65], v[70:71], v[64:65]
	v_pk_add_f32 v[66:67], v[66:67], v[68:69]
	v_pk_add_f32 v[64:65], v[64:65], v[76:77]
	v_pk_add_f32 v[66:67], v[66:67], v[78:79]
	v_mov_b32_e32 v69, v64
	v_mov_b32_e32 v68, v66
	v_mov_b32_e32 v64, v67
	v_pk_add_f32 v[64:65], v[68:69], v[64:65]
	s_waitcnt lgkmcnt(0)
	s_nop 1
	v_add_f32_dpp v64, v64, v64 quad_perm:[1,0,3,2] row_mask:0xf bank_mask:0xf
	v_add_f32_dpp v65, v65, v65 quad_perm:[1,0,3,2] row_mask:0xf bank_mask:0xf
	s_waitcnt lgkmcnt(0)
	s_nop 1
	v_add_f32_dpp v64, v64, v64 quad_perm:[2,3,0,1] row_mask:0xf bank_mask:0xf
	v_add_f32_dpp v65, v65, v65 quad_perm:[2,3,0,1] row_mask:0xf bank_mask:0xf
	s_waitcnt lgkmcnt(0)
	s_nop 1
	v_add_f32_dpp v64, v64, v64 row_half_mirror row_mask:0xf bank_mask:0xf
	v_add_f32_dpp v65, v65, v65 row_half_mirror row_mask:0xf bank_mask:0xf
	s_waitcnt lgkmcnt(0)
	s_nop 1
	v_add_f32_dpp v64, v64, v64 row_mirror row_mask:0xf bank_mask:0xf
	v_add_f32_dpp v65, v65, v65 row_mirror row_mask:0xf bank_mask:0xf
	ds_bpermute_b32 v67, v188, v65
	ds_bpermute_b32 v66, v188, v64
	s_waitcnt lgkmcnt(0)
	v_pk_add_f32 v[64:65], v[64:65], v[66:67]
	s_waitcnt lgkmcnt(0)
	v_mov_b32_e32 v66, v64
	v_mov_b32_e32 v67, v65
	s_nop 1
	v_permlane32_swap_b32_e32 v66, v64
	v_permlane32_swap_b32_e32 v67, v65
	v_pk_add_f32 v[64:65], v[64:65], v[66:67]
	s_nop 0
	v_pk_fma_f32 v[64:65], v[64:65], s[28:29], v[84:85] op_sel_hi:[1, 0, 0]
	s_nop 0
	v_mul_f32_e32 v66, 0x4b800000, v65
	v_cmp_gt_f32_e32 vcc, s79, v65
	s_nop 1
	v_cndmask_b32_e32 v65, v65, v66, vcc
	v_rsq_f32_e32 v65, v65
	v_lshl_add_u64 v[66:67], v[144:145], 0, s[46:47]
	s_add_u32 s46, s16, s46
	s_addc_u32 s47, s17, s47
	v_mul_f32_e32 v68, 0x45800000, v65
	v_cndmask_b32_e32 v68, v65, v68, vcc
	v_pk_mul_f32 v[70:71], v[74:75], v[68:69] op_sel_hi:[1, 0]
	v_pk_mul_f32 v[72:73], v[72:73], v[68:69] op_sel_hi:[1, 0]
	v_pk_mul_f32 v[38:39], v[110:111], v[70:71]
	v_pk_mul_f32 v[36:37], v[108:109], v[72:73]
	v_pk_fma_f32 v[38:39], v[14:15], v[38:39], v[10:11]
	v_pk_fma_f32 v[36:37], v[12:13], v[36:37], v[8:9]
	v_pk_mul_f32 v[62:63], v[62:63], v[68:69] op_sel_hi:[1, 0]
	v_cvt_pk_bf16_f32 v36, v36, v37
	v_cvt_pk_bf16_f32 v37, v38, v39
	global_store_dwordx2 v[66:67], v[36:37], off
	v_pk_mul_f32 v[60:61], v[60:61], v[68:69] op_sel_hi:[1, 0]
	v_pk_mul_f32 v[58:59], v[58:59], v[68:69] op_sel_hi:[1, 0]
	v_pk_mul_f32 v[56:57], v[56:57], v[68:69] op_sel_hi:[1, 0]
	v_pk_mul_f32 v[54:55], v[54:55], v[68:69] op_sel_hi:[1, 0]
	v_pk_mul_f32 v[52:53], v[52:53], v[68:69] op_sel_hi:[1, 0]
	v_cmp_gt_f32_e32 vcc, s79, v64
	s_lshl_b64 s[44:45], s[44:45], 11
	v_pk_mul_f32 v[36:37], v[112:113], v[60:61]
	v_pk_mul_f32 v[38:39], v[114:115], v[62:63]
	v_pk_fma_f32 v[36:37], v[20:21], v[36:37], v[16:17]
	v_pk_fma_f32 v[38:39], v[22:23], v[38:39], v[18:19]
	v_cvt_pk_bf16_f32 v36, v36, v37
	v_cvt_pk_bf16_f32 v37, v38, v39
	global_store_dwordx2 v200, v[36:37], s[46:47]
	v_pk_mul_f32 v[36:37], v[116:117], v[56:57]
	v_pk_mul_f32 v[38:39], v[118:119], v[58:59]
	v_pk_fma_f32 v[36:37], v[28:29], v[36:37], v[24:25]
	v_pk_fma_f32 v[38:39], v[30:31], v[38:39], v[26:27]
	v_cvt_pk_bf16_f32 v36, v36, v37
	v_cvt_pk_bf16_f32 v37, v38, v39
	global_store_dwordx2 v201, v[36:37], s[46:47]
	v_pk_mul_f32 v[36:37], v[120:121], v[52:53]
	v_pk_mul_f32 v[38:39], v[122:123], v[54:55]
	v_pk_fma_f32 v[36:37], v[4:5], v[36:37], v[0:1]
	v_pk_fma_f32 v[38:39], v[6:7], v[38:39], v[2:3]
	v_cvt_pk_bf16_f32 v36, v36, v37
	v_cvt_pk_bf16_f32 v37, v38, v39
	global_store_dwordx2 v210, v[36:37], s[46:47]
	v_mul_f32_e32 v52, 0x4b800000, v64
	v_cndmask_b32_e32 v52, v64, v52, vcc
	v_rsq_f32_e32 v54, v52
	v_lshl_add_u64 v[52:53], v[144:145], 0, s[44:45]
	s_add_u32 s44, s16, s44
	s_addc_u32 s45, s17, s45
	v_mul_f32_e32 v55, 0x45800000, v54
	v_cndmask_b32_e32 v54, v54, v55, vcc
	v_pk_mul_f32 v[50:51], v[50:51], v[54:55] op_sel_hi:[1, 0]
	v_pk_mul_f32 v[48:49], v[48:49], v[54:55] op_sel_hi:[1, 0]
	v_pk_mul_f32 v[46:47], v[46:47], v[54:55] op_sel_hi:[1, 0]
	v_pk_mul_f32 v[44:45], v[44:45], v[54:55] op_sel_hi:[1, 0]
	v_pk_mul_f32 v[42:43], v[42:43], v[54:55] op_sel_hi:[1, 0]
	v_pk_mul_f32 v[40:41], v[40:41], v[54:55] op_sel_hi:[1, 0]
	v_pk_mul_f32 v[34:35], v[34:35], v[54:55] op_sel_hi:[1, 0]
	v_pk_mul_f32 v[32:33], v[32:33], v[54:55] op_sel_hi:[1, 0]
	s_or_b32 s48, s42, 4
	s_ashr_i32 s49, s48, 31
	s_lshl_b64 s[46:47], s[48:49], 12
	s_lshl_b64 s[48:49], s[48:49], 11
	v_lshl_add_u64 v[104:105], v[144:145], 0, s[48:49]
	v_pk_mul_f32 v[36:37], v[108:109], v[48:49]
	v_pk_mul_f32 v[38:39], v[110:111], v[50:51]
	v_pk_fma_f32 v[36:37], v[12:13], v[36:37], v[8:9]
	v_pk_fma_f32 v[38:39], v[14:15], v[38:39], v[10:11]
	v_cvt_pk_bf16_f32 v36, v36, v37
	v_cvt_pk_bf16_f32 v37, v38, v39
	global_store_dwordx2 v[52:53], v[36:37], off
	v_pk_mul_f32 v[36:37], v[112:113], v[44:45]
	v_pk_mul_f32 v[38:39], v[114:115], v[46:47]
	v_pk_fma_f32 v[36:37], v[20:21], v[36:37], v[16:17]
	v_pk_fma_f32 v[38:39], v[22:23], v[38:39], v[18:19]
	v_cvt_pk_bf16_f32 v36, v36, v37
	v_cvt_pk_bf16_f32 v37, v38, v39
	global_store_dwordx2 v200, v[36:37], s[44:45]
	v_pk_mul_f32 v[36:37], v[116:117], v[40:41]
	v_pk_mul_f32 v[38:39], v[118:119], v[42:43]
	v_pk_fma_f32 v[36:37], v[28:29], v[36:37], v[24:25]
	v_pk_fma_f32 v[38:39], v[30:31], v[38:39], v[26:27]
	v_cvt_pk_bf16_f32 v36, v36, v37
	v_cvt_pk_bf16_f32 v37, v38, v39
	global_store_dwordx2 v201, v[36:37], s[44:45]
	v_lshl_add_u64 v[40:41], v[140:141], 0, s[46:47]
	s_or_b32 s46, s42, 5
	s_ashr_i32 s47, s46, 31
	v_pk_mul_f32 v[32:33], v[120:121], v[32:33]
	v_pk_mul_f32 v[34:35], v[122:123], v[34:35]
	v_pk_fma_f32 v[32:33], v[4:5], v[32:33], v[0:1]
	v_pk_fma_f32 v[34:35], v[6:7], v[34:35], v[2:3]
	v_cvt_pk_bf16_f32 v32, v32, v33
	v_cvt_pk_bf16_f32 v33, v34, v35
	global_store_dwordx2 v210, v[32:33], s[44:45]
	global_load_dwordx4 v[86:89], v[40:41], off
	global_load_dwordx4 v[90:93], v[40:41], off offset:1024
	global_load_dwordx4 v[80:83], v[40:41], off offset:3072
	global_load_dwordx4 v[94:97], v[40:41], off offset:2048
	s_lshl_b64 s[44:45], s[46:47], 12
	v_lshl_add_u64 v[32:33], v[140:141], 0, s[44:45]
	global_load_dwordx4 v[76:79], v[32:33], off
	global_load_dwordx4 v[72:75], v[32:33], off offset:1024
	global_load_dwordx4 v[36:39], v[32:33], off offset:3072
	global_load_dwordx4 v[68:71], v[32:33], off offset:2048
	s_or_b32 s44, s42, 6
	s_or_b32 s42, s42, 7
	s_ashr_i32 s45, s44, 31
	s_ashr_i32 s43, s42, 31
	s_lshl_b64 s[50:51], s[44:45], 12
	s_lshl_b64 s[52:53], s[42:43], 12
	s_add_u32 s48, s16, s48
	s_addc_u32 s49, s17, s49
	s_lshl_b64 s[46:47], s[46:47], 11
	s_waitcnt vmcnt(7)
	v_pk_mul_f32 v[32:33], v[88:89], v[88:89]
	v_pk_mul_f32 v[34:35], v[86:87], v[86:87]
	s_waitcnt vmcnt(6)
	v_pk_mul_f32 v[40:41], v[92:93], v[92:93]
	v_pk_mul_f32 v[42:43], v[90:91], v[90:91]
	s_waitcnt vmcnt(4)
	v_mul_f32_e32 v44, v95, v95
	v_mul_f32_e32 v46, v97, v97
	s_waitcnt vmcnt(3)
	v_pk_mul_f32 v[48:49], v[78:79], v[78:79]
	v_pk_mul_f32 v[50:51], v[76:77], v[76:77]
	s_waitcnt vmcnt(2)
	v_pk_mul_f32 v[52:53], v[74:75], v[74:75]
	v_pk_mul_f32 v[54:55], v[72:73], v[72:73]
	v_mul_f32_e32 v63, v82, v82
	v_mul_f32_e32 v64, v83, v83
	v_pk_mov_b32 v[60:61], v[34:35], v[32:33] op_sel:[1, 0]
	v_mov_b32_e32 v35, v33
	v_pk_mov_b32 v[32:33], v[42:43], v[40:41] op_sel:[1, 0]
	v_mov_b32_e32 v43, v41
	v_pk_fma_f32 v[40:41], v[94:95], v[94:95], v[44:45] op_sel_hi:[1, 1, 0]
	v_pk_fma_f32 v[44:45], v[96:97], v[96:97], v[46:47] op_sel_hi:[1, 1, 0]
	v_pk_mov_b32 v[46:47], v[50:51], v[48:49] op_sel:[1, 0]
	v_mov_b32_e32 v51, v49
	v_pk_mov_b32 v[48:49], v[54:55], v[52:53] op_sel:[1, 0]
	v_mov_b32_e32 v55, v53
	v_mul_f32_e32 v59, v80, v80
	s_waitcnt vmcnt(0)
	v_mul_f32_e32 v56, v69, v69
	v_mul_f32_e32 v58, v71, v71
	v_pk_add_f32 v[34:35], v[60:61], v[34:35]
	v_pk_add_f32 v[32:33], v[32:33], v[42:43]
	v_mov_b32_e32 v41, v63
	v_mov_b32_e32 v45, v64
	v_pk_add_f32 v[42:43], v[46:47], v[50:51]
	v_pk_add_f32 v[46:47], v[48:49], v[54:55]
	v_mul_f32_e32 v62, v81, v81
	v_mul_f32_e32 v65, v36, v36
	v_mul_f32_e32 v66, v37, v37
	v_mul_f32_e32 v67, v38, v38
	v_mul_f32_e32 v102, v39, v39
	v_pk_fma_f32 v[52:53], v[68:69], v[68:69], v[56:57] op_sel_hi:[1, 1, 0]
	v_pk_fma_f32 v[56:57], v[70:71], v[70:71], v[58:59] op_sel_hi:[1, 1, 0]
	v_pk_add_f32 v[34:35], v[34:35], v[34:35] op_sel:[0, 1] op_sel_hi:[1, 0]
	v_pk_add_f32 v[32:33], v[32:33], v[32:33] op_sel:[0, 1] op_sel_hi:[1, 0]
	v_pk_add_f32 v[40:41], v[40:41], v[44:45]
	v_pk_add_f32 v[42:43], v[42:43], v[42:43] op_sel:[0, 1] op_sel_hi:[1, 0]
	v_pk_add_f32 v[44:45], v[46:47], v[46:47] op_sel:[0, 1] op_sel_hi:[1, 0]
	v_mov_b32_e32 v53, v67
	v_mov_b32_e32 v57, v102
	v_mov_b32_e32 v35, v59
	v_mov_b32_e32 v33, v62
	v_mov_b32_e32 v43, v65
	v_mov_b32_e32 v45, v66
	v_pk_add_f32 v[46:47], v[52:53], v[56:57]
	v_pk_add_f32 v[32:33], v[34:35], v[32:33]
	v_pk_add_f32 v[34:35], v[42:43], v[44:45]
	v_pk_add_f32 v[32:33], v[32:33], v[40:41]
	v_pk_add_f32 v[34:35], v[34:35], v[46:47]
	v_mov_b32_e32 v41, v32
	v_mov_b32_e32 v40, v34
	v_mov_b32_e32 v32, v35
	v_pk_add_f32 v[32:33], v[40:41], v[32:33]
	v_lshl_add_u64 v[40:41], v[140:141], 0, s[50:51]
	v_lshl_add_u64 v[102:103], v[140:141], 0, s[52:53]
	global_load_dwordx4 v[64:67], v[40:41], off
	global_load_dwordx4 v[60:63], v[40:41], off offset:1024
	global_load_dwordx4 v[56:59], v[40:41], off offset:2048
	global_load_dwordx4 v[52:55], v[40:41], off offset:3072
	s_waitcnt lgkmcnt(0)
	s_nop 1
	v_add_f32_dpp v32, v32, v32 quad_perm:[1,0,3,2] row_mask:0xf bank_mask:0xf
	v_add_f32_dpp v33, v33, v33 quad_perm:[1,0,3,2] row_mask:0xf bank_mask:0xf
	s_waitcnt lgkmcnt(0)
	s_nop 1
	v_add_f32_dpp v32, v32, v32 quad_perm:[2,3,0,1] row_mask:0xf bank_mask:0xf
	v_add_f32_dpp v33, v33, v33 quad_perm:[2,3,0,1] row_mask:0xf bank_mask:0xf
	s_waitcnt lgkmcnt(0)
	s_nop 1
	v_add_f32_dpp v32, v32, v32 row_half_mirror row_mask:0xf bank_mask:0xf
	v_add_f32_dpp v33, v33, v33 row_half_mirror row_mask:0xf bank_mask:0xf
	s_waitcnt lgkmcnt(0)
	s_nop 1
	v_add_f32_dpp v32, v32, v32 row_mirror row_mask:0xf bank_mask:0xf
	v_add_f32_dpp v33, v33, v33 row_mirror row_mask:0xf bank_mask:0xf
	ds_bpermute_b32 v35, v188, v33
	ds_bpermute_b32 v34, v188, v32
	s_waitcnt lgkmcnt(0)
	v_pk_add_f32 v[32:33], v[32:33], v[34:35]
	s_waitcnt lgkmcnt(0)
	v_mov_b32_e32 v34, v32
	v_mov_b32_e32 v35, v33
	s_nop 1
	v_permlane32_swap_b32_e32 v34, v32
	v_permlane32_swap_b32_e32 v35, v33
	v_pk_add_f32 v[32:33], v[32:33], v[34:35]
	s_nop 0
	v_pk_fma_f32 v[106:107], v[32:33], s[28:29], v[84:85] op_sel_hi:[1, 0, 0]
	s_nop 0
	v_mul_f32_e32 v32, 0x4b800000, v107
	v_cmp_gt_f32_e32 vcc, s79, v107
	s_nop 1
	v_cndmask_b32_e32 v32, v107, v32, vcc
	v_rsq_f32_e32 v107, v32
	global_load_dwordx4 v[48:51], v[102:103], off
	global_load_dwordx4 v[44:47], v[102:103], off offset:1024
	global_load_dwordx4 v[40:43], v[102:103], off offset:2048
	global_load_dwordx4 v[32:35], v[102:103], off offset:3072
	v_mul_f32_e32 v102, 0x45800000, v107
	v_cndmask_b32_e32 v102, v107, v102, vcc
	v_pk_mul_f32 v[88:89], v[88:89], v[102:103] op_sel_hi:[1, 0]
	v_pk_mul_f32 v[86:87], v[86:87], v[102:103] op_sel_hi:[1, 0]
	v_pk_mul_f32 v[88:89], v[110:111], v[88:89]
	v_pk_mul_f32 v[86:87], v[108:109], v[86:87]
	v_pk_fma_f32 v[88:89], v[14:15], v[88:89], v[10:11]
	v_pk_fma_f32 v[86:87], v[12:13], v[86:87], v[8:9]
	v_pk_mul_f32 v[92:93], v[92:93], v[102:103] op_sel_hi:[1, 0]
	v_cvt_pk_bf16_f32 v86, v86, v87
	v_cvt_pk_bf16_f32 v87, v88, v89
	global_store_dwordx2 v[104:105], v[86:87], off
	v_pk_mul_f32 v[90:91], v[90:91], v[102:103] op_sel_hi:[1, 0]
	v_pk_mul_f32 v[82:83], v[82:83], v[102:103] op_sel_hi:[1, 0]
	v_pk_mul_f32 v[80:81], v[80:81], v[102:103] op_sel_hi:[1, 0]
	v_cmp_gt_f32_e32 vcc, s79, v106
	s_waitcnt vmcnt(5)
	v_mul_f32_e32 v99, v53, v53
	s_waitcnt vmcnt(2)
	v_mul_f32_e32 v98, v43, v43
	s_waitcnt vmcnt(1)
	v_mul_f32_e32 v104, v32, v32
	v_mul_f32_e32 v105, v33, v33
	v_mul_f32_e32 v107, v35, v35
	v_pk_mul_f32 v[86:87], v[112:113], v[90:91]
	v_pk_mul_f32 v[88:89], v[114:115], v[92:93]
	v_pk_fma_f32 v[86:87], v[20:21], v[86:87], v[16:17]
	v_pk_fma_f32 v[88:89], v[22:23], v[88:89], v[18:19]
	v_cvt_pk_bf16_f32 v86, v86, v87
	v_cvt_pk_bf16_f32 v87, v88, v89
	global_store_dwordx2 v200, v[86:87], s[48:49]
	v_pk_mul_f32 v[90:91], v[96:97], v[102:103] op_sel_hi:[1, 0]
	v_pk_mul_f32 v[92:93], v[94:95], v[102:103] op_sel_hi:[1, 0]
	v_pk_mul_f32 v[94:95], v[44:45], v[44:45]
	v_mul_f32_e32 v96, v41, v41
	v_mul_f32_e32 v102, v54, v54
	v_mul_f32_e32 v103, v55, v55
	v_pk_mul_f32 v[86:87], v[116:117], v[92:93]
	v_pk_mul_f32 v[88:89], v[118:119], v[90:91]
	v_pk_fma_f32 v[86:87], v[28:29], v[86:87], v[24:25]
	v_pk_fma_f32 v[88:89], v[30:31], v[88:89], v[26:27]
	v_cvt_pk_bf16_f32 v86, v86, v87
	v_cvt_pk_bf16_f32 v87, v88, v89
	global_store_dwordx2 v201, v[86:87], s[48:49]
	v_pk_mul_f32 v[90:91], v[48:49], v[48:49]
	v_pk_mul_f32 v[92:93], v[46:47], v[46:47]
	v_pk_mul_f32 v[80:81], v[120:121], v[80:81]
	v_pk_mul_f32 v[82:83], v[122:123], v[82:83]
	v_pk_fma_f32 v[80:81], v[4:5], v[80:81], v[0:1]
	v_pk_fma_f32 v[82:83], v[6:7], v[82:83], v[2:3]
	v_cvt_pk_bf16_f32 v80, v80, v81
	v_cvt_pk_bf16_f32 v81, v82, v83
	global_store_dwordx2 v210, v[80:81], s[48:49]
	v_mul_f32_e32 v86, 0x4b800000, v106
	v_cndmask_b32_e32 v86, v106, v86, vcc
	v_rsq_f32_e32 v88, v86
	v_lshl_add_u64 v[86:87], v[144:145], 0, s[46:47]
	s_add_u32 s46, s16, s46
	s_addc_u32 s47, s17, s47
	v_mul_f32_e32 v89, 0x45800000, v88
	v_cndmask_b32_e32 v88, v88, v89, vcc
	v_pk_mul_f32 v[78:79], v[78:79], v[88:89] op_sel_hi:[1, 0]
	v_pk_mul_f32 v[76:77], v[76:77], v[88:89] op_sel_hi:[1, 0]
	v_pk_mul_f32 v[74:75], v[74:75], v[88:89] op_sel_hi:[1, 0]
	v_pk_mul_f32 v[72:73], v[72:73], v[88:89] op_sel_hi:[1, 0]
	v_pk_mul_f32 v[70:71], v[70:71], v[88:89] op_sel_hi:[1, 0]
	v_pk_mul_f32 v[68:69], v[68:69], v[88:89] op_sel_hi:[1, 0]
	v_mul_f32_e32 v89, v52, v52
	v_pk_mul_f32 v[38:39], v[38:39], v[88:89] op_sel_hi:[1, 0]
	v_pk_mul_f32 v[36:37], v[36:37], v[88:89] op_sel_hi:[1, 0]
	v_mul_f32_e32 v106, v34, v34
	s_lshl_b64 s[44:45], s[44:45], 11
	v_pk_mul_f32 v[76:77], v[108:109], v[76:77]
	v_pk_mul_f32 v[78:79], v[110:111], v[78:79]
	v_pk_fma_f32 v[76:77], v[12:13], v[76:77], v[8:9]
	v_pk_fma_f32 v[78:79], v[14:15], v[78:79], v[10:11]
	v_cvt_pk_bf16_f32 v76, v76, v77
	v_cvt_pk_bf16_f32 v77, v78, v79
	global_store_dwordx2 v[86:87], v[76:77], off
	v_mul_f32_e32 v80, v57, v57
	v_mul_f32_e32 v82, v59, v59
	v_pk_mul_f32 v[86:87], v[50:51], v[50:51]
	v_pk_mul_f32 v[72:73], v[112:113], v[72:73]
	v_pk_mul_f32 v[74:75], v[114:115], v[74:75]
	v_pk_fma_f32 v[72:73], v[20:21], v[72:73], v[16:17]
	v_pk_fma_f32 v[74:75], v[22:23], v[74:75], v[18:19]
	v_cvt_pk_bf16_f32 v72, v72, v73
	v_cvt_pk_bf16_f32 v73, v74, v75
	global_store_dwordx2 v200, v[72:73], s[46:47]
	v_pk_mul_f32 v[76:77], v[62:63], v[62:63]
	v_pk_mul_f32 v[78:79], v[60:61], v[60:61]
	v_pk_mul_f32 v[68:69], v[116:117], v[68:69]
	v_pk_mul_f32 v[70:71], v[118:119], v[70:71]
	v_pk_fma_f32 v[68:69], v[28:29], v[68:69], v[24:25]
	v_pk_fma_f32 v[70:71], v[30:31], v[70:71], v[26:27]
	v_cvt_pk_bf16_f32 v68, v68, v69
	v_cvt_pk_bf16_f32 v69, v70, v71
	global_store_dwordx2 v201, v[68:69], s[46:47]
	v_pk_mul_f32 v[72:73], v[66:67], v[66:67]
	v_pk_mul_f32 v[74:75], v[64:65], v[64:65]
	v_pk_mul_f32 v[36:37], v[120:121], v[36:37]
	v_pk_mul_f32 v[38:39], v[122:123], v[38:39]
	v_pk_fma_f32 v[36:37], v[4:5], v[36:37], v[0:1]
	v_pk_fma_f32 v[38:39], v[6:7], v[38:39], v[2:3]
	v_cvt_pk_bf16_f32 v36, v36, v37
	v_cvt_pk_bf16_f32 v37, v38, v39
	global_store_dwordx2 v210, v[36:37], s[46:47]
	v_pk_mov_b32 v[100:101], v[74:75], v[72:73] op_sel:[1, 0]
	v_mov_b32_e32 v75, v73
	v_pk_mov_b32 v[72:73], v[78:79], v[76:77] op_sel:[1, 0]
	v_mov_b32_e32 v79, v77
	v_pk_fma_f32 v[76:77], v[56:57], v[56:57], v[80:81] op_sel_hi:[1, 1, 0]
	v_pk_fma_f32 v[80:81], v[58:59], v[58:59], v[82:83] op_sel_hi:[1, 1, 0]
	v_pk_mov_b32 v[82:83], v[90:91], v[86:87] op_sel:[1, 0]
	v_mov_b32_e32 v91, v87
	v_pk_mov_b32 v[86:87], v[94:95], v[92:93] op_sel:[1, 0]
	v_mov_b32_e32 v95, v93
	v_pk_add_f32 v[74:75], v[100:101], v[74:75]
	v_pk_add_f32 v[68:69], v[72:73], v[78:79]
	v_pk_add_f32 v[70:71], v[82:83], v[90:91]
	v_pk_add_f32 v[72:73], v[86:87], v[94:95]
	v_pk_fma_f32 v[92:93], v[40:41], v[40:41], v[96:97] op_sel_hi:[1, 1, 0]
	v_pk_fma_f32 v[96:97], v[42:43], v[42:43], v[98:99] op_sel_hi:[1, 1, 0]
	v_pk_add_f32 v[74:75], v[74:75], v[74:75] op_sel:[0, 1] op_sel_hi:[1, 0]
	v_pk_add_f32 v[68:69], v[68:69], v[68:69] op_sel:[0, 1] op_sel_hi:[1, 0]
	v_pk_add_f32 v[70:71], v[70:71], v[70:71] op_sel:[0, 1] op_sel_hi:[1, 0]
	v_pk_add_f32 v[72:73], v[72:73], v[72:73] op_sel:[0, 1] op_sel_hi:[1, 0]
	v_mov_b32_e32 v77, v102
	v_mov_b32_e32 v81, v103
	v_mov_b32_e32 v93, v106
	v_mov_b32_e32 v97, v107
	v_mov_b32_e32 v75, v89
	v_mov_b32_e32 v69, v99
	v_mov_b32_e32 v71, v104
	v_mov_b32_e32 v73, v105
	v_pk_add_f32 v[76:77], v[76:77], v[80:81]
	v_pk_add_f32 v[78:79], v[92:93], v[96:97]
	v_pk_add_f32 v[68:69], v[74:75], v[68:69]
	v_pk_add_f32 v[70:71], v[70:71], v[72:73]
	v_pk_add_f32 v[68:69], v[68:69], v[76:77]
	v_pk_add_f32 v[70:71], v[70:71], v[78:79]
	v_mov_b32_e32 v73, v68
	v_mov_b32_e32 v72, v70
	v_mov_b32_e32 v68, v71
	v_pk_add_f32 v[68:69], v[72:73], v[68:69]
	s_waitcnt lgkmcnt(0)
	s_nop 1
	v_add_f32_dpp v68, v68, v68 quad_perm:[1,0,3,2] row_mask:0xf bank_mask:0xf
	v_add_f32_dpp v69, v69, v69 quad_perm:[1,0,3,2] row_mask:0xf bank_mask:0xf
	s_waitcnt lgkmcnt(0)
	s_nop 1
	v_add_f32_dpp v68, v68, v68 quad_perm:[2,3,0,1] row_mask:0xf bank_mask:0xf
	v_add_f32_dpp v69, v69, v69 quad_perm:[2,3,0,1] row_mask:0xf bank_mask:0xf
	s_waitcnt lgkmcnt(0)
	s_nop 1
	v_add_f32_dpp v68, v68, v68 row_half_mirror row_mask:0xf bank_mask:0xf
	v_add_f32_dpp v69, v69, v69 row_half_mirror row_mask:0xf bank_mask:0xf
	s_waitcnt lgkmcnt(0)
	s_nop 1
	v_add_f32_dpp v68, v68, v68 row_mirror row_mask:0xf bank_mask:0xf
	v_add_f32_dpp v69, v69, v69 row_mirror row_mask:0xf bank_mask:0xf
	ds_bpermute_b32 v71, v188, v69
	ds_bpermute_b32 v70, v188, v68
	s_waitcnt lgkmcnt(0)
	v_pk_add_f32 v[68:69], v[68:69], v[70:71]
	s_waitcnt lgkmcnt(0)
	v_mov_b32_e32 v70, v68
	v_mov_b32_e32 v71, v69
	s_nop 1
	v_permlane32_swap_b32_e32 v70, v68
	v_permlane32_swap_b32_e32 v71, v69
	v_pk_add_f32 v[68:69], v[68:69], v[70:71]
	s_nop 0
	v_pk_fma_f32 v[68:69], v[68:69], s[28:29], v[84:85] op_sel_hi:[1, 0, 0]
	s_nop 0
	v_mul_f32_e32 v70, 0x4b800000, v69
	v_cmp_gt_f32_e32 vcc, s79, v69
	s_nop 1
	v_cndmask_b32_e32 v69, v69, v70, vcc
	v_rsq_f32_e32 v69, v69
	v_lshl_add_u64 v[70:71], v[144:145], 0, s[44:45]
	s_add_u32 s44, s16, s44
	s_addc_u32 s45, s17, s45
	v_mul_f32_e32 v72, 0x45800000, v69
	v_cndmask_b32_e32 v72, v69, v72, vcc
	v_pk_mul_f32 v[66:67], v[66:67], v[72:73] op_sel_hi:[1, 0]
	v_pk_mul_f32 v[64:65], v[64:65], v[72:73] op_sel_hi:[1, 0]
	v_pk_mul_f32 v[38:39], v[110:111], v[66:67]
	v_pk_mul_f32 v[36:37], v[108:109], v[64:65]
	v_pk_fma_f32 v[38:39], v[14:15], v[38:39], v[10:11]
	v_pk_fma_f32 v[36:37], v[12:13], v[36:37], v[8:9]
	v_pk_mul_f32 v[62:63], v[62:63], v[72:73] op_sel_hi:[1, 0]
	v_cvt_pk_bf16_f32 v36, v36, v37
	v_cvt_pk_bf16_f32 v37, v38, v39
	global_store_dwordx2 v[70:71], v[36:37], off
	v_pk_mul_f32 v[60:61], v[60:61], v[72:73] op_sel_hi:[1, 0]
	v_pk_mul_f32 v[58:59], v[58:59], v[72:73] op_sel_hi:[1, 0]
	v_pk_mul_f32 v[56:57], v[56:57], v[72:73] op_sel_hi:[1, 0]
	v_pk_mul_f32 v[54:55], v[54:55], v[72:73] op_sel_hi:[1, 0]
	v_pk_mul_f32 v[52:53], v[52:53], v[72:73] op_sel_hi:[1, 0]
	v_cmp_gt_f32_e32 vcc, s79, v68
	s_lshl_b64 s[42:43], s[42:43], 11
	v_pk_mul_f32 v[36:37], v[112:113], v[60:61]
	v_pk_mul_f32 v[38:39], v[114:115], v[62:63]
	v_pk_fma_f32 v[36:37], v[20:21], v[36:37], v[16:17]
	v_pk_fma_f32 v[38:39], v[22:23], v[38:39], v[18:19]
	v_cvt_pk_bf16_f32 v36, v36, v37
	v_cvt_pk_bf16_f32 v37, v38, v39
	global_store_dwordx2 v200, v[36:37], s[44:45]
	v_pk_mul_f32 v[36:37], v[116:117], v[56:57]
	v_pk_mul_f32 v[38:39], v[118:119], v[58:59]
	v_pk_fma_f32 v[36:37], v[28:29], v[36:37], v[24:25]
	v_pk_fma_f32 v[38:39], v[30:31], v[38:39], v[26:27]
	v_cvt_pk_bf16_f32 v36, v36, v37
	v_cvt_pk_bf16_f32 v37, v38, v39
	global_store_dwordx2 v201, v[36:37], s[44:45]
	v_pk_mul_f32 v[36:37], v[120:121], v[52:53]
	v_pk_mul_f32 v[38:39], v[122:123], v[54:55]
	v_pk_fma_f32 v[36:37], v[4:5], v[36:37], v[0:1]
	v_pk_fma_f32 v[38:39], v[6:7], v[38:39], v[2:3]
	v_cvt_pk_bf16_f32 v36, v36, v37
	v_cvt_pk_bf16_f32 v37, v38, v39
	global_store_dwordx2 v210, v[36:37], s[44:45]
	v_mul_f32_e32 v52, 0x4b800000, v68
	v_cndmask_b32_e32 v52, v68, v52, vcc
	v_rsq_f32_e32 v54, v52
	v_lshl_add_u64 v[52:53], v[144:145], 0, s[42:43]
	s_add_u32 s42, s16, s42
	s_addc_u32 s43, s17, s43
	v_mul_f32_e32 v55, 0x45800000, v54
	v_cndmask_b32_e32 v54, v54, v55, vcc
	v_pk_mul_f32 v[50:51], v[50:51], v[54:55] op_sel_hi:[1, 0]
	v_pk_mul_f32 v[48:49], v[48:49], v[54:55] op_sel_hi:[1, 0]
	s_andn2_b64 vcc, exec, s[8:9]
	s_mov_b64 s[8:9], -1
	v_pk_mul_f32 v[36:37], v[108:109], v[48:49]
	v_pk_mul_f32 v[38:39], v[110:111], v[50:51]
	v_pk_fma_f32 v[8:9], v[12:13], v[36:37], v[8:9]
	v_pk_fma_f32 v[10:11], v[14:15], v[38:39], v[10:11]
	v_cvt_pk_bf16_f32 v8, v8, v9
	v_cvt_pk_bf16_f32 v9, v10, v11
	global_store_dwordx2 v[52:53], v[8:9], off
	v_pk_mul_f32 v[12:13], v[46:47], v[54:55] op_sel_hi:[1, 0]
	v_pk_mul_f32 v[14:15], v[44:45], v[54:55] op_sel_hi:[1, 0]
	v_pk_mul_f32 v[10:11], v[114:115], v[12:13]
	v_pk_mul_f32 v[8:9], v[112:113], v[14:15]
	v_pk_fma_f32 v[10:11], v[22:23], v[10:11], v[18:19]
	v_pk_fma_f32 v[8:9], v[20:21], v[8:9], v[16:17]
	v_pk_mul_f32 v[12:13], v[42:43], v[54:55] op_sel_hi:[1, 0]
	v_cvt_pk_bf16_f32 v8, v8, v9
	v_cvt_pk_bf16_f32 v9, v10, v11
	global_store_dwordx2 v200, v[8:9], s[42:43]
	v_pk_mul_f32 v[14:15], v[40:41], v[54:55] op_sel_hi:[1, 0]
	v_pk_mul_f32 v[10:11], v[118:119], v[12:13]
	v_pk_mul_f32 v[8:9], v[116:117], v[14:15]
	v_pk_fma_f32 v[10:11], v[30:31], v[10:11], v[26:27]
	v_pk_fma_f32 v[8:9], v[28:29], v[8:9], v[24:25]
	v_pk_mul_f32 v[12:13], v[34:35], v[54:55] op_sel_hi:[1, 0]
	v_cvt_pk_bf16_f32 v8, v8, v9
	v_cvt_pk_bf16_f32 v9, v10, v11
	global_store_dwordx2 v201, v[8:9], s[42:43]
	v_pk_mul_f32 v[14:15], v[32:33], v[54:55] op_sel_hi:[1, 0]
	v_pk_mul_f32 v[10:11], v[122:123], v[12:13]
	v_pk_mul_f32 v[8:9], v[120:121], v[14:15]
	v_pk_fma_f32 v[2:3], v[6:7], v[10:11], v[2:3]
	v_pk_fma_f32 v[0:1], v[4:5], v[8:9], v[0:1]
	s_nop 0
	v_cvt_pk_bf16_f32 v0, v0, v1
	v_cvt_pk_bf16_f32 v1, v2, v3
	global_store_dwordx2 v210, v[0:1], s[42:43]
	s_cbranch_vccnz .LBB0_1163
	s_andn2_b64 vcc, exec, s[10:11]
	s_cbranch_vccnz .LBB0_1162
	s_barrier
	s_branch .LBB0_1162

.LBB0_1498:
	s_or_b64 exec, exec, s[36:37]
	s_add_i32 s36, s69, 64
	v_mad_i64_i32 v[4:5], s[36:37], s36, v211, v[134:135]
	s_add_i32 s36, s69, 0x48
	s_nop 0
	v_mad_i64_i32 v[8:9], s[36:37], s36, v211, v[134:135]
	s_add_i32 s36, s69, 0x50
	s_nop 0
	v_mad_i64_i32 v[12:13], s[36:37], s36, v211, v[134:135]
	s_add_i32 s36, s69, 0x58
	s_nop 0
	v_mad_i64_i32 v[16:17], s[36:37], s36, v211, v[134:135]
	s_barrier
	global_load_dwordx4 v[0:3], v[132:133], off
	s_add_i32 s36, s69, 0x60
	global_load_dwordx4 v[4:7], v[4:5], off
	s_nop 0
	global_load_dwordx4 v[8:11], v[8:9], off
	v_mad_i64_i32 v[20:21], s[36:37], s36, v211, v[134:135]
	s_add_i32 s36, s69, 0x68
	global_load_dwordx4 v[12:15], v[12:13], off
	s_nop 0
	global_load_dwordx4 v[16:19], v[16:17], off
	v_mad_i64_i32 v[24:25], s[36:37], s36, v211, v[134:135]
	s_add_i32 s36, s69, 0x70
	global_load_dwordx4 v[20:23], v[20:21], off
	s_nop 0
	global_load_dwordx4 v[24:27], v[24:25], off
	v_mad_i64_i32 v[28:29], s[36:37], s36, v211, v[134:135]
	s_addk_i32 s69, 0x78
	global_load_dwordx4 v[28:31], v[28:29], off
	v_mad_i64_i32 v[32:33], s[36:37], s69, v211, v[134:135]
	global_load_dwordx4 v[32:35], v[32:33], off
	s_lshl_b32 s36, s66, 6
	s_ashr_i32 s37, s70, 3
	s_add_i32 s36, s68, s36
	s_and_b32 s37, s37, -8
	s_add_i32 s36, s36, s37
	s_ashr_i32 s37, s36, 31
	s_lshl_b64 s[38:39], s[36:37], 12
	v_lshl_add_u64 v[36:37], v[136:137], 0, s[38:39]
	s_or_b32 s42, s36, 1
	s_ashr_i32 s43, s42, 31
	s_lshl_b64 s[38:39], s[42:43], 12
	v_mov_b64_e32 v[88:89], s[30:31]
	s_or_b32 s40, s36, 2
	s_ashr_i32 s41, s40, 31
	s_lshl_b64 s[68:69], s[40:41], 12
	s_lshl_b64 s[66:67], s[36:37], 11
	s_waitcnt vmcnt(7)
	v_pk_add_f32 v[2:3], v[2:3], v[6:7]
	v_pk_add_f32 v[0:1], v[0:1], v[4:5]
	s_waitcnt vmcnt(6)
	v_pk_add_f32 v[2:3], v[2:3], v[10:11]
	v_pk_add_f32 v[0:1], v[0:1], v[8:9]
	s_waitcnt vmcnt(5)
	v_pk_add_f32 v[2:3], v[2:3], v[14:15]
	v_pk_add_f32 v[0:1], v[0:1], v[12:13]
	s_waitcnt vmcnt(4)
	v_pk_add_f32 v[2:3], v[2:3], v[18:19]
	v_pk_add_f32 v[0:1], v[0:1], v[16:17]
	s_waitcnt vmcnt(3)
	v_pk_add_f32 v[2:3], v[2:3], v[22:23]
	v_pk_add_f32 v[0:1], v[0:1], v[20:21]
	s_waitcnt vmcnt(2)
	v_pk_add_f32 v[2:3], v[2:3], v[26:27]
	v_pk_add_f32 v[0:1], v[0:1], v[24:25]
	v_lshl_add_u64 v[8:9], v[136:137], 0, s[38:39]
	s_waitcnt vmcnt(1)
	v_pk_add_f32 v[2:3], v[2:3], v[30:31]
	v_pk_add_f32 v[0:1], v[0:1], v[28:29]
	s_or_b32 s38, s36, 3
	s_waitcnt vmcnt(0)
	v_pk_add_f32 v[2:3], v[2:3], v[34:35]
	v_pk_add_f32 v[0:1], v[0:1], v[32:33]
	v_pk_add_f32 v[4:5], v[2:3], 1.0 op_sel_hi:[1,0]
	v_pk_add_f32 v[6:7], v[0:1], 1.0 op_sel_hi:[1,0]
	v_cndmask_b32_e64 v3, v5, v3, s[6:7]
	v_cndmask_b32_e64 v2, v4, v2, s[6:7]
	v_cndmask_b32_e64 v1, v7, v1, s[6:7]
	v_cndmask_b32_e64 v0, v6, v0, s[6:7]
	ds_write_b128 v183, v[0:3]
	s_waitcnt lgkmcnt(0)
	s_barrier
	global_load_dwordx4 v[108:111], v[138:139], off
	global_load_dwordx4 v[112:115], v[142:143], off
	global_load_dwordx4 v[116:119], v[144:145], off
	global_load_dwordx4 v[120:123], v[146:147], off
	global_load_dwordx4 v[16:19], v[36:37], off
	global_load_dwordx4 v[4:7], v[36:37], off offset:1024
	global_load_dwordx4 v[80:83], v[36:37], off offset:3072
	global_load_dwordx4 v[0:3], v[36:37], off offset:2048
	global_load_dwordx4 v[76:79], v[8:9], off
	global_load_dwordx4 v[68:71], v[8:9], off offset:1024
	s_nop 0
	global_load_dwordx4 v[36:39], v[8:9], off offset:3072
	global_load_dwordx4 v[64:67], v[8:9], off offset:2048
	s_ashr_i32 s39, s38, 31
	s_lshl_b64 s[70:71], s[38:39], 12
	s_waitcnt vmcnt(3)
	v_pk_mul_f32 v[28:29], v[78:79], v[78:79]
	v_pk_mul_f32 v[8:9], v[18:19], v[18:19]
	v_pk_mul_f32 v[10:11], v[16:17], v[16:17]
	v_pk_mul_f32 v[12:13], v[6:7], v[6:7]
	v_pk_mul_f32 v[14:15], v[4:5], v[4:5]
	v_mul_f32_e32 v24, v1, v1
	v_mul_f32_e32 v26, v3, v3
	v_pk_mul_f32 v[30:31], v[76:77], v[76:77]
	s_waitcnt vmcnt(2)
	v_pk_mul_f32 v[32:33], v[70:71], v[70:71]
	v_pk_mul_f32 v[34:35], v[68:69], v[68:69]
	v_mul_f32_e32 v47, v82, v82
	v_mul_f32_e32 v48, v83, v83
	v_pk_mov_b32 v[44:45], v[10:11], v[8:9] op_sel:[1, 0]
	v_mov_b32_e32 v11, v9
	v_pk_mov_b32 v[8:9], v[14:15], v[12:13] op_sel:[1, 0]
	v_mov_b32_e32 v15, v13
	v_pk_fma_f32 v[12:13], v[0:1], v[0:1], v[24:25] op_sel_hi:[1, 1, 0]
	v_pk_fma_f32 v[24:25], v[2:3], v[2:3], v[26:27] op_sel_hi:[1, 1, 0]
	v_pk_mov_b32 v[26:27], v[30:31], v[28:29] op_sel:[1, 0]
	v_mov_b32_e32 v31, v29
	v_pk_mov_b32 v[28:29], v[34:35], v[32:33] op_sel:[1, 0]
	v_mov_b32_e32 v35, v33
	v_mul_f32_e32 v43, v80, v80
	s_waitcnt vmcnt(0)
	v_mul_f32_e32 v40, v65, v65
	v_mul_f32_e32 v42, v67, v67
	v_pk_add_f32 v[10:11], v[44:45], v[10:11]
	v_pk_add_f32 v[8:9], v[8:9], v[14:15]
	v_mov_b32_e32 v13, v47
	v_mov_b32_e32 v25, v48
	v_pk_add_f32 v[14:15], v[26:27], v[30:31]
	v_pk_add_f32 v[26:27], v[28:29], v[34:35]
	v_mul_f32_e32 v46, v81, v81
	v_mul_f32_e32 v49, v36, v36
	v_mul_f32_e32 v50, v37, v37
	v_mul_f32_e32 v51, v38, v38
	v_mul_f32_e32 v52, v39, v39
	v_pk_fma_f32 v[32:33], v[64:65], v[64:65], v[40:41] op_sel_hi:[1, 1, 0]
	v_pk_fma_f32 v[40:41], v[66:67], v[66:67], v[42:43] op_sel_hi:[1, 1, 0]
	v_pk_add_f32 v[10:11], v[10:11], v[10:11] op_sel:[0, 1] op_sel_hi:[1, 0]
	v_pk_add_f32 v[8:9], v[8:9], v[8:9] op_sel:[0, 1] op_sel_hi:[1, 0]
	v_pk_add_f32 v[12:13], v[12:13], v[24:25]
	v_pk_add_f32 v[14:15], v[14:15], v[14:15] op_sel:[0, 1] op_sel_hi:[1, 0]
	v_pk_add_f32 v[24:25], v[26:27], v[26:27] op_sel:[0, 1] op_sel_hi:[1, 0]
	v_mov_b32_e32 v33, v51
	v_mov_b32_e32 v41, v52
	v_mov_b32_e32 v11, v43
	v_mov_b32_e32 v9, v46
	v_mov_b32_e32 v15, v49
	v_mov_b32_e32 v25, v50
	v_pk_add_f32 v[26:27], v[32:33], v[40:41]
	v_pk_add_f32 v[8:9], v[10:11], v[8:9]
	v_pk_add_f32 v[10:11], v[14:15], v[24:25]
	v_pk_add_f32 v[8:9], v[8:9], v[12:13]
	v_pk_add_f32 v[10:11], v[10:11], v[26:27]
	v_mov_b32_e32 v13, v8
	v_mov_b32_e32 v12, v10
	v_mov_b32_e32 v8, v11
	v_pk_add_f32 v[8:9], v[12:13], v[8:9]
	v_lshl_add_u64 v[12:13], v[136:137], 0, s[68:69]
	v_lshl_add_u64 v[14:15], v[136:137], 0, s[70:71]
	global_load_dwordx4 v[72:75], v[12:13], off
	global_load_dwordx4 v[60:63], v[12:13], off offset:1024
	global_load_dwordx4 v[56:59], v[12:13], off offset:2048
	global_load_dwordx4 v[52:55], v[12:13], off offset:3072
	global_load_dwordx4 v[48:51], v[14:15], off
	global_load_dwordx4 v[44:47], v[14:15], off offset:1024
	s_waitcnt lgkmcnt(0)
	s_nop 1
	v_add_f32_dpp v8, v8, v8 quad_perm:[1,0,3,2] row_mask:0xf bank_mask:0xf
	v_add_f32_dpp v9, v9, v9 quad_perm:[1,0,3,2] row_mask:0xf bank_mask:0xf
	global_load_dwordx4 v[40:43], v[14:15], off offset:2048
	global_load_dwordx4 v[32:35], v[14:15], off offset:3072
	v_lshl_add_u64 v[24:25], v[140:141], 0, s[66:67]
	s_add_u32 s66, s10, s66
	s_addc_u32 s67, s11, s67
	s_waitcnt lgkmcnt(0)
	s_nop 1
	v_add_f32_dpp v8, v8, v8 quad_perm:[2,3,0,1] row_mask:0xf bank_mask:0xf
	v_add_f32_dpp v9, v9, v9 quad_perm:[2,3,0,1] row_mask:0xf bank_mask:0xf
	s_lshl_b64 s[42:43], s[42:43], 11
	s_waitcnt lgkmcnt(0)
	s_nop 1
	v_add_f32_dpp v8, v8, v8 row_half_mirror row_mask:0xf bank_mask:0xf
	v_add_f32_dpp v9, v9, v9 row_half_mirror row_mask:0xf bank_mask:0xf
	s_waitcnt lgkmcnt(0)
	s_nop 1
	v_add_f32_dpp v8, v8, v8 row_mirror row_mask:0xf bank_mask:0xf
	v_add_f32_dpp v9, v9, v9 row_mirror row_mask:0xf bank_mask:0xf
	ds_bpermute_b32 v11, v188, v9
	ds_bpermute_b32 v10, v188, v8
	s_waitcnt lgkmcnt(0)
	v_pk_add_f32 v[8:9], v[8:9], v[10:11]
	s_waitcnt lgkmcnt(0)
	v_mov_b32_e32 v10, v8
	v_mov_b32_e32 v11, v9
	s_nop 1
	v_permlane32_swap_b32_e32 v10, v8
	v_permlane32_swap_b32_e32 v11, v9
	v_pk_add_f32 v[8:9], v[8:9], v[10:11]
	s_nop 0
	v_pk_fma_f32 v[90:91], v[8:9], s[28:29], v[88:89] op_sel_hi:[1, 0, 0]
	s_waitcnt vmcnt(4)
	v_mul_f32_e32 v99, v53, v53
	v_mul_f32_e32 v8, 0x4b800000, v91
	v_cmp_gt_f32_e32 vcc, s63, v91
	s_waitcnt vmcnt(2)
	v_pk_mul_f32 v[94:95], v[44:45], v[44:45]
	v_mul_f32_e32 v102, v54, v54
	v_cndmask_b32_e32 v8, v91, v8, vcc
	v_rsq_f32_e32 v26, v8
	ds_read_b128 v[8:11], v190
	ds_read_b128 v[12:15], v191
	s_waitcnt vmcnt(1)
	v_mul_f32_e32 v96, v41, v41
	v_mul_f32_e32 v98, v43, v43
	v_mul_f32_e32 v27, 0x45800000, v26
	v_cndmask_b32_e32 v92, v26, v27, vcc
	v_pk_mul_f32 v[18:19], v[18:19], v[92:93] op_sel_hi:[1, 0]
	v_pk_mul_f32 v[16:17], v[16:17], v[92:93] op_sel_hi:[1, 0]
	v_pk_mul_f32 v[18:19], v[110:111], v[18:19]
	v_pk_mul_f32 v[16:17], v[108:109], v[16:17]
	s_waitcnt lgkmcnt(0)
	v_pk_fma_f32 v[18:19], v[14:15], v[18:19], v[10:11]
	v_pk_fma_f32 v[16:17], v[12:13], v[16:17], v[8:9]
	v_pk_mul_f32 v[6:7], v[6:7], v[92:93] op_sel_hi:[1, 0]
	v_cvt_pk_bf16_f32 v16, v16, v17
	v_cvt_pk_bf16_f32 v17, v18, v19
	global_store_dwordx2 v[24:25], v[16:17], off
	ds_read_b128 v[16:19], v192
	ds_read_b128 v[20:23], v193
	v_pk_mul_f32 v[4:5], v[4:5], v[92:93] op_sel_hi:[1, 0]
	v_pk_mul_f32 v[2:3], v[2:3], v[92:93] op_sel_hi:[1, 0]
	v_pk_mul_f32 v[0:1], v[0:1], v[92:93] op_sel_hi:[1, 0]
	v_pk_mul_f32 v[82:83], v[82:83], v[92:93] op_sel_hi:[1, 0]
	v_pk_mul_f32 v[80:81], v[80:81], v[92:93] op_sel_hi:[1, 0]
	v_cmp_gt_f32_e32 vcc, s63, v90
	v_pk_mul_f32 v[92:93], v[46:47], v[46:47]
	v_mul_f32_e32 v103, v55, v55
	s_waitcnt vmcnt(1)
	v_mul_f32_e32 v104, v32, v32
	v_mul_f32_e32 v105, v33, v33
	v_mul_f32_e32 v106, v34, v34
	v_mul_f32_e32 v107, v35, v35
	v_pk_mul_f32 v[4:5], v[112:113], v[4:5]
	v_pk_mul_f32 v[6:7], v[114:115], v[6:7]
	s_waitcnt lgkmcnt(0)
	v_pk_fma_f32 v[4:5], v[20:21], v[4:5], v[16:17]
	v_pk_fma_f32 v[6:7], v[22:23], v[6:7], v[18:19]
	v_cvt_pk_bf16_f32 v4, v4, v5
	v_cvt_pk_bf16_f32 v5, v6, v7
	global_store_dwordx2 v200, v[4:5], s[66:67]
	ds_read_b128 v[24:27], v194
	ds_read_b128 v[28:31], v195
	v_pk_mul_f32 v[0:1], v[116:117], v[0:1]
	v_pk_mul_f32 v[2:3], v[118:119], v[2:3]
	s_waitcnt lgkmcnt(0)
	v_pk_fma_f32 v[0:1], v[28:29], v[0:1], v[24:25]
	v_pk_fma_f32 v[2:3], v[30:31], v[2:3], v[26:27]
	v_cvt_pk_bf16_f32 v0, v0, v1
	v_cvt_pk_bf16_f32 v1, v2, v3
	global_store_dwordx2 v201, v[0:1], s[66:67]
	ds_read_b128 v[0:3], v196
	ds_read_b128 v[4:7], v197
	v_pk_mul_f32 v[80:81], v[80:81], v[120:121]
	v_pk_mul_f32 v[82:83], v[82:83], v[122:123]
	s_waitcnt lgkmcnt(0)
	v_pk_fma_f32 v[80:81], v[80:81], v[4:5], v[0:1]
	v_pk_fma_f32 v[82:83], v[82:83], v[6:7], v[2:3]
	v_cvt_pk_bf16_f32 v80, v80, v81
	v_cvt_pk_bf16_f32 v81, v82, v83
	global_store_dwordx2 v210, v[80:81], s[66:67]
	v_mul_f32_e32 v84, 0x4b800000, v90
	v_cndmask_b32_e32 v84, v90, v84, vcc
	v_rsq_f32_e32 v86, v84
	v_lshl_add_u64 v[84:85], v[140:141], 0, s[42:43]
	s_add_u32 s42, s10, s42
	s_addc_u32 s43, s11, s43
	v_mul_f32_e32 v87, 0x45800000, v86
	v_cndmask_b32_e32 v86, v86, v87, vcc
	v_pk_mul_f32 v[78:79], v[78:79], v[86:87] op_sel_hi:[1, 0]
	v_pk_mul_f32 v[76:77], v[76:77], v[86:87] op_sel_hi:[1, 0]
	v_pk_mul_f32 v[70:71], v[70:71], v[86:87] op_sel_hi:[1, 0]
	v_pk_mul_f32 v[68:69], v[68:69], v[86:87] op_sel_hi:[1, 0]
	v_pk_mul_f32 v[66:67], v[66:67], v[86:87] op_sel_hi:[1, 0]
	v_pk_mul_f32 v[64:65], v[64:65], v[86:87] op_sel_hi:[1, 0]
	v_mul_f32_e32 v87, v52, v52
	v_pk_mul_f32 v[38:39], v[38:39], v[86:87] op_sel_hi:[1, 0]
	v_pk_mul_f32 v[36:37], v[36:37], v[86:87] op_sel_hi:[1, 0]
	v_pk_mul_f32 v[90:91], v[48:49], v[48:49]
	s_lshl_b64 s[40:41], s[40:41], 11
	v_pk_mul_f32 v[76:77], v[108:109], v[76:77]
	v_pk_mul_f32 v[78:79], v[110:111], v[78:79]
	v_pk_fma_f32 v[76:77], v[12:13], v[76:77], v[8:9]
	v_pk_fma_f32 v[78:79], v[14:15], v[78:79], v[10:11]
	v_cvt_pk_bf16_f32 v76, v76, v77
	v_cvt_pk_bf16_f32 v77, v78, v79
	global_store_dwordx2 v[84:85], v[76:77], off
	v_mul_f32_e32 v80, v57, v57
	v_mul_f32_e32 v82, v59, v59
	v_pk_mul_f32 v[84:85], v[50:51], v[50:51]
	v_pk_mul_f32 v[68:69], v[112:113], v[68:69]
	v_pk_mul_f32 v[70:71], v[114:115], v[70:71]
	v_pk_fma_f32 v[68:69], v[20:21], v[68:69], v[16:17]
	v_pk_fma_f32 v[70:71], v[22:23], v[70:71], v[18:19]
	v_cvt_pk_bf16_f32 v68, v68, v69
	v_cvt_pk_bf16_f32 v69, v70, v71
	global_store_dwordx2 v200, v[68:69], s[42:43]
	v_pk_mul_f32 v[76:77], v[62:63], v[62:63]
	v_pk_mul_f32 v[78:79], v[60:61], v[60:61]
	v_pk_mul_f32 v[64:65], v[116:117], v[64:65]
	v_pk_mul_f32 v[66:67], v[118:119], v[66:67]
	v_pk_fma_f32 v[64:65], v[28:29], v[64:65], v[24:25]
	v_pk_fma_f32 v[66:67], v[30:31], v[66:67], v[26:27]
	v_cvt_pk_bf16_f32 v64, v64, v65
	v_cvt_pk_bf16_f32 v65, v66, v67
	global_store_dwordx2 v201, v[64:65], s[42:43]
	v_pk_mul_f32 v[68:69], v[74:75], v[74:75]
	v_pk_mul_f32 v[70:71], v[72:73], v[72:73]
	v_pk_mul_f32 v[36:37], v[120:121], v[36:37]
	v_pk_mul_f32 v[38:39], v[122:123], v[38:39]
	v_pk_fma_f32 v[36:37], v[4:5], v[36:37], v[0:1]
	v_pk_fma_f32 v[38:39], v[6:7], v[38:39], v[2:3]
	v_cvt_pk_bf16_f32 v36, v36, v37
	v_cvt_pk_bf16_f32 v37, v38, v39
	global_store_dwordx2 v210, v[36:37], s[42:43]
	v_pk_mov_b32 v[100:101], v[70:71], v[68:69] op_sel:[1, 0]
	v_mov_b32_e32 v71, v69
	v_pk_mov_b32 v[68:69], v[78:79], v[76:77] op_sel:[1, 0]
	v_mov_b32_e32 v79, v77
	v_pk_fma_f32 v[76:77], v[56:57], v[56:57], v[80:81] op_sel_hi:[1, 1, 0]
	v_pk_fma_f32 v[80:81], v[58:59], v[58:59], v[82:83] op_sel_hi:[1, 1, 0]
	v_pk_mov_b32 v[82:83], v[90:91], v[84:85] op_sel:[1, 0]
	v_mov_b32_e32 v91, v85
	v_pk_mov_b32 v[84:85], v[94:95], v[92:93] op_sel:[1, 0]
	v_mov_b32_e32 v95, v93
	v_pk_add_f32 v[70:71], v[100:101], v[70:71]
	v_pk_add_f32 v[64:65], v[68:69], v[78:79]
	v_pk_add_f32 v[66:67], v[82:83], v[90:91]
	v_pk_add_f32 v[68:69], v[84:85], v[94:95]
	v_pk_fma_f32 v[92:93], v[40:41], v[40:41], v[96:97] op_sel_hi:[1, 1, 0]
	v_pk_fma_f32 v[96:97], v[42:43], v[42:43], v[98:99] op_sel_hi:[1, 1, 0]
	v_pk_add_f32 v[70:71], v[70:71], v[70:71] op_sel:[0, 1] op_sel_hi:[1, 0]
	v_pk_add_f32 v[64:65], v[64:65], v[64:65] op_sel:[0, 1] op_sel_hi:[1, 0]
	v_pk_add_f32 v[66:67], v[66:67], v[66:67] op_sel:[0, 1] op_sel_hi:[1, 0]
	v_pk_add_f32 v[68:69], v[68:69], v[68:69] op_sel:[0, 1] op_sel_hi:[1, 0]
	v_mov_b32_e32 v77, v102
	v_mov_b32_e32 v81, v103
	v_mov_b32_e32 v93, v106
	v_mov_b32_e32 v97, v107
	v_mov_b32_e32 v71, v87
	v_mov_b32_e32 v65, v99
	v_mov_b32_e32 v67, v104
	v_mov_b32_e32 v69, v105
	v_pk_add_f32 v[76:77], v[76:77], v[80:81]
	v_pk_add_f32 v[78:79], v[92:93], v[96:97]
	v_pk_add_f32 v[64:65], v[70:71], v[64:65]
	v_pk_add_f32 v[66:67], v[66:67], v[68:69]
	v_pk_add_f32 v[64:65], v[64:65], v[76:77]
	v_pk_add_f32 v[66:67], v[66:67], v[78:79]
	v_mov_b32_e32 v69, v64
	v_mov_b32_e32 v68, v66
	v_mov_b32_e32 v64, v67
	v_pk_add_f32 v[64:65], v[68:69], v[64:65]
	s_waitcnt lgkmcnt(0)
	s_nop 1
	v_add_f32_dpp v64, v64, v64 quad_perm:[1,0,3,2] row_mask:0xf bank_mask:0xf
	v_add_f32_dpp v65, v65, v65 quad_perm:[1,0,3,2] row_mask:0xf bank_mask:0xf
	s_waitcnt lgkmcnt(0)
	s_nop 1
	v_add_f32_dpp v64, v64, v64 quad_perm:[2,3,0,1] row_mask:0xf bank_mask:0xf
	v_add_f32_dpp v65, v65, v65 quad_perm:[2,3,0,1] row_mask:0xf bank_mask:0xf
	s_waitcnt lgkmcnt(0)
	s_nop 1
	v_add_f32_dpp v64, v64, v64 row_half_mirror row_mask:0xf bank_mask:0xf
	v_add_f32_dpp v65, v65, v65 row_half_mirror row_mask:0xf bank_mask:0xf
	s_waitcnt lgkmcnt(0)
	s_nop 1
	v_add_f32_dpp v64, v64, v64 row_mirror row_mask:0xf bank_mask:0xf
	v_add_f32_dpp v65, v65, v65 row_mirror row_mask:0xf bank_mask:0xf
	ds_bpermute_b32 v67, v188, v65
	ds_bpermute_b32 v66, v188, v64
	s_waitcnt lgkmcnt(0)
	v_pk_add_f32 v[64:65], v[64:65], v[66:67]
	s_waitcnt lgkmcnt(0)
	v_mov_b32_e32 v66, v64
	v_mov_b32_e32 v67, v65
	s_nop 1
	v_permlane32_swap_b32_e32 v66, v64
	v_permlane32_swap_b32_e32 v67, v65
	v_pk_add_f32 v[64:65], v[64:65], v[66:67]
	s_nop 0
	v_pk_fma_f32 v[64:65], v[64:65], s[28:29], v[88:89] op_sel_hi:[1, 0, 0]
	s_nop 0
	v_mul_f32_e32 v66, 0x4b800000, v65
	v_cmp_gt_f32_e32 vcc, s63, v65
	s_nop 1
	v_cndmask_b32_e32 v65, v65, v66, vcc
	v_rsq_f32_e32 v65, v65
	v_lshl_add_u64 v[66:67], v[140:141], 0, s[40:41]
	s_add_u32 s40, s10, s40
	s_addc_u32 s41, s11, s41
	v_mul_f32_e32 v68, 0x45800000, v65
	v_cndmask_b32_e32 v68, v65, v68, vcc
	v_pk_mul_f32 v[70:71], v[74:75], v[68:69] op_sel_hi:[1, 0]
	v_pk_mul_f32 v[72:73], v[72:73], v[68:69] op_sel_hi:[1, 0]
	v_pk_mul_f32 v[38:39], v[110:111], v[70:71]
	v_pk_mul_f32 v[36:37], v[108:109], v[72:73]
	v_pk_fma_f32 v[38:39], v[14:15], v[38:39], v[10:11]
	v_pk_fma_f32 v[36:37], v[12:13], v[36:37], v[8:9]
	v_pk_mul_f32 v[62:63], v[62:63], v[68:69] op_sel_hi:[1, 0]
	v_cvt_pk_bf16_f32 v36, v36, v37
	v_cvt_pk_bf16_f32 v37, v38, v39
	global_store_dwordx2 v[66:67], v[36:37], off
	v_pk_mul_f32 v[60:61], v[60:61], v[68:69] op_sel_hi:[1, 0]
	v_pk_mul_f32 v[58:59], v[58:59], v[68:69] op_sel_hi:[1, 0]
	v_pk_mul_f32 v[56:57], v[56:57], v[68:69] op_sel_hi:[1, 0]
	v_pk_mul_f32 v[54:55], v[54:55], v[68:69] op_sel_hi:[1, 0]
	v_pk_mul_f32 v[52:53], v[52:53], v[68:69] op_sel_hi:[1, 0]
	v_cmp_gt_f32_e32 vcc, s63, v64
	s_lshl_b64 s[38:39], s[38:39], 11
	v_pk_mul_f32 v[36:37], v[112:113], v[60:61]
	v_pk_mul_f32 v[38:39], v[114:115], v[62:63]
	v_pk_fma_f32 v[36:37], v[20:21], v[36:37], v[16:17]
	v_pk_fma_f32 v[38:39], v[22:23], v[38:39], v[18:19]
	v_cvt_pk_bf16_f32 v36, v36, v37
	v_cvt_pk_bf16_f32 v37, v38, v39
	global_store_dwordx2 v200, v[36:37], s[40:41]
	v_pk_mul_f32 v[36:37], v[116:117], v[56:57]
	v_pk_mul_f32 v[38:39], v[118:119], v[58:59]
	v_pk_fma_f32 v[36:37], v[28:29], v[36:37], v[24:25]
	v_pk_fma_f32 v[38:39], v[30:31], v[38:39], v[26:27]
	v_cvt_pk_bf16_f32 v36, v36, v37
	v_cvt_pk_bf16_f32 v37, v38, v39
	global_store_dwordx2 v201, v[36:37], s[40:41]
	v_pk_mul_f32 v[36:37], v[120:121], v[52:53]
	v_pk_mul_f32 v[38:39], v[122:123], v[54:55]
	v_pk_fma_f32 v[36:37], v[4:5], v[36:37], v[0:1]
	v_pk_fma_f32 v[38:39], v[6:7], v[38:39], v[2:3]
	v_cvt_pk_bf16_f32 v36, v36, v37
	v_cvt_pk_bf16_f32 v37, v38, v39
	global_store_dwordx2 v210, v[36:37], s[40:41]
	v_mul_f32_e32 v52, 0x4b800000, v64
	v_cndmask_b32_e32 v52, v64, v52, vcc
	v_rsq_f32_e32 v54, v52
	v_lshl_add_u64 v[52:53], v[140:141], 0, s[38:39]
	s_add_u32 s38, s10, s38
	s_addc_u32 s39, s11, s39
	v_mul_f32_e32 v55, 0x45800000, v54
	v_cndmask_b32_e32 v54, v54, v55, vcc
	v_pk_mul_f32 v[50:51], v[50:51], v[54:55] op_sel_hi:[1, 0]
	v_pk_mul_f32 v[48:49], v[48:49], v[54:55] op_sel_hi:[1, 0]
	v_pk_mul_f32 v[46:47], v[46:47], v[54:55] op_sel_hi:[1, 0]
	v_pk_mul_f32 v[44:45], v[44:45], v[54:55] op_sel_hi:[1, 0]
	v_pk_mul_f32 v[42:43], v[42:43], v[54:55] op_sel_hi:[1, 0]
	v_pk_mul_f32 v[40:41], v[40:41], v[54:55] op_sel_hi:[1, 0]
	v_pk_mul_f32 v[34:35], v[34:35], v[54:55] op_sel_hi:[1, 0]
	v_pk_mul_f32 v[32:33], v[32:33], v[54:55] op_sel_hi:[1, 0]
	s_or_b32 s42, s36, 4
	s_ashr_i32 s43, s42, 31
	s_lshl_b64 s[40:41], s[42:43], 12
	s_lshl_b64 s[42:43], s[42:43], 11
	v_lshl_add_u64 v[104:105], v[140:141], 0, s[42:43]
	v_pk_mul_f32 v[36:37], v[108:109], v[48:49]
	v_pk_mul_f32 v[38:39], v[110:111], v[50:51]
	v_pk_fma_f32 v[36:37], v[12:13], v[36:37], v[8:9]
	v_pk_fma_f32 v[38:39], v[14:15], v[38:39], v[10:11]
	v_cvt_pk_bf16_f32 v36, v36, v37
	v_cvt_pk_bf16_f32 v37, v38, v39
	global_store_dwordx2 v[52:53], v[36:37], off
	v_pk_mul_f32 v[36:37], v[112:113], v[44:45]
	v_pk_mul_f32 v[38:39], v[114:115], v[46:47]
	v_pk_fma_f32 v[36:37], v[20:21], v[36:37], v[16:17]
	v_pk_fma_f32 v[38:39], v[22:23], v[38:39], v[18:19]
	v_cvt_pk_bf16_f32 v36, v36, v37
	v_cvt_pk_bf16_f32 v37, v38, v39
	global_store_dwordx2 v200, v[36:37], s[38:39]
	v_pk_mul_f32 v[36:37], v[116:117], v[40:41]
	v_pk_mul_f32 v[38:39], v[118:119], v[42:43]
	v_pk_fma_f32 v[36:37], v[28:29], v[36:37], v[24:25]
	v_pk_fma_f32 v[38:39], v[30:31], v[38:39], v[26:27]
	v_cvt_pk_bf16_f32 v36, v36, v37
	v_cvt_pk_bf16_f32 v37, v38, v39
	global_store_dwordx2 v201, v[36:37], s[38:39]
	v_lshl_add_u64 v[40:41], v[136:137], 0, s[40:41]
	s_or_b32 s40, s36, 5
	s_ashr_i32 s41, s40, 31
	v_pk_mul_f32 v[32:33], v[120:121], v[32:33]
	v_pk_mul_f32 v[34:35], v[122:123], v[34:35]
	v_pk_fma_f32 v[32:33], v[4:5], v[32:33], v[0:1]
	v_pk_fma_f32 v[34:35], v[6:7], v[34:35], v[2:3]
	v_cvt_pk_bf16_f32 v32, v32, v33
	v_cvt_pk_bf16_f32 v33, v34, v35
	global_store_dwordx2 v210, v[32:33], s[38:39]
	global_load_dwordx4 v[90:93], v[40:41], off
	global_load_dwordx4 v[94:97], v[40:41], off offset:1024
	global_load_dwordx4 v[80:83], v[40:41], off offset:3072
	global_load_dwordx4 v[84:87], v[40:41], off offset:2048
	s_lshl_b64 s[38:39], s[40:41], 12
	v_lshl_add_u64 v[32:33], v[136:137], 0, s[38:39]
	global_load_dwordx4 v[76:79], v[32:33], off
	global_load_dwordx4 v[72:75], v[32:33], off offset:1024
	global_load_dwordx4 v[36:39], v[32:33], off offset:3072
	global_load_dwordx4 v[68:71], v[32:33], off offset:2048
	s_or_b32 s38, s36, 6
	s_or_b32 s36, s36, 7
	s_ashr_i32 s39, s38, 31
	s_ashr_i32 s37, s36, 31
	s_lshl_b64 s[66:67], s[38:39], 12
	s_lshl_b64 s[68:69], s[36:37], 12
	s_add_u32 s42, s10, s42
	s_addc_u32 s43, s11, s43
	s_lshl_b64 s[40:41], s[40:41], 11
	s_waitcnt vmcnt(7)
	v_pk_mul_f32 v[32:33], v[92:93], v[92:93]
	v_pk_mul_f32 v[34:35], v[90:91], v[90:91]
	s_waitcnt vmcnt(6)
	v_pk_mul_f32 v[40:41], v[96:97], v[96:97]
	v_pk_mul_f32 v[42:43], v[94:95], v[94:95]
	s_waitcnt vmcnt(4)
	v_mul_f32_e32 v44, v85, v85
	v_mul_f32_e32 v46, v87, v87
	s_waitcnt vmcnt(3)
	v_pk_mul_f32 v[48:49], v[78:79], v[78:79]
	v_pk_mul_f32 v[50:51], v[76:77], v[76:77]
	s_waitcnt vmcnt(2)
	v_pk_mul_f32 v[52:53], v[74:75], v[74:75]
	v_pk_mul_f32 v[54:55], v[72:73], v[72:73]
	v_mul_f32_e32 v63, v82, v82
	v_mul_f32_e32 v64, v83, v83
	v_pk_mov_b32 v[60:61], v[34:35], v[32:33] op_sel:[1, 0]
	v_mov_b32_e32 v35, v33
	v_pk_mov_b32 v[32:33], v[42:43], v[40:41] op_sel:[1, 0]
	v_mov_b32_e32 v43, v41
	v_pk_fma_f32 v[40:41], v[84:85], v[84:85], v[44:45] op_sel_hi:[1, 1, 0]
	v_pk_fma_f32 v[44:45], v[86:87], v[86:87], v[46:47] op_sel_hi:[1, 1, 0]
	v_pk_mov_b32 v[46:47], v[50:51], v[48:49] op_sel:[1, 0]
	v_mov_b32_e32 v51, v49
	v_pk_mov_b32 v[48:49], v[54:55], v[52:53] op_sel:[1, 0]
	v_mov_b32_e32 v55, v53
	v_mul_f32_e32 v59, v80, v80
	s_waitcnt vmcnt(0)
	v_mul_f32_e32 v56, v69, v69
	v_mul_f32_e32 v58, v71, v71
	v_pk_add_f32 v[34:35], v[60:61], v[34:35]
	v_pk_add_f32 v[32:33], v[32:33], v[42:43]
	v_mov_b32_e32 v41, v63
	v_mov_b32_e32 v45, v64
	v_pk_add_f32 v[42:43], v[46:47], v[50:51]
	v_pk_add_f32 v[46:47], v[48:49], v[54:55]
	v_mul_f32_e32 v62, v81, v81
	v_mul_f32_e32 v65, v36, v36
	v_mul_f32_e32 v66, v37, v37
	v_mul_f32_e32 v67, v38, v38
	v_mul_f32_e32 v102, v39, v39
	v_pk_fma_f32 v[52:53], v[68:69], v[68:69], v[56:57] op_sel_hi:[1, 1, 0]
	v_pk_fma_f32 v[56:57], v[70:71], v[70:71], v[58:59] op_sel_hi:[1, 1, 0]
	v_pk_add_f32 v[34:35], v[34:35], v[34:35] op_sel:[0, 1] op_sel_hi:[1, 0]
	v_pk_add_f32 v[32:33], v[32:33], v[32:33] op_sel:[0, 1] op_sel_hi:[1, 0]
	v_pk_add_f32 v[40:41], v[40:41], v[44:45]
	v_pk_add_f32 v[42:43], v[42:43], v[42:43] op_sel:[0, 1] op_sel_hi:[1, 0]
	v_pk_add_f32 v[44:45], v[46:47], v[46:47] op_sel:[0, 1] op_sel_hi:[1, 0]
	v_mov_b32_e32 v53, v67
	v_mov_b32_e32 v57, v102
	v_mov_b32_e32 v35, v59
	v_mov_b32_e32 v33, v62
	v_mov_b32_e32 v43, v65
	v_mov_b32_e32 v45, v66
	v_pk_add_f32 v[46:47], v[52:53], v[56:57]
	v_pk_add_f32 v[32:33], v[34:35], v[32:33]
	v_pk_add_f32 v[34:35], v[42:43], v[44:45]
	v_pk_add_f32 v[32:33], v[32:33], v[40:41]
	v_pk_add_f32 v[34:35], v[34:35], v[46:47]
	v_mov_b32_e32 v41, v32
	v_mov_b32_e32 v40, v34
	v_mov_b32_e32 v32, v35
	v_pk_add_f32 v[32:33], v[40:41], v[32:33]
	v_lshl_add_u64 v[40:41], v[136:137], 0, s[66:67]
	v_lshl_add_u64 v[102:103], v[136:137], 0, s[68:69]
	global_load_dwordx4 v[64:67], v[40:41], off
	global_load_dwordx4 v[60:63], v[40:41], off offset:1024
	global_load_dwordx4 v[56:59], v[40:41], off offset:2048
	global_load_dwordx4 v[52:55], v[40:41], off offset:3072
	s_waitcnt lgkmcnt(0)
	s_nop 1
	v_add_f32_dpp v32, v32, v32 quad_perm:[1,0,3,2] row_mask:0xf bank_mask:0xf
	v_add_f32_dpp v33, v33, v33 quad_perm:[1,0,3,2] row_mask:0xf bank_mask:0xf
	s_waitcnt lgkmcnt(0)
	s_nop 1
	v_add_f32_dpp v32, v32, v32 quad_perm:[2,3,0,1] row_mask:0xf bank_mask:0xf
	v_add_f32_dpp v33, v33, v33 quad_perm:[2,3,0,1] row_mask:0xf bank_mask:0xf
	s_waitcnt lgkmcnt(0)
	s_nop 1
	v_add_f32_dpp v32, v32, v32 row_half_mirror row_mask:0xf bank_mask:0xf
	v_add_f32_dpp v33, v33, v33 row_half_mirror row_mask:0xf bank_mask:0xf
	s_waitcnt lgkmcnt(0)
	s_nop 1
	v_add_f32_dpp v32, v32, v32 row_mirror row_mask:0xf bank_mask:0xf
	v_add_f32_dpp v33, v33, v33 row_mirror row_mask:0xf bank_mask:0xf
	ds_bpermute_b32 v35, v188, v33
	ds_bpermute_b32 v34, v188, v32
	s_waitcnt lgkmcnt(0)
	v_pk_add_f32 v[32:33], v[32:33], v[34:35]
	s_waitcnt lgkmcnt(0)
	v_mov_b32_e32 v34, v32
	v_mov_b32_e32 v35, v33
	s_nop 1
	v_permlane32_swap_b32_e32 v34, v32
	v_permlane32_swap_b32_e32 v35, v33
	v_pk_add_f32 v[32:33], v[32:33], v[34:35]
	s_nop 0
	v_pk_fma_f32 v[106:107], v[32:33], s[28:29], v[88:89] op_sel_hi:[1, 0, 0]
	s_nop 0
	v_mul_f32_e32 v32, 0x4b800000, v107
	v_cmp_gt_f32_e32 vcc, s63, v107
	s_nop 1
	v_cndmask_b32_e32 v32, v107, v32, vcc
	v_rsq_f32_e32 v107, v32
	global_load_dwordx4 v[48:51], v[102:103], off
	global_load_dwordx4 v[44:47], v[102:103], off offset:1024
	global_load_dwordx4 v[40:43], v[102:103], off offset:2048
	global_load_dwordx4 v[32:35], v[102:103], off offset:3072
	v_mul_f32_e32 v102, 0x45800000, v107
	v_cndmask_b32_e32 v102, v107, v102, vcc
	v_pk_mul_f32 v[92:93], v[92:93], v[102:103] op_sel_hi:[1, 0]
	v_pk_mul_f32 v[90:91], v[90:91], v[102:103] op_sel_hi:[1, 0]
	v_pk_mul_f32 v[92:93], v[110:111], v[92:93]
	v_pk_mul_f32 v[90:91], v[108:109], v[90:91]
	v_pk_fma_f32 v[92:93], v[14:15], v[92:93], v[10:11]
	v_pk_fma_f32 v[90:91], v[12:13], v[90:91], v[8:9]
	v_pk_mul_f32 v[96:97], v[96:97], v[102:103] op_sel_hi:[1, 0]
	v_cvt_pk_bf16_f32 v90, v90, v91
	v_cvt_pk_bf16_f32 v91, v92, v93
	global_store_dwordx2 v[104:105], v[90:91], off
	v_pk_mul_f32 v[94:95], v[94:95], v[102:103] op_sel_hi:[1, 0]
	v_pk_mul_f32 v[86:87], v[86:87], v[102:103] op_sel_hi:[1, 0]
	v_pk_mul_f32 v[84:85], v[84:85], v[102:103] op_sel_hi:[1, 0]
	v_pk_mul_f32 v[82:83], v[82:83], v[102:103] op_sel_hi:[1, 0]
	v_pk_mul_f32 v[80:81], v[80:81], v[102:103] op_sel_hi:[1, 0]
	v_cmp_gt_f32_e32 vcc, s63, v106
	s_waitcnt vmcnt(5)
	v_mul_f32_e32 v99, v53, v53
	v_mul_f32_e32 v102, v54, v54
	v_mul_f32_e32 v103, v55, v55
	s_waitcnt vmcnt(2)
	v_mul_f32_e32 v98, v43, v43
	s_waitcnt vmcnt(1)
	v_mul_f32_e32 v104, v32, v32
	v_mul_f32_e32 v105, v33, v33
	v_mul_f32_e32 v107, v35, v35
	v_pk_mul_f32 v[90:91], v[112:113], v[94:95]
	v_pk_mul_f32 v[92:93], v[114:115], v[96:97]
	v_pk_fma_f32 v[90:91], v[20:21], v[90:91], v[16:17]
	v_pk_fma_f32 v[92:93], v[22:23], v[92:93], v[18:19]
	v_cvt_pk_bf16_f32 v90, v90, v91
	v_cvt_pk_bf16_f32 v91, v92, v93
	global_store_dwordx2 v200, v[90:91], s[42:43]
	v_pk_mul_f32 v[94:95], v[44:45], v[44:45]
	v_mul_f32_e32 v96, v41, v41
	v_pk_mul_f32 v[84:85], v[116:117], v[84:85]
	v_pk_mul_f32 v[86:87], v[118:119], v[86:87]
	v_pk_fma_f32 v[84:85], v[28:29], v[84:85], v[24:25]
	v_pk_fma_f32 v[86:87], v[30:31], v[86:87], v[26:27]
	v_cvt_pk_bf16_f32 v84, v84, v85
	v_cvt_pk_bf16_f32 v85, v86, v87
	global_store_dwordx2 v201, v[84:85], s[42:43]
	v_pk_mul_f32 v[90:91], v[48:49], v[48:49]
	v_pk_mul_f32 v[92:93], v[46:47], v[46:47]
	v_pk_mul_f32 v[80:81], v[120:121], v[80:81]
	v_pk_mul_f32 v[82:83], v[122:123], v[82:83]
	v_pk_fma_f32 v[80:81], v[4:5], v[80:81], v[0:1]
	v_pk_fma_f32 v[82:83], v[6:7], v[82:83], v[2:3]
	v_cvt_pk_bf16_f32 v80, v80, v81
	v_cvt_pk_bf16_f32 v81, v82, v83
	global_store_dwordx2 v210, v[80:81], s[42:43]
	v_mul_f32_e32 v84, 0x4b800000, v106
	v_cndmask_b32_e32 v84, v106, v84, vcc
	v_rsq_f32_e32 v86, v84
	v_lshl_add_u64 v[84:85], v[140:141], 0, s[40:41]
	s_add_u32 s40, s10, s40
	s_addc_u32 s41, s11, s41
	v_mul_f32_e32 v87, 0x45800000, v86
	v_cndmask_b32_e32 v86, v86, v87, vcc
	v_pk_mul_f32 v[78:79], v[78:79], v[86:87] op_sel_hi:[1, 0]
	v_pk_mul_f32 v[76:77], v[76:77], v[86:87] op_sel_hi:[1, 0]
	v_pk_mul_f32 v[74:75], v[74:75], v[86:87] op_sel_hi:[1, 0]
	v_pk_mul_f32 v[72:73], v[72:73], v[86:87] op_sel_hi:[1, 0]
	v_pk_mul_f32 v[70:71], v[70:71], v[86:87] op_sel_hi:[1, 0]
	v_pk_mul_f32 v[68:69], v[68:69], v[86:87] op_sel_hi:[1, 0]
	v_mul_f32_e32 v87, v52, v52
	v_pk_mul_f32 v[38:39], v[38:39], v[86:87] op_sel_hi:[1, 0]
	v_pk_mul_f32 v[36:37], v[36:37], v[86:87] op_sel_hi:[1, 0]
	v_mul_f32_e32 v106, v34, v34
	s_lshl_b64 s[38:39], s[38:39], 11
	v_pk_mul_f32 v[76:77], v[108:109], v[76:77]
	v_pk_mul_f32 v[78:79], v[110:111], v[78:79]
	v_pk_fma_f32 v[76:77], v[12:13], v[76:77], v[8:9]
	v_pk_fma_f32 v[78:79], v[14:15], v[78:79], v[10:11]
	v_cvt_pk_bf16_f32 v76, v76, v77
	v_cvt_pk_bf16_f32 v77, v78, v79
	global_store_dwordx2 v[84:85], v[76:77], off
	v_mul_f32_e32 v80, v57, v57
	v_mul_f32_e32 v82, v59, v59
	v_pk_mul_f32 v[84:85], v[50:51], v[50:51]
	v_pk_mul_f32 v[72:73], v[112:113], v[72:73]
	v_pk_mul_f32 v[74:75], v[114:115], v[74:75]
	v_pk_fma_f32 v[72:73], v[20:21], v[72:73], v[16:17]
	v_pk_fma_f32 v[74:75], v[22:23], v[74:75], v[18:19]
	v_cvt_pk_bf16_f32 v72, v72, v73
	v_cvt_pk_bf16_f32 v73, v74, v75
	global_store_dwordx2 v200, v[72:73], s[40:41]
	v_pk_mul_f32 v[76:77], v[62:63], v[62:63]
	v_pk_mul_f32 v[78:79], v[60:61], v[60:61]
	v_pk_mul_f32 v[68:69], v[116:117], v[68:69]
	v_pk_mul_f32 v[70:71], v[118:119], v[70:71]
	v_pk_fma_f32 v[68:69], v[28:29], v[68:69], v[24:25]
	v_pk_fma_f32 v[70:71], v[30:31], v[70:71], v[26:27]
	v_cvt_pk_bf16_f32 v68, v68, v69
	v_cvt_pk_bf16_f32 v69, v70, v71
	global_store_dwordx2 v201, v[68:69], s[40:41]
	v_pk_mul_f32 v[72:73], v[66:67], v[66:67]
	v_pk_mul_f32 v[74:75], v[64:65], v[64:65]
	v_pk_mul_f32 v[36:37], v[120:121], v[36:37]
	v_pk_mul_f32 v[38:39], v[122:123], v[38:39]
	v_pk_fma_f32 v[36:37], v[4:5], v[36:37], v[0:1]
	v_pk_fma_f32 v[38:39], v[6:7], v[38:39], v[2:3]
	v_cvt_pk_bf16_f32 v36, v36, v37
	v_cvt_pk_bf16_f32 v37, v38, v39
	global_store_dwordx2 v210, v[36:37], s[40:41]
	v_pk_mov_b32 v[100:101], v[74:75], v[72:73] op_sel:[1, 0]
	v_mov_b32_e32 v75, v73
	v_pk_mov_b32 v[72:73], v[78:79], v[76:77] op_sel:[1, 0]
	v_mov_b32_e32 v79, v77
	v_pk_fma_f32 v[76:77], v[56:57], v[56:57], v[80:81] op_sel_hi:[1, 1, 0]
	v_pk_fma_f32 v[80:81], v[58:59], v[58:59], v[82:83] op_sel_hi:[1, 1, 0]
	v_pk_mov_b32 v[82:83], v[90:91], v[84:85] op_sel:[1, 0]
	v_mov_b32_e32 v91, v85
	v_pk_mov_b32 v[84:85], v[94:95], v[92:93] op_sel:[1, 0]
	v_mov_b32_e32 v95, v93
	v_pk_add_f32 v[74:75], v[100:101], v[74:75]
	v_pk_add_f32 v[68:69], v[72:73], v[78:79]
	v_pk_add_f32 v[70:71], v[82:83], v[90:91]
	v_pk_add_f32 v[72:73], v[84:85], v[94:95]
	v_pk_fma_f32 v[92:93], v[40:41], v[40:41], v[96:97] op_sel_hi:[1, 1, 0]
	v_pk_fma_f32 v[96:97], v[42:43], v[42:43], v[98:99] op_sel_hi:[1, 1, 0]
	v_pk_add_f32 v[74:75], v[74:75], v[74:75] op_sel:[0, 1] op_sel_hi:[1, 0]
	v_pk_add_f32 v[68:69], v[68:69], v[68:69] op_sel:[0, 1] op_sel_hi:[1, 0]
	v_pk_add_f32 v[70:71], v[70:71], v[70:71] op_sel:[0, 1] op_sel_hi:[1, 0]
	v_pk_add_f32 v[72:73], v[72:73], v[72:73] op_sel:[0, 1] op_sel_hi:[1, 0]
	v_mov_b32_e32 v77, v102
	v_mov_b32_e32 v81, v103
	v_mov_b32_e32 v93, v106
	v_mov_b32_e32 v97, v107
	v_mov_b32_e32 v75, v87
	v_mov_b32_e32 v69, v99
	v_mov_b32_e32 v71, v104
	v_mov_b32_e32 v73, v105
	v_pk_add_f32 v[76:77], v[76:77], v[80:81]
	v_pk_add_f32 v[78:79], v[92:93], v[96:97]
	v_pk_add_f32 v[68:69], v[74:75], v[68:69]
	v_pk_add_f32 v[70:71], v[70:71], v[72:73]
	v_pk_add_f32 v[68:69], v[68:69], v[76:77]
	v_pk_add_f32 v[70:71], v[70:71], v[78:79]
	v_mov_b32_e32 v73, v68
	v_mov_b32_e32 v72, v70
	v_mov_b32_e32 v68, v71
	v_pk_add_f32 v[68:69], v[72:73], v[68:69]
	s_waitcnt lgkmcnt(0)
	s_nop 1
	v_add_f32_dpp v68, v68, v68 quad_perm:[1,0,3,2] row_mask:0xf bank_mask:0xf
	v_add_f32_dpp v69, v69, v69 quad_perm:[1,0,3,2] row_mask:0xf bank_mask:0xf
	s_waitcnt lgkmcnt(0)
	s_nop 1
	v_add_f32_dpp v68, v68, v68 quad_perm:[2,3,0,1] row_mask:0xf bank_mask:0xf
	v_add_f32_dpp v69, v69, v69 quad_perm:[2,3,0,1] row_mask:0xf bank_mask:0xf
	s_waitcnt lgkmcnt(0)
	s_nop 1
	v_add_f32_dpp v68, v68, v68 row_half_mirror row_mask:0xf bank_mask:0xf
	v_add_f32_dpp v69, v69, v69 row_half_mirror row_mask:0xf bank_mask:0xf
	s_waitcnt lgkmcnt(0)
	s_nop 1
	v_add_f32_dpp v68, v68, v68 row_mirror row_mask:0xf bank_mask:0xf
	v_add_f32_dpp v69, v69, v69 row_mirror row_mask:0xf bank_mask:0xf
	ds_bpermute_b32 v71, v188, v69
	ds_bpermute_b32 v70, v188, v68
	s_waitcnt lgkmcnt(0)
	v_pk_add_f32 v[68:69], v[68:69], v[70:71]
	s_waitcnt lgkmcnt(0)
	v_mov_b32_e32 v70, v68
	v_mov_b32_e32 v71, v69
	s_nop 1
	v_permlane32_swap_b32_e32 v70, v68
	v_permlane32_swap_b32_e32 v71, v69
	v_pk_add_f32 v[68:69], v[68:69], v[70:71]
	s_nop 0
	v_pk_fma_f32 v[68:69], v[68:69], s[28:29], v[88:89] op_sel_hi:[1, 0, 0]
	s_nop 0
	v_mul_f32_e32 v70, 0x4b800000, v69
	v_cmp_gt_f32_e32 vcc, s63, v69
	s_nop 1
	v_cndmask_b32_e32 v69, v69, v70, vcc
	v_rsq_f32_e32 v69, v69
	v_lshl_add_u64 v[70:71], v[140:141], 0, s[38:39]
	s_add_u32 s38, s10, s38
	s_addc_u32 s39, s11, s39
	v_mul_f32_e32 v72, 0x45800000, v69
	v_cndmask_b32_e32 v72, v69, v72, vcc
	v_pk_mul_f32 v[66:67], v[66:67], v[72:73] op_sel_hi:[1, 0]
	v_pk_mul_f32 v[64:65], v[64:65], v[72:73] op_sel_hi:[1, 0]
	v_pk_mul_f32 v[38:39], v[110:111], v[66:67]
	v_pk_mul_f32 v[36:37], v[108:109], v[64:65]
	v_pk_fma_f32 v[38:39], v[14:15], v[38:39], v[10:11]
	v_pk_fma_f32 v[36:37], v[12:13], v[36:37], v[8:9]
	v_pk_mul_f32 v[62:63], v[62:63], v[72:73] op_sel_hi:[1, 0]
	v_cvt_pk_bf16_f32 v36, v36, v37
	v_cvt_pk_bf16_f32 v37, v38, v39
	global_store_dwordx2 v[70:71], v[36:37], off
	v_pk_mul_f32 v[60:61], v[60:61], v[72:73] op_sel_hi:[1, 0]
	v_pk_mul_f32 v[58:59], v[58:59], v[72:73] op_sel_hi:[1, 0]
	v_pk_mul_f32 v[56:57], v[56:57], v[72:73] op_sel_hi:[1, 0]
	v_pk_mul_f32 v[54:55], v[54:55], v[72:73] op_sel_hi:[1, 0]
	v_pk_mul_f32 v[52:53], v[52:53], v[72:73] op_sel_hi:[1, 0]
	v_cmp_gt_f32_e32 vcc, s63, v68
	s_lshl_b64 s[36:37], s[36:37], 11
	v_pk_mul_f32 v[36:37], v[112:113], v[60:61]
	v_pk_mul_f32 v[38:39], v[114:115], v[62:63]
	v_pk_fma_f32 v[36:37], v[20:21], v[36:37], v[16:17]
	v_pk_fma_f32 v[38:39], v[22:23], v[38:39], v[18:19]
	v_cvt_pk_bf16_f32 v36, v36, v37
	v_cvt_pk_bf16_f32 v37, v38, v39
	global_store_dwordx2 v200, v[36:37], s[38:39]
	v_pk_mul_f32 v[36:37], v[116:117], v[56:57]
	v_pk_mul_f32 v[38:39], v[118:119], v[58:59]
	v_pk_fma_f32 v[36:37], v[28:29], v[36:37], v[24:25]
	v_pk_fma_f32 v[38:39], v[30:31], v[38:39], v[26:27]
	v_cvt_pk_bf16_f32 v36, v36, v37
	v_cvt_pk_bf16_f32 v37, v38, v39
	global_store_dwordx2 v201, v[36:37], s[38:39]
	v_pk_mul_f32 v[36:37], v[120:121], v[52:53]
	v_pk_mul_f32 v[38:39], v[122:123], v[54:55]
	v_pk_fma_f32 v[36:37], v[4:5], v[36:37], v[0:1]
	v_pk_fma_f32 v[38:39], v[6:7], v[38:39], v[2:3]
	v_cvt_pk_bf16_f32 v36, v36, v37
	v_cvt_pk_bf16_f32 v37, v38, v39
	global_store_dwordx2 v210, v[36:37], s[38:39]
	v_mul_f32_e32 v52, 0x4b800000, v68
	v_cndmask_b32_e32 v52, v68, v52, vcc
	v_rsq_f32_e32 v54, v52
	v_lshl_add_u64 v[52:53], v[140:141], 0, s[36:37]
	s_add_u32 s36, s10, s36
	s_addc_u32 s37, s11, s37
	v_mul_f32_e32 v55, 0x45800000, v54
	v_cndmask_b32_e32 v54, v54, v55, vcc
	v_pk_mul_f32 v[50:51], v[50:51], v[54:55] op_sel_hi:[1, 0]
	v_pk_mul_f32 v[48:49], v[48:49], v[54:55] op_sel_hi:[1, 0]
	s_and_b64 vcc, exec, s[8:9]
	s_mov_b64 s[8:9], -1
	v_pk_mul_f32 v[36:37], v[108:109], v[48:49]
	v_pk_mul_f32 v[38:39], v[110:111], v[50:51]
	v_pk_fma_f32 v[8:9], v[12:13], v[36:37], v[8:9]
	v_pk_fma_f32 v[10:11], v[14:15], v[38:39], v[10:11]
	v_cvt_pk_bf16_f32 v8, v8, v9
	v_cvt_pk_bf16_f32 v9, v10, v11
	global_store_dwordx2 v[52:53], v[8:9], off
	v_pk_mul_f32 v[12:13], v[46:47], v[54:55] op_sel_hi:[1, 0]
	v_pk_mul_f32 v[14:15], v[44:45], v[54:55] op_sel_hi:[1, 0]
	v_pk_mul_f32 v[10:11], v[114:115], v[12:13]
	v_pk_mul_f32 v[8:9], v[112:113], v[14:15]
	v_pk_fma_f32 v[10:11], v[22:23], v[10:11], v[18:19]
	v_pk_fma_f32 v[8:9], v[20:21], v[8:9], v[16:17]
	v_pk_mul_f32 v[12:13], v[42:43], v[54:55] op_sel_hi:[1, 0]
	v_cvt_pk_bf16_f32 v8, v8, v9
	v_cvt_pk_bf16_f32 v9, v10, v11
	global_store_dwordx2 v200, v[8:9], s[36:37]
	v_pk_mul_f32 v[14:15], v[40:41], v[54:55] op_sel_hi:[1, 0]
	v_pk_mul_f32 v[10:11], v[118:119], v[12:13]
	v_pk_mul_f32 v[8:9], v[116:117], v[14:15]
	v_pk_fma_f32 v[10:11], v[30:31], v[10:11], v[26:27]
	v_pk_fma_f32 v[8:9], v[28:29], v[8:9], v[24:25]
	v_pk_mul_f32 v[12:13], v[34:35], v[54:55] op_sel_hi:[1, 0]
	v_cvt_pk_bf16_f32 v8, v8, v9
	v_cvt_pk_bf16_f32 v9, v10, v11
	global_store_dwordx2 v201, v[8:9], s[36:37]
	v_pk_mul_f32 v[14:15], v[32:33], v[54:55] op_sel_hi:[1, 0]
	v_pk_mul_f32 v[10:11], v[122:123], v[12:13]
	v_pk_mul_f32 v[8:9], v[120:121], v[14:15]
	v_pk_fma_f32 v[2:3], v[6:7], v[10:11], v[2:3]
	v_pk_fma_f32 v[0:1], v[4:5], v[8:9], v[0:1]
	s_nop 0
	v_cvt_pk_bf16_f32 v0, v0, v1
	v_cvt_pk_bf16_f32 v1, v2, v3
	global_store_dwordx2 v210, v[0:1], s[36:37]
	s_cbranch_vccnz .LBB0_1469
	s_andn2_b64 vcc, exec, s[2:3]
	s_cbranch_vccnz .LBB0_1468
	s_barrier
	s_branch .LBB0_1468

.LBB0_1662:
	s_or_b64 exec, exec, s[36:37]
	s_mul_i32 s36, s48, 0x9000
	s_mul_hi_i32 s51, s49, 0x9000
	s_add_i32 s50, s36, 0x240000
	s_mul_hi_i32 s49, s47, 0x9000
	s_add_i32 s48, s36, 0x288000
	v_lshl_add_u64 v[4:5], v[134:135], 0, s[50:51]
	s_mul_hi_i32 s47, s46, 0x9000
	s_add_i32 s46, s36, 0x2d0000
	s_barrier
	global_load_dwordx4 v[0:3], v[132:133], off
	v_lshl_add_u64 v[8:9], v[134:135], 0, s[48:49]
	global_load_dwordx4 v[4:7], v[4:5], off
	s_mul_hi_i32 s45, s45, 0x9000
	s_add_i32 s44, s36, 0x318000
	global_load_dwordx4 v[8:11], v[8:9], off
	v_lshl_add_u64 v[12:13], v[134:135], 0, s[46:47]
	s_mul_hi_i32 s43, s79, 0x9000
	s_add_i32 s42, s36, 0x360000
	global_load_dwordx4 v[12:15], v[12:13], off
	v_lshl_add_u64 v[16:17], v[134:135], 0, s[44:45]
	s_mul_hi_i32 s41, s78, 0x9000
	s_add_i32 s40, s36, 0x3a8000
	global_load_dwordx4 v[16:19], v[16:17], off
	v_lshl_add_u64 v[20:21], v[134:135], 0, s[42:43]
	s_mul_hi_i32 s39, s77, 0x9000
	s_add_i32 s38, s36, 0x3f0000
	global_load_dwordx4 v[20:23], v[20:21], off
	v_lshl_add_u64 v[24:25], v[134:135], 0, s[40:41]
	s_mul_hi_i32 s37, s76, 0x9000
	s_add_i32 s36, s36, 0x438000
	global_load_dwordx4 v[24:27], v[24:25], off
	v_lshl_add_u64 v[28:29], v[134:135], 0, s[38:39]
	global_load_dwordx4 v[28:31], v[28:29], off
	v_lshl_add_u64 v[32:33], v[134:135], 0, s[36:37]
	global_load_dwordx4 v[32:35], v[32:33], off
	s_lshl_b32 s36, s74, 6
	s_ashr_i32 s37, s80, 3
	s_add_i32 s36, s75, s36
	s_and_b32 s37, s37, -8
	s_add_i32 s36, s36, s37
	s_ashr_i32 s37, s36, 31
	s_lshl_b64 s[38:39], s[36:37], 12
	v_lshl_add_u64 v[36:37], v[136:137], 0, s[38:39]
	s_or_b32 s42, s36, 1
	s_ashr_i32 s43, s42, 31
	s_lshl_b64 s[38:39], s[42:43], 12
	v_mov_b64_e32 v[88:89], s[30:31]
	s_or_b32 s40, s36, 2
	s_ashr_i32 s41, s40, 31
	s_lshl_b64 s[46:47], s[40:41], 12
	s_lshl_b64 s[44:45], s[36:37], 11
	s_waitcnt vmcnt(7)
	v_pk_add_f32 v[2:3], v[2:3], v[6:7]
	v_pk_add_f32 v[0:1], v[0:1], v[4:5]
	s_waitcnt vmcnt(6)
	v_pk_add_f32 v[2:3], v[2:3], v[10:11]
	v_pk_add_f32 v[0:1], v[0:1], v[8:9]
	v_lshl_add_u64 v[8:9], v[136:137], 0, s[38:39]
	s_or_b32 s38, s36, 3
	s_waitcnt vmcnt(5)
	v_pk_add_f32 v[2:3], v[2:3], v[14:15]
	v_pk_add_f32 v[0:1], v[0:1], v[12:13]
	s_ashr_i32 s39, s38, 31
	s_lshl_b64 s[48:49], s[38:39], 12
	s_waitcnt vmcnt(4)
	v_pk_add_f32 v[2:3], v[2:3], v[18:19]
	v_pk_add_f32 v[0:1], v[0:1], v[16:17]
	s_waitcnt vmcnt(3)
	v_pk_add_f32 v[2:3], v[2:3], v[22:23]
	v_pk_add_f32 v[0:1], v[0:1], v[20:21]
	s_waitcnt vmcnt(2)
	v_pk_add_f32 v[2:3], v[2:3], v[26:27]
	v_pk_add_f32 v[0:1], v[0:1], v[24:25]
	s_waitcnt vmcnt(1)
	v_pk_add_f32 v[2:3], v[2:3], v[30:31]
	v_pk_add_f32 v[0:1], v[0:1], v[28:29]
	s_waitcnt vmcnt(0)
	v_pk_add_f32 v[2:3], v[2:3], v[34:35]
	v_pk_add_f32 v[0:1], v[0:1], v[32:33]
	v_pk_add_f32 v[4:5], v[2:3], 1.0 op_sel_hi:[1,0]
	v_pk_add_f32 v[6:7], v[0:1], 1.0 op_sel_hi:[1,0]
	v_cndmask_b32_e64 v3, v5, v3, s[6:7]
	v_cndmask_b32_e64 v2, v4, v2, s[6:7]
	v_cndmask_b32_e64 v1, v7, v1, s[6:7]
	v_cndmask_b32_e64 v0, v6, v0, s[6:7]
	ds_write_b128 v183, v[0:3]
	s_waitcnt lgkmcnt(0)
	s_barrier
	global_load_dwordx4 v[108:111], v[138:139], off
	global_load_dwordx4 v[112:115], v[142:143], off
	global_load_dwordx4 v[116:119], v[144:145], off
	global_load_dwordx4 v[120:123], v[146:147], off
	global_load_dwordx4 v[16:19], v[36:37], off
	global_load_dwordx4 v[4:7], v[36:37], off offset:1024
	global_load_dwordx4 v[80:83], v[36:37], off offset:3072
	global_load_dwordx4 v[0:3], v[36:37], off offset:2048
	global_load_dwordx4 v[76:79], v[8:9], off
	global_load_dwordx4 v[68:71], v[8:9], off offset:1024
	s_nop 0
	global_load_dwordx4 v[36:39], v[8:9], off offset:3072
	global_load_dwordx4 v[64:67], v[8:9], off offset:2048
	s_waitcnt vmcnt(3)
	v_pk_mul_f32 v[28:29], v[78:79], v[78:79]
	v_pk_mul_f32 v[8:9], v[18:19], v[18:19]
	v_pk_mul_f32 v[10:11], v[16:17], v[16:17]
	v_pk_mul_f32 v[12:13], v[6:7], v[6:7]
	v_pk_mul_f32 v[14:15], v[4:5], v[4:5]
	v_mul_f32_e32 v24, v1, v1
	v_mul_f32_e32 v26, v3, v3
	v_pk_mul_f32 v[30:31], v[76:77], v[76:77]
	s_waitcnt vmcnt(2)
	v_pk_mul_f32 v[32:33], v[70:71], v[70:71]
	v_pk_mul_f32 v[34:35], v[68:69], v[68:69]
	v_mul_f32_e32 v47, v82, v82
	v_mul_f32_e32 v48, v83, v83
	v_pk_mov_b32 v[44:45], v[10:11], v[8:9] op_sel:[1, 0]
	v_mov_b32_e32 v11, v9
	v_pk_mov_b32 v[8:9], v[14:15], v[12:13] op_sel:[1, 0]
	v_mov_b32_e32 v15, v13
	v_pk_fma_f32 v[12:13], v[0:1], v[0:1], v[24:25] op_sel_hi:[1, 1, 0]
	v_pk_fma_f32 v[24:25], v[2:3], v[2:3], v[26:27] op_sel_hi:[1, 1, 0]
	v_pk_mov_b32 v[26:27], v[30:31], v[28:29] op_sel:[1, 0]
	v_mov_b32_e32 v31, v29
	v_pk_mov_b32 v[28:29], v[34:35], v[32:33] op_sel:[1, 0]
	v_mov_b32_e32 v35, v33
	v_mul_f32_e32 v43, v80, v80
	s_waitcnt vmcnt(0)
	v_mul_f32_e32 v40, v65, v65
	v_mul_f32_e32 v42, v67, v67
	v_pk_add_f32 v[10:11], v[44:45], v[10:11]
	v_pk_add_f32 v[8:9], v[8:9], v[14:15]
	v_mov_b32_e32 v13, v47
	v_mov_b32_e32 v25, v48
	v_pk_add_f32 v[14:15], v[26:27], v[30:31]
	v_pk_add_f32 v[26:27], v[28:29], v[34:35]
	v_mul_f32_e32 v46, v81, v81
	v_mul_f32_e32 v49, v36, v36
	v_mul_f32_e32 v50, v37, v37
	v_mul_f32_e32 v51, v38, v38
	v_mul_f32_e32 v52, v39, v39
	v_pk_fma_f32 v[32:33], v[64:65], v[64:65], v[40:41] op_sel_hi:[1, 1, 0]
	v_pk_fma_f32 v[40:41], v[66:67], v[66:67], v[42:43] op_sel_hi:[1, 1, 0]
	v_pk_add_f32 v[10:11], v[10:11], v[10:11] op_sel:[0, 1] op_sel_hi:[1, 0]
	v_pk_add_f32 v[8:9], v[8:9], v[8:9] op_sel:[0, 1] op_sel_hi:[1, 0]
	v_pk_add_f32 v[12:13], v[12:13], v[24:25]
	v_pk_add_f32 v[14:15], v[14:15], v[14:15] op_sel:[0, 1] op_sel_hi:[1, 0]
	v_pk_add_f32 v[24:25], v[26:27], v[26:27] op_sel:[0, 1] op_sel_hi:[1, 0]
	v_mov_b32_e32 v33, v51
	v_mov_b32_e32 v41, v52
	v_mov_b32_e32 v11, v43
	v_mov_b32_e32 v9, v46
	v_mov_b32_e32 v15, v49
	v_mov_b32_e32 v25, v50
	v_pk_add_f32 v[26:27], v[32:33], v[40:41]
	v_pk_add_f32 v[8:9], v[10:11], v[8:9]
	v_pk_add_f32 v[10:11], v[14:15], v[24:25]
	v_pk_add_f32 v[8:9], v[8:9], v[12:13]
	v_pk_add_f32 v[10:11], v[10:11], v[26:27]
	v_mov_b32_e32 v13, v8
	v_mov_b32_e32 v12, v10
	v_mov_b32_e32 v8, v11
	v_pk_add_f32 v[8:9], v[12:13], v[8:9]
	v_lshl_add_u64 v[12:13], v[136:137], 0, s[46:47]
	v_lshl_add_u64 v[14:15], v[136:137], 0, s[48:49]
	global_load_dwordx4 v[72:75], v[12:13], off
	global_load_dwordx4 v[60:63], v[12:13], off offset:1024
	global_load_dwordx4 v[56:59], v[12:13], off offset:2048
	global_load_dwordx4 v[52:55], v[12:13], off offset:3072
	global_load_dwordx4 v[48:51], v[14:15], off
	global_load_dwordx4 v[44:47], v[14:15], off offset:1024
	s_waitcnt lgkmcnt(0)
	s_nop 1
	v_add_f32_dpp v8, v8, v8 quad_perm:[1,0,3,2] row_mask:0xf bank_mask:0xf
	v_add_f32_dpp v9, v9, v9 quad_perm:[1,0,3,2] row_mask:0xf bank_mask:0xf
	global_load_dwordx4 v[40:43], v[14:15], off offset:2048
	global_load_dwordx4 v[32:35], v[14:15], off offset:3072
	v_lshl_add_u64 v[24:25], v[140:141], 0, s[44:45]
	s_add_u32 s44, s16, s44
	s_addc_u32 s45, s17, s45
	s_waitcnt lgkmcnt(0)
	s_nop 1
	v_add_f32_dpp v8, v8, v8 quad_perm:[2,3,0,1] row_mask:0xf bank_mask:0xf
	v_add_f32_dpp v9, v9, v9 quad_perm:[2,3,0,1] row_mask:0xf bank_mask:0xf
	s_lshl_b64 s[42:43], s[42:43], 11
	s_waitcnt lgkmcnt(0)
	s_nop 1
	v_add_f32_dpp v8, v8, v8 row_half_mirror row_mask:0xf bank_mask:0xf
	v_add_f32_dpp v9, v9, v9 row_half_mirror row_mask:0xf bank_mask:0xf
	s_waitcnt lgkmcnt(0)
	s_nop 1
	v_add_f32_dpp v8, v8, v8 row_mirror row_mask:0xf bank_mask:0xf
	v_add_f32_dpp v9, v9, v9 row_mirror row_mask:0xf bank_mask:0xf
	ds_bpermute_b32 v11, v188, v9
	ds_bpermute_b32 v10, v188, v8
	s_waitcnt lgkmcnt(0)
	v_pk_add_f32 v[8:9], v[8:9], v[10:11]
	s_waitcnt lgkmcnt(0)
	v_mov_b32_e32 v10, v8
	v_mov_b32_e32 v11, v9
	s_nop 1
	v_permlane32_swap_b32_e32 v10, v8
	v_permlane32_swap_b32_e32 v11, v9
	v_pk_add_f32 v[8:9], v[8:9], v[10:11]
	s_nop 0
	v_pk_fma_f32 v[90:91], v[8:9], s[28:29], v[88:89] op_sel_hi:[1, 0, 0]
	s_waitcnt vmcnt(4)
	v_mul_f32_e32 v99, v53, v53
	v_mul_f32_e32 v8, 0x4b800000, v91
	v_cmp_gt_f32_e32 vcc, s71, v91
	s_waitcnt vmcnt(2)
	v_pk_mul_f32 v[94:95], v[44:45], v[44:45]
	v_mul_f32_e32 v102, v54, v54
	v_cndmask_b32_e32 v8, v91, v8, vcc
	v_rsq_f32_e32 v26, v8
	ds_read_b128 v[8:11], v190
	ds_read_b128 v[12:15], v191
	s_waitcnt vmcnt(1)
	v_mul_f32_e32 v96, v41, v41
	v_mul_f32_e32 v98, v43, v43
	v_mul_f32_e32 v27, 0x45800000, v26
	v_cndmask_b32_e32 v92, v26, v27, vcc
	v_pk_mul_f32 v[18:19], v[18:19], v[92:93] op_sel_hi:[1, 0]
	v_pk_mul_f32 v[16:17], v[16:17], v[92:93] op_sel_hi:[1, 0]
	v_pk_mul_f32 v[18:19], v[110:111], v[18:19]
	v_pk_mul_f32 v[16:17], v[108:109], v[16:17]
	s_waitcnt lgkmcnt(0)
	v_pk_fma_f32 v[18:19], v[14:15], v[18:19], v[10:11]
	v_pk_fma_f32 v[16:17], v[12:13], v[16:17], v[8:9]
	v_pk_mul_f32 v[6:7], v[6:7], v[92:93] op_sel_hi:[1, 0]
	v_cvt_pk_bf16_f32 v16, v16, v17
	v_cvt_pk_bf16_f32 v17, v18, v19
	global_store_dwordx2 v[24:25], v[16:17], off
	ds_read_b128 v[16:19], v192
	ds_read_b128 v[20:23], v193
	v_pk_mul_f32 v[4:5], v[4:5], v[92:93] op_sel_hi:[1, 0]
	v_pk_mul_f32 v[2:3], v[2:3], v[92:93] op_sel_hi:[1, 0]
	v_pk_mul_f32 v[0:1], v[0:1], v[92:93] op_sel_hi:[1, 0]
	v_pk_mul_f32 v[82:83], v[82:83], v[92:93] op_sel_hi:[1, 0]
	v_pk_mul_f32 v[80:81], v[80:81], v[92:93] op_sel_hi:[1, 0]
	v_cmp_gt_f32_e32 vcc, s71, v90
	v_pk_mul_f32 v[92:93], v[46:47], v[46:47]
	v_mul_f32_e32 v103, v55, v55
	s_waitcnt vmcnt(1)
	v_mul_f32_e32 v104, v32, v32
	v_mul_f32_e32 v105, v33, v33
	v_mul_f32_e32 v106, v34, v34
	v_mul_f32_e32 v107, v35, v35
	v_pk_mul_f32 v[4:5], v[112:113], v[4:5]
	v_pk_mul_f32 v[6:7], v[114:115], v[6:7]
	s_waitcnt lgkmcnt(0)
	v_pk_fma_f32 v[4:5], v[20:21], v[4:5], v[16:17]
	v_pk_fma_f32 v[6:7], v[22:23], v[6:7], v[18:19]
	v_cvt_pk_bf16_f32 v4, v4, v5
	v_cvt_pk_bf16_f32 v5, v6, v7
	global_store_dwordx2 v200, v[4:5], s[44:45]
	ds_read_b128 v[24:27], v194
	ds_read_b128 v[28:31], v195
	v_pk_mul_f32 v[0:1], v[116:117], v[0:1]
	v_pk_mul_f32 v[2:3], v[118:119], v[2:3]
	s_waitcnt lgkmcnt(0)
	v_pk_fma_f32 v[0:1], v[28:29], v[0:1], v[24:25]
	v_pk_fma_f32 v[2:3], v[30:31], v[2:3], v[26:27]
	v_cvt_pk_bf16_f32 v0, v0, v1
	v_cvt_pk_bf16_f32 v1, v2, v3
	global_store_dwordx2 v201, v[0:1], s[44:45]
	ds_read_b128 v[0:3], v196
	ds_read_b128 v[4:7], v197
	v_pk_mul_f32 v[80:81], v[80:81], v[120:121]
	v_pk_mul_f32 v[82:83], v[82:83], v[122:123]
	s_waitcnt lgkmcnt(0)
	v_pk_fma_f32 v[80:81], v[80:81], v[4:5], v[0:1]
	v_pk_fma_f32 v[82:83], v[82:83], v[6:7], v[2:3]
	v_cvt_pk_bf16_f32 v80, v80, v81
	v_cvt_pk_bf16_f32 v81, v82, v83
	global_store_dwordx2 v210, v[80:81], s[44:45]
	v_mul_f32_e32 v84, 0x4b800000, v90
	v_cndmask_b32_e32 v84, v90, v84, vcc
	v_rsq_f32_e32 v86, v84
	v_lshl_add_u64 v[84:85], v[140:141], 0, s[42:43]
	s_add_u32 s42, s16, s42
	s_addc_u32 s43, s17, s43
	v_mul_f32_e32 v87, 0x45800000, v86
	v_cndmask_b32_e32 v86, v86, v87, vcc
	v_pk_mul_f32 v[78:79], v[78:79], v[86:87] op_sel_hi:[1, 0]
	v_pk_mul_f32 v[76:77], v[76:77], v[86:87] op_sel_hi:[1, 0]
	v_pk_mul_f32 v[70:71], v[70:71], v[86:87] op_sel_hi:[1, 0]
	v_pk_mul_f32 v[68:69], v[68:69], v[86:87] op_sel_hi:[1, 0]
	v_pk_mul_f32 v[66:67], v[66:67], v[86:87] op_sel_hi:[1, 0]
	v_pk_mul_f32 v[64:65], v[64:65], v[86:87] op_sel_hi:[1, 0]
	v_mul_f32_e32 v87, v52, v52
	v_pk_mul_f32 v[38:39], v[38:39], v[86:87] op_sel_hi:[1, 0]
	v_pk_mul_f32 v[36:37], v[36:37], v[86:87] op_sel_hi:[1, 0]
	v_pk_mul_f32 v[90:91], v[48:49], v[48:49]
	s_lshl_b64 s[40:41], s[40:41], 11
	v_pk_mul_f32 v[76:77], v[108:109], v[76:77]
	v_pk_mul_f32 v[78:79], v[110:111], v[78:79]
	v_pk_fma_f32 v[76:77], v[12:13], v[76:77], v[8:9]
	v_pk_fma_f32 v[78:79], v[14:15], v[78:79], v[10:11]
	v_cvt_pk_bf16_f32 v76, v76, v77
	v_cvt_pk_bf16_f32 v77, v78, v79
	global_store_dwordx2 v[84:85], v[76:77], off
	v_mul_f32_e32 v80, v57, v57
	v_mul_f32_e32 v82, v59, v59
	v_pk_mul_f32 v[84:85], v[50:51], v[50:51]
	v_pk_mul_f32 v[68:69], v[112:113], v[68:69]
	v_pk_mul_f32 v[70:71], v[114:115], v[70:71]
	v_pk_fma_f32 v[68:69], v[20:21], v[68:69], v[16:17]
	v_pk_fma_f32 v[70:71], v[22:23], v[70:71], v[18:19]
	v_cvt_pk_bf16_f32 v68, v68, v69
	v_cvt_pk_bf16_f32 v69, v70, v71
	global_store_dwordx2 v200, v[68:69], s[42:43]
	v_pk_mul_f32 v[76:77], v[62:63], v[62:63]
	v_pk_mul_f32 v[78:79], v[60:61], v[60:61]
	v_pk_mul_f32 v[64:65], v[116:117], v[64:65]
	v_pk_mul_f32 v[66:67], v[118:119], v[66:67]
	v_pk_fma_f32 v[64:65], v[28:29], v[64:65], v[24:25]
	v_pk_fma_f32 v[66:67], v[30:31], v[66:67], v[26:27]
	v_cvt_pk_bf16_f32 v64, v64, v65
	v_cvt_pk_bf16_f32 v65, v66, v67
	global_store_dwordx2 v201, v[64:65], s[42:43]
	v_pk_mul_f32 v[68:69], v[74:75], v[74:75]
	v_pk_mul_f32 v[70:71], v[72:73], v[72:73]
	v_pk_mul_f32 v[36:37], v[120:121], v[36:37]
	v_pk_mul_f32 v[38:39], v[122:123], v[38:39]
	v_pk_fma_f32 v[36:37], v[4:5], v[36:37], v[0:1]
	v_pk_fma_f32 v[38:39], v[6:7], v[38:39], v[2:3]
	v_cvt_pk_bf16_f32 v36, v36, v37
	v_cvt_pk_bf16_f32 v37, v38, v39
	global_store_dwordx2 v210, v[36:37], s[42:43]
	v_pk_mov_b32 v[100:101], v[70:71], v[68:69] op_sel:[1, 0]
	v_mov_b32_e32 v71, v69
	v_pk_mov_b32 v[68:69], v[78:79], v[76:77] op_sel:[1, 0]
	v_mov_b32_e32 v79, v77
	v_pk_fma_f32 v[76:77], v[56:57], v[56:57], v[80:81] op_sel_hi:[1, 1, 0]
	v_pk_fma_f32 v[80:81], v[58:59], v[58:59], v[82:83] op_sel_hi:[1, 1, 0]
	v_pk_mov_b32 v[82:83], v[90:91], v[84:85] op_sel:[1, 0]
	v_mov_b32_e32 v91, v85
	v_pk_mov_b32 v[84:85], v[94:95], v[92:93] op_sel:[1, 0]
	v_mov_b32_e32 v95, v93
	v_pk_add_f32 v[70:71], v[100:101], v[70:71]
	v_pk_add_f32 v[64:65], v[68:69], v[78:79]
	v_pk_add_f32 v[66:67], v[82:83], v[90:91]
	v_pk_add_f32 v[68:69], v[84:85], v[94:95]
	v_pk_fma_f32 v[92:93], v[40:41], v[40:41], v[96:97] op_sel_hi:[1, 1, 0]
	v_pk_fma_f32 v[96:97], v[42:43], v[42:43], v[98:99] op_sel_hi:[1, 1, 0]
	v_pk_add_f32 v[70:71], v[70:71], v[70:71] op_sel:[0, 1] op_sel_hi:[1, 0]
	v_pk_add_f32 v[64:65], v[64:65], v[64:65] op_sel:[0, 1] op_sel_hi:[1, 0]
	v_pk_add_f32 v[66:67], v[66:67], v[66:67] op_sel:[0, 1] op_sel_hi:[1, 0]
	v_pk_add_f32 v[68:69], v[68:69], v[68:69] op_sel:[0, 1] op_sel_hi:[1, 0]
	v_mov_b32_e32 v77, v102
	v_mov_b32_e32 v81, v103
	v_mov_b32_e32 v93, v106
	v_mov_b32_e32 v97, v107
	v_mov_b32_e32 v71, v87
	v_mov_b32_e32 v65, v99
	v_mov_b32_e32 v67, v104
	v_mov_b32_e32 v69, v105
	v_pk_add_f32 v[76:77], v[76:77], v[80:81]
	v_pk_add_f32 v[78:79], v[92:93], v[96:97]
	v_pk_add_f32 v[64:65], v[70:71], v[64:65]
	v_pk_add_f32 v[66:67], v[66:67], v[68:69]
	v_pk_add_f32 v[64:65], v[64:65], v[76:77]
	v_pk_add_f32 v[66:67], v[66:67], v[78:79]
	v_mov_b32_e32 v69, v64
	v_mov_b32_e32 v68, v66
	v_mov_b32_e32 v64, v67
	v_pk_add_f32 v[64:65], v[68:69], v[64:65]
	s_waitcnt lgkmcnt(0)
	s_nop 1
	v_add_f32_dpp v64, v64, v64 quad_perm:[1,0,3,2] row_mask:0xf bank_mask:0xf
	v_add_f32_dpp v65, v65, v65 quad_perm:[1,0,3,2] row_mask:0xf bank_mask:0xf
	s_waitcnt lgkmcnt(0)
	s_nop 1
	v_add_f32_dpp v64, v64, v64 quad_perm:[2,3,0,1] row_mask:0xf bank_mask:0xf
	v_add_f32_dpp v65, v65, v65 quad_perm:[2,3,0,1] row_mask:0xf bank_mask:0xf
	s_waitcnt lgkmcnt(0)
	s_nop 1
	v_add_f32_dpp v64, v64, v64 row_half_mirror row_mask:0xf bank_mask:0xf
	v_add_f32_dpp v65, v65, v65 row_half_mirror row_mask:0xf bank_mask:0xf
	s_waitcnt lgkmcnt(0)
	s_nop 1
	v_add_f32_dpp v64, v64, v64 row_mirror row_mask:0xf bank_mask:0xf
	v_add_f32_dpp v65, v65, v65 row_mirror row_mask:0xf bank_mask:0xf
	ds_bpermute_b32 v67, v188, v65
	ds_bpermute_b32 v66, v188, v64
	s_waitcnt lgkmcnt(0)
	v_pk_add_f32 v[64:65], v[64:65], v[66:67]
	s_waitcnt lgkmcnt(0)
	v_mov_b32_e32 v66, v64
	v_mov_b32_e32 v67, v65
	s_nop 1
	v_permlane32_swap_b32_e32 v66, v64
	v_permlane32_swap_b32_e32 v67, v65
	v_pk_add_f32 v[64:65], v[64:65], v[66:67]
	s_nop 0
	v_pk_fma_f32 v[64:65], v[64:65], s[28:29], v[88:89] op_sel_hi:[1, 0, 0]
	s_nop 0
	v_mul_f32_e32 v66, 0x4b800000, v65
	v_cmp_gt_f32_e32 vcc, s71, v65
	s_nop 1
	v_cndmask_b32_e32 v65, v65, v66, vcc
	v_rsq_f32_e32 v65, v65
	v_lshl_add_u64 v[66:67], v[140:141], 0, s[40:41]
	s_add_u32 s40, s16, s40
	s_addc_u32 s41, s17, s41
	v_mul_f32_e32 v68, 0x45800000, v65
	v_cndmask_b32_e32 v68, v65, v68, vcc
	v_pk_mul_f32 v[70:71], v[74:75], v[68:69] op_sel_hi:[1, 0]
	v_pk_mul_f32 v[72:73], v[72:73], v[68:69] op_sel_hi:[1, 0]
	v_pk_mul_f32 v[38:39], v[110:111], v[70:71]
	v_pk_mul_f32 v[36:37], v[108:109], v[72:73]
	v_pk_fma_f32 v[38:39], v[14:15], v[38:39], v[10:11]
	v_pk_fma_f32 v[36:37], v[12:13], v[36:37], v[8:9]
	v_pk_mul_f32 v[62:63], v[62:63], v[68:69] op_sel_hi:[1, 0]
	v_cvt_pk_bf16_f32 v36, v36, v37
	v_cvt_pk_bf16_f32 v37, v38, v39
	global_store_dwordx2 v[66:67], v[36:37], off
	v_pk_mul_f32 v[60:61], v[60:61], v[68:69] op_sel_hi:[1, 0]
	v_pk_mul_f32 v[58:59], v[58:59], v[68:69] op_sel_hi:[1, 0]
	v_pk_mul_f32 v[56:57], v[56:57], v[68:69] op_sel_hi:[1, 0]
	v_pk_mul_f32 v[54:55], v[54:55], v[68:69] op_sel_hi:[1, 0]
	v_pk_mul_f32 v[52:53], v[52:53], v[68:69] op_sel_hi:[1, 0]
	v_cmp_gt_f32_e32 vcc, s71, v64
	s_lshl_b64 s[38:39], s[38:39], 11
	v_pk_mul_f32 v[36:37], v[112:113], v[60:61]
	v_pk_mul_f32 v[38:39], v[114:115], v[62:63]
	v_pk_fma_f32 v[36:37], v[20:21], v[36:37], v[16:17]
	v_pk_fma_f32 v[38:39], v[22:23], v[38:39], v[18:19]
	v_cvt_pk_bf16_f32 v36, v36, v37
	v_cvt_pk_bf16_f32 v37, v38, v39
	global_store_dwordx2 v200, v[36:37], s[40:41]
	v_pk_mul_f32 v[36:37], v[116:117], v[56:57]
	v_pk_mul_f32 v[38:39], v[118:119], v[58:59]
	v_pk_fma_f32 v[36:37], v[28:29], v[36:37], v[24:25]
	v_pk_fma_f32 v[38:39], v[30:31], v[38:39], v[26:27]
	v_cvt_pk_bf16_f32 v36, v36, v37
	v_cvt_pk_bf16_f32 v37, v38, v39
	global_store_dwordx2 v201, v[36:37], s[40:41]
	v_pk_mul_f32 v[36:37], v[120:121], v[52:53]
	v_pk_mul_f32 v[38:39], v[122:123], v[54:55]
	v_pk_fma_f32 v[36:37], v[4:5], v[36:37], v[0:1]
	v_pk_fma_f32 v[38:39], v[6:7], v[38:39], v[2:3]
	v_cvt_pk_bf16_f32 v36, v36, v37
	v_cvt_pk_bf16_f32 v37, v38, v39
	global_store_dwordx2 v210, v[36:37], s[40:41]
	v_mul_f32_e32 v52, 0x4b800000, v64
	v_cndmask_b32_e32 v52, v64, v52, vcc
	v_rsq_f32_e32 v54, v52
	v_lshl_add_u64 v[52:53], v[140:141], 0, s[38:39]
	s_add_u32 s38, s16, s38
	s_addc_u32 s39, s17, s39
	v_mul_f32_e32 v55, 0x45800000, v54
	v_cndmask_b32_e32 v54, v54, v55, vcc
	v_pk_mul_f32 v[50:51], v[50:51], v[54:55] op_sel_hi:[1, 0]
	v_pk_mul_f32 v[48:49], v[48:49], v[54:55] op_sel_hi:[1, 0]
	v_pk_mul_f32 v[46:47], v[46:47], v[54:55] op_sel_hi:[1, 0]
	v_pk_mul_f32 v[44:45], v[44:45], v[54:55] op_sel_hi:[1, 0]
	v_pk_mul_f32 v[42:43], v[42:43], v[54:55] op_sel_hi:[1, 0]
	v_pk_mul_f32 v[40:41], v[40:41], v[54:55] op_sel_hi:[1, 0]
	v_pk_mul_f32 v[34:35], v[34:35], v[54:55] op_sel_hi:[1, 0]
	v_pk_mul_f32 v[32:33], v[32:33], v[54:55] op_sel_hi:[1, 0]
	s_or_b32 s42, s36, 4
	s_ashr_i32 s43, s42, 31
	s_lshl_b64 s[40:41], s[42:43], 12
	s_lshl_b64 s[42:43], s[42:43], 11
	v_lshl_add_u64 v[104:105], v[140:141], 0, s[42:43]
	v_pk_mul_f32 v[36:37], v[108:109], v[48:49]
	v_pk_mul_f32 v[38:39], v[110:111], v[50:51]
	v_pk_fma_f32 v[36:37], v[12:13], v[36:37], v[8:9]
	v_pk_fma_f32 v[38:39], v[14:15], v[38:39], v[10:11]
	v_cvt_pk_bf16_f32 v36, v36, v37
	v_cvt_pk_bf16_f32 v37, v38, v39
	global_store_dwordx2 v[52:53], v[36:37], off
	v_pk_mul_f32 v[36:37], v[112:113], v[44:45]
	v_pk_mul_f32 v[38:39], v[114:115], v[46:47]
	v_pk_fma_f32 v[36:37], v[20:21], v[36:37], v[16:17]
	v_pk_fma_f32 v[38:39], v[22:23], v[38:39], v[18:19]
	v_cvt_pk_bf16_f32 v36, v36, v37
	v_cvt_pk_bf16_f32 v37, v38, v39
	global_store_dwordx2 v200, v[36:37], s[38:39]
	v_pk_mul_f32 v[36:37], v[116:117], v[40:41]
	v_pk_mul_f32 v[38:39], v[118:119], v[42:43]
	v_pk_fma_f32 v[36:37], v[28:29], v[36:37], v[24:25]
	v_pk_fma_f32 v[38:39], v[30:31], v[38:39], v[26:27]
	v_cvt_pk_bf16_f32 v36, v36, v37
	v_cvt_pk_bf16_f32 v37, v38, v39
	global_store_dwordx2 v201, v[36:37], s[38:39]
	v_lshl_add_u64 v[40:41], v[136:137], 0, s[40:41]
	s_or_b32 s40, s36, 5
	s_ashr_i32 s41, s40, 31
	v_pk_mul_f32 v[32:33], v[120:121], v[32:33]
	v_pk_mul_f32 v[34:35], v[122:123], v[34:35]
	v_pk_fma_f32 v[32:33], v[4:5], v[32:33], v[0:1]
	v_pk_fma_f32 v[34:35], v[6:7], v[34:35], v[2:3]
	v_cvt_pk_bf16_f32 v32, v32, v33
	v_cvt_pk_bf16_f32 v33, v34, v35
	global_store_dwordx2 v210, v[32:33], s[38:39]
	global_load_dwordx4 v[90:93], v[40:41], off
	global_load_dwordx4 v[94:97], v[40:41], off offset:1024
	global_load_dwordx4 v[80:83], v[40:41], off offset:3072
	global_load_dwordx4 v[84:87], v[40:41], off offset:2048
	s_lshl_b64 s[38:39], s[40:41], 12
	v_lshl_add_u64 v[32:33], v[136:137], 0, s[38:39]
	global_load_dwordx4 v[76:79], v[32:33], off
	global_load_dwordx4 v[72:75], v[32:33], off offset:1024
	global_load_dwordx4 v[36:39], v[32:33], off offset:3072
	global_load_dwordx4 v[68:71], v[32:33], off offset:2048
	s_or_b32 s38, s36, 6
	s_or_b32 s36, s36, 7
	s_ashr_i32 s39, s38, 31
	s_ashr_i32 s37, s36, 31
	s_lshl_b64 s[44:45], s[38:39], 12
	s_lshl_b64 s[46:47], s[36:37], 12
	s_add_u32 s42, s16, s42
	s_addc_u32 s43, s17, s43
	s_lshl_b64 s[40:41], s[40:41], 11
	s_waitcnt vmcnt(7)
	v_pk_mul_f32 v[32:33], v[92:93], v[92:93]
	v_pk_mul_f32 v[34:35], v[90:91], v[90:91]
	s_waitcnt vmcnt(6)
	v_pk_mul_f32 v[40:41], v[96:97], v[96:97]
	v_pk_mul_f32 v[42:43], v[94:95], v[94:95]
	s_waitcnt vmcnt(4)
	v_mul_f32_e32 v44, v85, v85
	v_mul_f32_e32 v46, v87, v87
	s_waitcnt vmcnt(3)
	v_pk_mul_f32 v[48:49], v[78:79], v[78:79]
	v_pk_mul_f32 v[50:51], v[76:77], v[76:77]
	s_waitcnt vmcnt(2)
	v_pk_mul_f32 v[52:53], v[74:75], v[74:75]
	v_pk_mul_f32 v[54:55], v[72:73], v[72:73]
	v_mul_f32_e32 v63, v82, v82
	v_mul_f32_e32 v64, v83, v83
	v_pk_mov_b32 v[60:61], v[34:35], v[32:33] op_sel:[1, 0]
	v_mov_b32_e32 v35, v33
	v_pk_mov_b32 v[32:33], v[42:43], v[40:41] op_sel:[1, 0]
	v_mov_b32_e32 v43, v41
	v_pk_fma_f32 v[40:41], v[84:85], v[84:85], v[44:45] op_sel_hi:[1, 1, 0]
	v_pk_fma_f32 v[44:45], v[86:87], v[86:87], v[46:47] op_sel_hi:[1, 1, 0]
	v_pk_mov_b32 v[46:47], v[50:51], v[48:49] op_sel:[1, 0]
	v_mov_b32_e32 v51, v49
	v_pk_mov_b32 v[48:49], v[54:55], v[52:53] op_sel:[1, 0]
	v_mov_b32_e32 v55, v53
	v_mul_f32_e32 v59, v80, v80
	s_waitcnt vmcnt(0)
	v_mul_f32_e32 v56, v69, v69
	v_mul_f32_e32 v58, v71, v71
	v_pk_add_f32 v[34:35], v[60:61], v[34:35]
	v_pk_add_f32 v[32:33], v[32:33], v[42:43]
	v_mov_b32_e32 v41, v63
	v_mov_b32_e32 v45, v64
	v_pk_add_f32 v[42:43], v[46:47], v[50:51]
	v_pk_add_f32 v[46:47], v[48:49], v[54:55]
	v_mul_f32_e32 v62, v81, v81
	v_mul_f32_e32 v65, v36, v36
	v_mul_f32_e32 v66, v37, v37
	v_mul_f32_e32 v67, v38, v38
	v_mul_f32_e32 v102, v39, v39
	v_pk_fma_f32 v[52:53], v[68:69], v[68:69], v[56:57] op_sel_hi:[1, 1, 0]
	v_pk_fma_f32 v[56:57], v[70:71], v[70:71], v[58:59] op_sel_hi:[1, 1, 0]
	v_pk_add_f32 v[34:35], v[34:35], v[34:35] op_sel:[0, 1] op_sel_hi:[1, 0]
	v_pk_add_f32 v[32:33], v[32:33], v[32:33] op_sel:[0, 1] op_sel_hi:[1, 0]
	v_pk_add_f32 v[40:41], v[40:41], v[44:45]
	v_pk_add_f32 v[42:43], v[42:43], v[42:43] op_sel:[0, 1] op_sel_hi:[1, 0]
	v_pk_add_f32 v[44:45], v[46:47], v[46:47] op_sel:[0, 1] op_sel_hi:[1, 0]
	v_mov_b32_e32 v53, v67
	v_mov_b32_e32 v57, v102
	v_mov_b32_e32 v35, v59
	v_mov_b32_e32 v33, v62
	v_mov_b32_e32 v43, v65
	v_mov_b32_e32 v45, v66
	v_pk_add_f32 v[46:47], v[52:53], v[56:57]
	v_pk_add_f32 v[32:33], v[34:35], v[32:33]
	v_pk_add_f32 v[34:35], v[42:43], v[44:45]
	v_pk_add_f32 v[32:33], v[32:33], v[40:41]
	v_pk_add_f32 v[34:35], v[34:35], v[46:47]
	v_mov_b32_e32 v41, v32
	v_mov_b32_e32 v40, v34
	v_mov_b32_e32 v32, v35
	v_pk_add_f32 v[32:33], v[40:41], v[32:33]
	v_lshl_add_u64 v[40:41], v[136:137], 0, s[44:45]
	v_lshl_add_u64 v[102:103], v[136:137], 0, s[46:47]
	global_load_dwordx4 v[64:67], v[40:41], off
	global_load_dwordx4 v[60:63], v[40:41], off offset:1024
	global_load_dwordx4 v[56:59], v[40:41], off offset:2048
	global_load_dwordx4 v[52:55], v[40:41], off offset:3072
	s_waitcnt lgkmcnt(0)
	s_nop 1
	v_add_f32_dpp v32, v32, v32 quad_perm:[1,0,3,2] row_mask:0xf bank_mask:0xf
	v_add_f32_dpp v33, v33, v33 quad_perm:[1,0,3,2] row_mask:0xf bank_mask:0xf
	s_waitcnt lgkmcnt(0)
	s_nop 1
	v_add_f32_dpp v32, v32, v32 quad_perm:[2,3,0,1] row_mask:0xf bank_mask:0xf
	v_add_f32_dpp v33, v33, v33 quad_perm:[2,3,0,1] row_mask:0xf bank_mask:0xf
	s_waitcnt lgkmcnt(0)
	s_nop 1
	v_add_f32_dpp v32, v32, v32 row_half_mirror row_mask:0xf bank_mask:0xf
	v_add_f32_dpp v33, v33, v33 row_half_mirror row_mask:0xf bank_mask:0xf
	s_waitcnt lgkmcnt(0)
	s_nop 1
	v_add_f32_dpp v32, v32, v32 row_mirror row_mask:0xf bank_mask:0xf
	v_add_f32_dpp v33, v33, v33 row_mirror row_mask:0xf bank_mask:0xf
	ds_bpermute_b32 v35, v188, v33
	ds_bpermute_b32 v34, v188, v32
	s_waitcnt lgkmcnt(0)
	v_pk_add_f32 v[32:33], v[32:33], v[34:35]
	s_waitcnt lgkmcnt(0)
	v_mov_b32_e32 v34, v32
	v_mov_b32_e32 v35, v33
	s_nop 1
	v_permlane32_swap_b32_e32 v34, v32
	v_permlane32_swap_b32_e32 v35, v33
	v_pk_add_f32 v[32:33], v[32:33], v[34:35]
	s_nop 0
	v_pk_fma_f32 v[106:107], v[32:33], s[28:29], v[88:89] op_sel_hi:[1, 0, 0]
	s_nop 0
	v_mul_f32_e32 v32, 0x4b800000, v107
	v_cmp_gt_f32_e32 vcc, s71, v107
	s_nop 1
	v_cndmask_b32_e32 v32, v107, v32, vcc
	v_rsq_f32_e32 v107, v32
	global_load_dwordx4 v[48:51], v[102:103], off
	global_load_dwordx4 v[44:47], v[102:103], off offset:1024
	global_load_dwordx4 v[40:43], v[102:103], off offset:2048
	global_load_dwordx4 v[32:35], v[102:103], off offset:3072
	v_mul_f32_e32 v102, 0x45800000, v107
	v_cndmask_b32_e32 v102, v107, v102, vcc
	v_pk_mul_f32 v[92:93], v[92:93], v[102:103] op_sel_hi:[1, 0]
	v_pk_mul_f32 v[90:91], v[90:91], v[102:103] op_sel_hi:[1, 0]
	v_pk_mul_f32 v[92:93], v[110:111], v[92:93]
	v_pk_mul_f32 v[90:91], v[108:109], v[90:91]
	v_pk_fma_f32 v[92:93], v[14:15], v[92:93], v[10:11]
	v_pk_fma_f32 v[90:91], v[12:13], v[90:91], v[8:9]
	v_pk_mul_f32 v[96:97], v[96:97], v[102:103] op_sel_hi:[1, 0]
	v_cvt_pk_bf16_f32 v90, v90, v91
	v_cvt_pk_bf16_f32 v91, v92, v93
	global_store_dwordx2 v[104:105], v[90:91], off
	v_pk_mul_f32 v[94:95], v[94:95], v[102:103] op_sel_hi:[1, 0]
	v_pk_mul_f32 v[86:87], v[86:87], v[102:103] op_sel_hi:[1, 0]
	v_pk_mul_f32 v[84:85], v[84:85], v[102:103] op_sel_hi:[1, 0]
	v_pk_mul_f32 v[82:83], v[82:83], v[102:103] op_sel_hi:[1, 0]
	v_pk_mul_f32 v[80:81], v[80:81], v[102:103] op_sel_hi:[1, 0]
	v_cmp_gt_f32_e32 vcc, s71, v106
	s_waitcnt vmcnt(5)
	v_mul_f32_e32 v99, v53, v53
	v_mul_f32_e32 v102, v54, v54
	v_mul_f32_e32 v103, v55, v55
	s_waitcnt vmcnt(2)
	v_mul_f32_e32 v98, v43, v43
	s_waitcnt vmcnt(1)
	v_mul_f32_e32 v104, v32, v32
	v_mul_f32_e32 v105, v33, v33
	v_mul_f32_e32 v107, v35, v35
	v_pk_mul_f32 v[90:91], v[112:113], v[94:95]
	v_pk_mul_f32 v[92:93], v[114:115], v[96:97]
	v_pk_fma_f32 v[90:91], v[20:21], v[90:91], v[16:17]
	v_pk_fma_f32 v[92:93], v[22:23], v[92:93], v[18:19]
	v_cvt_pk_bf16_f32 v90, v90, v91
	v_cvt_pk_bf16_f32 v91, v92, v93
	global_store_dwordx2 v200, v[90:91], s[42:43]
	v_pk_mul_f32 v[94:95], v[44:45], v[44:45]
	v_mul_f32_e32 v96, v41, v41
	v_pk_mul_f32 v[84:85], v[116:117], v[84:85]
	v_pk_mul_f32 v[86:87], v[118:119], v[86:87]
	v_pk_fma_f32 v[84:85], v[28:29], v[84:85], v[24:25]
	v_pk_fma_f32 v[86:87], v[30:31], v[86:87], v[26:27]
	v_cvt_pk_bf16_f32 v84, v84, v85
	v_cvt_pk_bf16_f32 v85, v86, v87
	global_store_dwordx2 v201, v[84:85], s[42:43]
	v_pk_mul_f32 v[90:91], v[48:49], v[48:49]
	v_pk_mul_f32 v[92:93], v[46:47], v[46:47]
	v_pk_mul_f32 v[80:81], v[120:121], v[80:81]
	v_pk_mul_f32 v[82:83], v[122:123], v[82:83]
	v_pk_fma_f32 v[80:81], v[4:5], v[80:81], v[0:1]
	v_pk_fma_f32 v[82:83], v[6:7], v[82:83], v[2:3]
	v_cvt_pk_bf16_f32 v80, v80, v81
	v_cvt_pk_bf16_f32 v81, v82, v83
	global_store_dwordx2 v210, v[80:81], s[42:43]
	v_mul_f32_e32 v84, 0x4b800000, v106
	v_cndmask_b32_e32 v84, v106, v84, vcc
	v_rsq_f32_e32 v86, v84
	v_lshl_add_u64 v[84:85], v[140:141], 0, s[40:41]
	s_add_u32 s40, s16, s40
	s_addc_u32 s41, s17, s41
	v_mul_f32_e32 v87, 0x45800000, v86
	v_cndmask_b32_e32 v86, v86, v87, vcc
	v_pk_mul_f32 v[78:79], v[78:79], v[86:87] op_sel_hi:[1, 0]
	v_pk_mul_f32 v[76:77], v[76:77], v[86:87] op_sel_hi:[1, 0]
	v_pk_mul_f32 v[74:75], v[74:75], v[86:87] op_sel_hi:[1, 0]
	v_pk_mul_f32 v[72:73], v[72:73], v[86:87] op_sel_hi:[1, 0]
	v_pk_mul_f32 v[70:71], v[70:71], v[86:87] op_sel_hi:[1, 0]
	v_pk_mul_f32 v[68:69], v[68:69], v[86:87] op_sel_hi:[1, 0]
	v_mul_f32_e32 v87, v52, v52
	v_pk_mul_f32 v[38:39], v[38:39], v[86:87] op_sel_hi:[1, 0]
	v_pk_mul_f32 v[36:37], v[36:37], v[86:87] op_sel_hi:[1, 0]
	v_mul_f32_e32 v106, v34, v34
	s_lshl_b64 s[38:39], s[38:39], 11
	v_pk_mul_f32 v[76:77], v[108:109], v[76:77]
	v_pk_mul_f32 v[78:79], v[110:111], v[78:79]
	v_pk_fma_f32 v[76:77], v[12:13], v[76:77], v[8:9]
	v_pk_fma_f32 v[78:79], v[14:15], v[78:79], v[10:11]
	v_cvt_pk_bf16_f32 v76, v76, v77
	v_cvt_pk_bf16_f32 v77, v78, v79
	global_store_dwordx2 v[84:85], v[76:77], off
	v_mul_f32_e32 v80, v57, v57
	v_mul_f32_e32 v82, v59, v59
	v_pk_mul_f32 v[84:85], v[50:51], v[50:51]
	v_pk_mul_f32 v[72:73], v[112:113], v[72:73]
	v_pk_mul_f32 v[74:75], v[114:115], v[74:75]
	v_pk_fma_f32 v[72:73], v[20:21], v[72:73], v[16:17]
	v_pk_fma_f32 v[74:75], v[22:23], v[74:75], v[18:19]
	v_cvt_pk_bf16_f32 v72, v72, v73
	v_cvt_pk_bf16_f32 v73, v74, v75
	global_store_dwordx2 v200, v[72:73], s[40:41]
	v_pk_mul_f32 v[76:77], v[62:63], v[62:63]
	v_pk_mul_f32 v[78:79], v[60:61], v[60:61]
	v_pk_mul_f32 v[68:69], v[116:117], v[68:69]
	v_pk_mul_f32 v[70:71], v[118:119], v[70:71]
	v_pk_fma_f32 v[68:69], v[28:29], v[68:69], v[24:25]
	v_pk_fma_f32 v[70:71], v[30:31], v[70:71], v[26:27]
	v_cvt_pk_bf16_f32 v68, v68, v69
	v_cvt_pk_bf16_f32 v69, v70, v71
	global_store_dwordx2 v201, v[68:69], s[40:41]
	v_pk_mul_f32 v[72:73], v[66:67], v[66:67]
	v_pk_mul_f32 v[74:75], v[64:65], v[64:65]
	v_pk_mul_f32 v[36:37], v[120:121], v[36:37]
	v_pk_mul_f32 v[38:39], v[122:123], v[38:39]
	v_pk_fma_f32 v[36:37], v[4:5], v[36:37], v[0:1]
	v_pk_fma_f32 v[38:39], v[6:7], v[38:39], v[2:3]
	v_cvt_pk_bf16_f32 v36, v36, v37
	v_cvt_pk_bf16_f32 v37, v38, v39
	global_store_dwordx2 v210, v[36:37], s[40:41]
	v_pk_mov_b32 v[100:101], v[74:75], v[72:73] op_sel:[1, 0]
	v_mov_b32_e32 v75, v73
	v_pk_mov_b32 v[72:73], v[78:79], v[76:77] op_sel:[1, 0]
	v_mov_b32_e32 v79, v77
	v_pk_fma_f32 v[76:77], v[56:57], v[56:57], v[80:81] op_sel_hi:[1, 1, 0]
	v_pk_fma_f32 v[80:81], v[58:59], v[58:59], v[82:83] op_sel_hi:[1, 1, 0]
	v_pk_mov_b32 v[82:83], v[90:91], v[84:85] op_sel:[1, 0]
	v_mov_b32_e32 v91, v85
	v_pk_mov_b32 v[84:85], v[94:95], v[92:93] op_sel:[1, 0]
	v_mov_b32_e32 v95, v93
	v_pk_add_f32 v[74:75], v[100:101], v[74:75]
	v_pk_add_f32 v[68:69], v[72:73], v[78:79]
	v_pk_add_f32 v[70:71], v[82:83], v[90:91]
	v_pk_add_f32 v[72:73], v[84:85], v[94:95]
	v_pk_fma_f32 v[92:93], v[40:41], v[40:41], v[96:97] op_sel_hi:[1, 1, 0]
	v_pk_fma_f32 v[96:97], v[42:43], v[42:43], v[98:99] op_sel_hi:[1, 1, 0]
	v_pk_add_f32 v[74:75], v[74:75], v[74:75] op_sel:[0, 1] op_sel_hi:[1, 0]
	v_pk_add_f32 v[68:69], v[68:69], v[68:69] op_sel:[0, 1] op_sel_hi:[1, 0]
	v_pk_add_f32 v[70:71], v[70:71], v[70:71] op_sel:[0, 1] op_sel_hi:[1, 0]
	v_pk_add_f32 v[72:73], v[72:73], v[72:73] op_sel:[0, 1] op_sel_hi:[1, 0]
	v_mov_b32_e32 v77, v102
	v_mov_b32_e32 v81, v103
	v_mov_b32_e32 v93, v106
	v_mov_b32_e32 v97, v107
	v_mov_b32_e32 v75, v87
	v_mov_b32_e32 v69, v99
	v_mov_b32_e32 v71, v104
	v_mov_b32_e32 v73, v105
	v_pk_add_f32 v[76:77], v[76:77], v[80:81]
	v_pk_add_f32 v[78:79], v[92:93], v[96:97]
	v_pk_add_f32 v[68:69], v[74:75], v[68:69]
	v_pk_add_f32 v[70:71], v[70:71], v[72:73]
	v_pk_add_f32 v[68:69], v[68:69], v[76:77]
	v_pk_add_f32 v[70:71], v[70:71], v[78:79]
	v_mov_b32_e32 v73, v68
	v_mov_b32_e32 v72, v70
	v_mov_b32_e32 v68, v71
	v_pk_add_f32 v[68:69], v[72:73], v[68:69]
	s_waitcnt lgkmcnt(0)
	s_nop 1
	v_add_f32_dpp v68, v68, v68 quad_perm:[1,0,3,2] row_mask:0xf bank_mask:0xf
	v_add_f32_dpp v69, v69, v69 quad_perm:[1,0,3,2] row_mask:0xf bank_mask:0xf
	s_waitcnt lgkmcnt(0)
	s_nop 1
	v_add_f32_dpp v68, v68, v68 quad_perm:[2,3,0,1] row_mask:0xf bank_mask:0xf
	v_add_f32_dpp v69, v69, v69 quad_perm:[2,3,0,1] row_mask:0xf bank_mask:0xf
	s_waitcnt lgkmcnt(0)
	s_nop 1
	v_add_f32_dpp v68, v68, v68 row_half_mirror row_mask:0xf bank_mask:0xf
	v_add_f32_dpp v69, v69, v69 row_half_mirror row_mask:0xf bank_mask:0xf
	s_waitcnt lgkmcnt(0)
	s_nop 1
	v_add_f32_dpp v68, v68, v68 row_mirror row_mask:0xf bank_mask:0xf
	v_add_f32_dpp v69, v69, v69 row_mirror row_mask:0xf bank_mask:0xf
	ds_bpermute_b32 v71, v188, v69
	ds_bpermute_b32 v70, v188, v68
	s_waitcnt lgkmcnt(0)
	v_pk_add_f32 v[68:69], v[68:69], v[70:71]
	s_waitcnt lgkmcnt(0)
	v_mov_b32_e32 v70, v68
	v_mov_b32_e32 v71, v69
	s_nop 1
	v_permlane32_swap_b32_e32 v70, v68
	v_permlane32_swap_b32_e32 v71, v69
	v_pk_add_f32 v[68:69], v[68:69], v[70:71]
	s_nop 0
	v_pk_fma_f32 v[68:69], v[68:69], s[28:29], v[88:89] op_sel_hi:[1, 0, 0]
	s_nop 0
	v_mul_f32_e32 v70, 0x4b800000, v69
	v_cmp_gt_f32_e32 vcc, s71, v69
	s_nop 1
	v_cndmask_b32_e32 v69, v69, v70, vcc
	v_rsq_f32_e32 v69, v69
	v_lshl_add_u64 v[70:71], v[140:141], 0, s[38:39]
	s_add_u32 s38, s16, s38
	s_addc_u32 s39, s17, s39
	v_mul_f32_e32 v72, 0x45800000, v69
	v_cndmask_b32_e32 v72, v69, v72, vcc
	v_pk_mul_f32 v[66:67], v[66:67], v[72:73] op_sel_hi:[1, 0]
	v_pk_mul_f32 v[64:65], v[64:65], v[72:73] op_sel_hi:[1, 0]
	v_pk_mul_f32 v[38:39], v[110:111], v[66:67]
	v_pk_mul_f32 v[36:37], v[108:109], v[64:65]
	v_pk_fma_f32 v[38:39], v[14:15], v[38:39], v[10:11]
	v_pk_fma_f32 v[36:37], v[12:13], v[36:37], v[8:9]
	v_pk_mul_f32 v[62:63], v[62:63], v[72:73] op_sel_hi:[1, 0]
	v_cvt_pk_bf16_f32 v36, v36, v37
	v_cvt_pk_bf16_f32 v37, v38, v39
	global_store_dwordx2 v[70:71], v[36:37], off
	v_pk_mul_f32 v[60:61], v[60:61], v[72:73] op_sel_hi:[1, 0]
	v_pk_mul_f32 v[58:59], v[58:59], v[72:73] op_sel_hi:[1, 0]
	v_pk_mul_f32 v[56:57], v[56:57], v[72:73] op_sel_hi:[1, 0]
	v_pk_mul_f32 v[54:55], v[54:55], v[72:73] op_sel_hi:[1, 0]
	v_pk_mul_f32 v[52:53], v[52:53], v[72:73] op_sel_hi:[1, 0]
	v_cmp_gt_f32_e32 vcc, s71, v68
	s_lshl_b64 s[36:37], s[36:37], 11
	v_pk_mul_f32 v[36:37], v[112:113], v[60:61]
	v_pk_mul_f32 v[38:39], v[114:115], v[62:63]
	v_pk_fma_f32 v[36:37], v[20:21], v[36:37], v[16:17]
	v_pk_fma_f32 v[38:39], v[22:23], v[38:39], v[18:19]
	v_cvt_pk_bf16_f32 v36, v36, v37
	v_cvt_pk_bf16_f32 v37, v38, v39
	global_store_dwordx2 v200, v[36:37], s[38:39]
	v_pk_mul_f32 v[36:37], v[116:117], v[56:57]
	v_pk_mul_f32 v[38:39], v[118:119], v[58:59]
	v_pk_fma_f32 v[36:37], v[28:29], v[36:37], v[24:25]
	v_pk_fma_f32 v[38:39], v[30:31], v[38:39], v[26:27]
	v_cvt_pk_bf16_f32 v36, v36, v37
	v_cvt_pk_bf16_f32 v37, v38, v39
	global_store_dwordx2 v201, v[36:37], s[38:39]
	v_pk_mul_f32 v[36:37], v[120:121], v[52:53]
	v_pk_mul_f32 v[38:39], v[122:123], v[54:55]
	v_pk_fma_f32 v[36:37], v[4:5], v[36:37], v[0:1]
	v_pk_fma_f32 v[38:39], v[6:7], v[38:39], v[2:3]
	v_cvt_pk_bf16_f32 v36, v36, v37
	v_cvt_pk_bf16_f32 v37, v38, v39
	global_store_dwordx2 v210, v[36:37], s[38:39]
	v_mul_f32_e32 v52, 0x4b800000, v68
	v_cndmask_b32_e32 v52, v68, v52, vcc
	v_rsq_f32_e32 v54, v52
	v_lshl_add_u64 v[52:53], v[140:141], 0, s[36:37]
	s_add_u32 s36, s16, s36
	s_addc_u32 s37, s17, s37
	v_mul_f32_e32 v55, 0x45800000, v54
	v_cndmask_b32_e32 v54, v54, v55, vcc
	v_pk_mul_f32 v[50:51], v[50:51], v[54:55] op_sel_hi:[1, 0]
	v_pk_mul_f32 v[48:49], v[48:49], v[54:55] op_sel_hi:[1, 0]
	s_and_b64 vcc, exec, s[8:9]
	s_mov_b64 s[8:9], -1
	v_pk_mul_f32 v[36:37], v[108:109], v[48:49]
	v_pk_mul_f32 v[38:39], v[110:111], v[50:51]
	v_pk_fma_f32 v[8:9], v[12:13], v[36:37], v[8:9]
	v_pk_fma_f32 v[10:11], v[14:15], v[38:39], v[10:11]
	v_cvt_pk_bf16_f32 v8, v8, v9
	v_cvt_pk_bf16_f32 v9, v10, v11
	global_store_dwordx2 v[52:53], v[8:9], off
	v_pk_mul_f32 v[12:13], v[46:47], v[54:55] op_sel_hi:[1, 0]
	v_pk_mul_f32 v[14:15], v[44:45], v[54:55] op_sel_hi:[1, 0]
	v_pk_mul_f32 v[10:11], v[114:115], v[12:13]
	v_pk_mul_f32 v[8:9], v[112:113], v[14:15]
	v_pk_fma_f32 v[10:11], v[22:23], v[10:11], v[18:19]
	v_pk_fma_f32 v[8:9], v[20:21], v[8:9], v[16:17]
	v_pk_mul_f32 v[12:13], v[42:43], v[54:55] op_sel_hi:[1, 0]
	v_cvt_pk_bf16_f32 v8, v8, v9
	v_cvt_pk_bf16_f32 v9, v10, v11
	global_store_dwordx2 v200, v[8:9], s[36:37]
	v_pk_mul_f32 v[14:15], v[40:41], v[54:55] op_sel_hi:[1, 0]
	v_pk_mul_f32 v[10:11], v[118:119], v[12:13]
	v_pk_mul_f32 v[8:9], v[116:117], v[14:15]
	v_pk_fma_f32 v[10:11], v[30:31], v[10:11], v[26:27]
	v_pk_fma_f32 v[8:9], v[28:29], v[8:9], v[24:25]
	v_pk_mul_f32 v[12:13], v[34:35], v[54:55] op_sel_hi:[1, 0]
	v_cvt_pk_bf16_f32 v8, v8, v9
	v_cvt_pk_bf16_f32 v9, v10, v11
	global_store_dwordx2 v201, v[8:9], s[36:37]
	v_pk_mul_f32 v[14:15], v[32:33], v[54:55] op_sel_hi:[1, 0]
	v_pk_mul_f32 v[10:11], v[122:123], v[12:13]
	v_pk_mul_f32 v[8:9], v[120:121], v[14:15]
	v_pk_fma_f32 v[2:3], v[6:7], v[10:11], v[2:3]
	v_pk_fma_f32 v[0:1], v[4:5], v[8:9], v[0:1]
	s_nop 0
	v_cvt_pk_bf16_f32 v0, v0, v1
	v_cvt_pk_bf16_f32 v1, v2, v3
	global_store_dwordx2 v210, v[0:1], s[36:37]
	s_cbranch_vccnz .LBB0_1633
	s_andn2_b64 vcc, exec, s[10:11]
	s_cbranch_vccnz .LBB0_1632
	s_barrier
	s_branch .LBB0_1632

.LBB0_2375:
	s_or_b64 exec, exec, s[46:47]
	s_mul_i32 s44, s55, 0x9000
	s_mul_hi_i32 s59, s56, 0x9000
	s_add_i32 s58, s44, 0x240000
	s_mul_hi_i32 s57, s54, 0x9000
	s_add_i32 s56, s44, 0x288000
	v_lshl_add_u64 v[4:5], v[138:139], 0, s[58:59]
	s_mul_hi_i32 s55, s53, 0x9000
	s_add_i32 s54, s44, 0x2d0000
	s_barrier
	global_load_dwordx4 v[0:3], v[136:137], off
	v_lshl_add_u64 v[8:9], v[138:139], 0, s[56:57]
	global_load_dwordx4 v[4:7], v[4:5], off
	s_mul_hi_i32 s53, s52, 0x9000
	s_add_i32 s52, s44, 0x318000
	global_load_dwordx4 v[8:11], v[8:9], off
	v_lshl_add_u64 v[12:13], v[138:139], 0, s[54:55]
	s_mul_hi_i32 s51, s81, 0x9000
	s_add_i32 s50, s44, 0x360000
	global_load_dwordx4 v[12:15], v[12:13], off
	v_lshl_add_u64 v[16:17], v[138:139], 0, s[52:53]
	s_mul_hi_i32 s49, s80, 0x9000
	s_add_i32 s48, s44, 0x3a8000
	global_load_dwordx4 v[16:19], v[16:17], off
	v_lshl_add_u64 v[20:21], v[138:139], 0, s[50:51]
	s_mul_hi_i32 s47, s43, 0x9000
	s_add_i32 s46, s44, 0x3f0000
	global_load_dwordx4 v[20:23], v[20:21], off
	v_lshl_add_u64 v[24:25], v[138:139], 0, s[48:49]
	s_mul_hi_i32 s45, s37, 0x9000
	s_add_i32 s44, s44, 0x438000
	global_load_dwordx4 v[24:27], v[24:25], off
	v_lshl_add_u64 v[28:29], v[138:139], 0, s[46:47]
	global_load_dwordx4 v[28:31], v[28:29], off
	v_lshl_add_u64 v[32:33], v[138:139], 0, s[44:45]
	global_load_dwordx4 v[32:35], v[32:33], off
	s_lshl_b32 s37, s42, 6
	s_ashr_i32 s42, s82, 3
	s_add_i32 s35, s35, s37
	s_and_b32 s37, s42, -8
	s_add_i32 s42, s35, s37
	s_ashr_i32 s43, s42, 31
	s_lshl_b64 s[44:45], s[42:43], 12
	v_lshl_add_u64 v[36:37], v[140:141], 0, s[44:45]
	s_or_b32 s48, s42, 1
	s_ashr_i32 s49, s48, 31
	s_lshl_b64 s[44:45], s[48:49], 12
	v_mov_b64_e32 v[84:85], s[30:31]
	s_or_b32 s46, s42, 2
	s_ashr_i32 s47, s46, 31
	s_lshl_b64 s[52:53], s[46:47], 12
	s_lshl_b64 s[50:51], s[42:43], 11
	s_waitcnt vmcnt(7)
	v_pk_add_f32 v[2:3], v[2:3], v[6:7]
	v_pk_add_f32 v[0:1], v[0:1], v[4:5]
	s_waitcnt vmcnt(6)
	v_pk_add_f32 v[2:3], v[2:3], v[10:11]
	v_pk_add_f32 v[0:1], v[0:1], v[8:9]
	v_lshl_add_u64 v[8:9], v[140:141], 0, s[44:45]
	s_or_b32 s44, s42, 3
	s_waitcnt vmcnt(5)
	v_pk_add_f32 v[2:3], v[2:3], v[14:15]
	v_pk_add_f32 v[0:1], v[0:1], v[12:13]
	s_ashr_i32 s45, s44, 31
	s_lshl_b64 s[54:55], s[44:45], 12
	s_waitcnt vmcnt(4)
	v_pk_add_f32 v[2:3], v[2:3], v[18:19]
	v_pk_add_f32 v[0:1], v[0:1], v[16:17]
	s_waitcnt vmcnt(3)
	v_pk_add_f32 v[2:3], v[2:3], v[22:23]
	v_pk_add_f32 v[0:1], v[0:1], v[20:21]
	s_waitcnt vmcnt(2)
	v_pk_add_f32 v[2:3], v[2:3], v[26:27]
	v_pk_add_f32 v[0:1], v[0:1], v[24:25]
	s_waitcnt vmcnt(1)
	v_pk_add_f32 v[2:3], v[2:3], v[30:31]
	v_pk_add_f32 v[0:1], v[0:1], v[28:29]
	s_waitcnt vmcnt(0)
	v_pk_add_f32 v[2:3], v[2:3], v[34:35]
	v_pk_add_f32 v[0:1], v[0:1], v[32:33]
	v_pk_add_f32 v[4:5], v[2:3], 1.0 op_sel_hi:[1,0]
	v_pk_add_f32 v[6:7], v[0:1], 1.0 op_sel_hi:[1,0]
	v_cndmask_b32_e64 v3, v5, v3, s[6:7]
	v_cndmask_b32_e64 v2, v4, v2, s[6:7]
	v_cndmask_b32_e64 v1, v7, v1, s[6:7]
	v_cndmask_b32_e64 v0, v6, v0, s[6:7]
	ds_write_b128 v183, v[0:3]
	s_waitcnt lgkmcnt(0)
	s_barrier
	global_load_dwordx4 v[108:111], v[142:143], off
	global_load_dwordx4 v[112:115], v[146:147], off
	global_load_dwordx4 v[116:119], v[148:149], off
	global_load_dwordx4 v[120:123], v[150:151], off
	global_load_dwordx4 v[16:19], v[36:37], off
	global_load_dwordx4 v[4:7], v[36:37], off offset:1024
	global_load_dwordx4 v[80:83], v[36:37], off offset:3072
	global_load_dwordx4 v[0:3], v[36:37], off offset:2048
	global_load_dwordx4 v[76:79], v[8:9], off
	global_load_dwordx4 v[68:71], v[8:9], off offset:1024
	s_nop 0
	global_load_dwordx4 v[36:39], v[8:9], off offset:3072
	global_load_dwordx4 v[64:67], v[8:9], off offset:2048
	s_waitcnt vmcnt(3)
	v_pk_mul_f32 v[28:29], v[78:79], v[78:79]
	v_pk_mul_f32 v[8:9], v[18:19], v[18:19]
	v_pk_mul_f32 v[10:11], v[16:17], v[16:17]
	v_pk_mul_f32 v[12:13], v[6:7], v[6:7]
	v_pk_mul_f32 v[14:15], v[4:5], v[4:5]
	v_mul_f32_e32 v24, v1, v1
	v_mul_f32_e32 v26, v3, v3
	v_pk_mul_f32 v[30:31], v[76:77], v[76:77]
	s_waitcnt vmcnt(2)
	v_pk_mul_f32 v[32:33], v[70:71], v[70:71]
	v_pk_mul_f32 v[34:35], v[68:69], v[68:69]
	v_mul_f32_e32 v47, v82, v82
	v_mul_f32_e32 v48, v83, v83
	v_pk_mov_b32 v[44:45], v[10:11], v[8:9] op_sel:[1, 0]
	v_mov_b32_e32 v11, v9
	v_pk_mov_b32 v[8:9], v[14:15], v[12:13] op_sel:[1, 0]
	v_mov_b32_e32 v15, v13
	v_pk_fma_f32 v[12:13], v[0:1], v[0:1], v[24:25] op_sel_hi:[1, 1, 0]
	v_pk_fma_f32 v[24:25], v[2:3], v[2:3], v[26:27] op_sel_hi:[1, 1, 0]
	v_pk_mov_b32 v[26:27], v[30:31], v[28:29] op_sel:[1, 0]
	v_mov_b32_e32 v31, v29
	v_pk_mov_b32 v[28:29], v[34:35], v[32:33] op_sel:[1, 0]
	v_mov_b32_e32 v35, v33
	v_mul_f32_e32 v43, v80, v80
	s_waitcnt vmcnt(0)
	v_mul_f32_e32 v40, v65, v65
	v_mul_f32_e32 v42, v67, v67
	v_pk_add_f32 v[10:11], v[44:45], v[10:11]
	v_pk_add_f32 v[8:9], v[8:9], v[14:15]
	v_mov_b32_e32 v13, v47
	v_mov_b32_e32 v25, v48
	v_pk_add_f32 v[14:15], v[26:27], v[30:31]
	v_pk_add_f32 v[26:27], v[28:29], v[34:35]
	v_mul_f32_e32 v46, v81, v81
	v_mul_f32_e32 v49, v36, v36
	v_mul_f32_e32 v50, v37, v37
	v_mul_f32_e32 v51, v38, v38
	v_mul_f32_e32 v52, v39, v39
	v_pk_fma_f32 v[32:33], v[64:65], v[64:65], v[40:41] op_sel_hi:[1, 1, 0]
	v_pk_fma_f32 v[40:41], v[66:67], v[66:67], v[42:43] op_sel_hi:[1, 1, 0]
	v_pk_add_f32 v[10:11], v[10:11], v[10:11] op_sel:[0, 1] op_sel_hi:[1, 0]
	v_pk_add_f32 v[8:9], v[8:9], v[8:9] op_sel:[0, 1] op_sel_hi:[1, 0]
	v_pk_add_f32 v[12:13], v[12:13], v[24:25]
	v_pk_add_f32 v[14:15], v[14:15], v[14:15] op_sel:[0, 1] op_sel_hi:[1, 0]
	v_pk_add_f32 v[24:25], v[26:27], v[26:27] op_sel:[0, 1] op_sel_hi:[1, 0]
	v_mov_b32_e32 v33, v51
	v_mov_b32_e32 v41, v52
	v_mov_b32_e32 v11, v43
	v_mov_b32_e32 v9, v46
	v_mov_b32_e32 v15, v49
	v_mov_b32_e32 v25, v50
	v_pk_add_f32 v[26:27], v[32:33], v[40:41]
	v_pk_add_f32 v[8:9], v[10:11], v[8:9]
	v_pk_add_f32 v[10:11], v[14:15], v[24:25]
	v_pk_add_f32 v[8:9], v[8:9], v[12:13]
	v_pk_add_f32 v[10:11], v[10:11], v[26:27]
	v_mov_b32_e32 v13, v8
	v_mov_b32_e32 v12, v10
	v_mov_b32_e32 v8, v11
	v_pk_add_f32 v[8:9], v[12:13], v[8:9]
	v_lshl_add_u64 v[12:13], v[140:141], 0, s[52:53]
	v_lshl_add_u64 v[14:15], v[140:141], 0, s[54:55]
	global_load_dwordx4 v[72:75], v[12:13], off
	global_load_dwordx4 v[60:63], v[12:13], off offset:1024
	global_load_dwordx4 v[56:59], v[12:13], off offset:2048
	global_load_dwordx4 v[52:55], v[12:13], off offset:3072
	global_load_dwordx4 v[48:51], v[14:15], off
	global_load_dwordx4 v[44:47], v[14:15], off offset:1024
	s_waitcnt lgkmcnt(0)
	s_nop 1
	v_add_f32_dpp v8, v8, v8 quad_perm:[1,0,3,2] row_mask:0xf bank_mask:0xf
	v_add_f32_dpp v9, v9, v9 quad_perm:[1,0,3,2] row_mask:0xf bank_mask:0xf
	global_load_dwordx4 v[40:43], v[14:15], off offset:2048
	global_load_dwordx4 v[32:35], v[14:15], off offset:3072
	v_lshl_add_u64 v[24:25], v[144:145], 0, s[50:51]
	s_add_u32 s50, s12, s50
	s_addc_u32 s51, s13, s51
	s_waitcnt lgkmcnt(0)
	s_nop 1
	v_add_f32_dpp v8, v8, v8 quad_perm:[2,3,0,1] row_mask:0xf bank_mask:0xf
	v_add_f32_dpp v9, v9, v9 quad_perm:[2,3,0,1] row_mask:0xf bank_mask:0xf
	s_lshl_b64 s[48:49], s[48:49], 11
	s_waitcnt lgkmcnt(0)
	s_nop 1
	v_add_f32_dpp v8, v8, v8 row_half_mirror row_mask:0xf bank_mask:0xf
	v_add_f32_dpp v9, v9, v9 row_half_mirror row_mask:0xf bank_mask:0xf
	s_waitcnt lgkmcnt(0)
	s_nop 1
	v_add_f32_dpp v8, v8, v8 row_mirror row_mask:0xf bank_mask:0xf
	v_add_f32_dpp v9, v9, v9 row_mirror row_mask:0xf bank_mask:0xf
	ds_bpermute_b32 v11, v188, v9
	ds_bpermute_b32 v10, v188, v8
	s_waitcnt lgkmcnt(0)
	v_pk_add_f32 v[8:9], v[8:9], v[10:11]
	s_waitcnt lgkmcnt(0)
	v_mov_b32_e32 v10, v8
	v_mov_b32_e32 v11, v9
	s_nop 1
	v_permlane32_swap_b32_e32 v10, v8
	v_permlane32_swap_b32_e32 v11, v9
	v_pk_add_f32 v[8:9], v[8:9], v[10:11]
	s_nop 0
	v_pk_fma_f32 v[90:91], v[8:9], s[28:29], v[84:85] op_sel_hi:[1, 0, 0]
	s_waitcnt vmcnt(4)
	v_mul_f32_e32 v99, v53, v53
	v_mul_f32_e32 v8, 0x4b800000, v91
	v_cmp_gt_f32_e32 vcc, s79, v91
	s_waitcnt vmcnt(2)
	v_pk_mul_f32 v[94:95], v[44:45], v[44:45]
	v_mul_f32_e32 v102, v54, v54
	v_cndmask_b32_e32 v8, v91, v8, vcc
	v_rsq_f32_e32 v26, v8
	ds_read_b128 v[8:11], v190
	ds_read_b128 v[12:15], v191
	s_waitcnt vmcnt(1)
	v_mul_f32_e32 v96, v41, v41
	v_mul_f32_e32 v98, v43, v43
	v_mul_f32_e32 v27, 0x45800000, v26
	v_cndmask_b32_e32 v92, v26, v27, vcc
	v_pk_mul_f32 v[18:19], v[18:19], v[92:93] op_sel_hi:[1, 0]
	v_pk_mul_f32 v[16:17], v[16:17], v[92:93] op_sel_hi:[1, 0]
	v_pk_mul_f32 v[18:19], v[110:111], v[18:19]
	v_pk_mul_f32 v[16:17], v[108:109], v[16:17]
	s_waitcnt lgkmcnt(0)
	v_pk_fma_f32 v[18:19], v[14:15], v[18:19], v[10:11]
	v_pk_fma_f32 v[16:17], v[12:13], v[16:17], v[8:9]
	v_pk_mul_f32 v[6:7], v[6:7], v[92:93] op_sel_hi:[1, 0]
	v_cvt_pk_bf16_f32 v16, v16, v17
	v_cvt_pk_bf16_f32 v17, v18, v19
	global_store_dwordx2 v[24:25], v[16:17], off
	ds_read_b128 v[16:19], v192
	ds_read_b128 v[20:23], v193
	v_pk_mul_f32 v[4:5], v[4:5], v[92:93] op_sel_hi:[1, 0]
	v_pk_mul_f32 v[2:3], v[2:3], v[92:93] op_sel_hi:[1, 0]
	v_pk_mul_f32 v[0:1], v[0:1], v[92:93] op_sel_hi:[1, 0]
	v_pk_mul_f32 v[82:83], v[82:83], v[92:93] op_sel_hi:[1, 0]
	v_pk_mul_f32 v[80:81], v[80:81], v[92:93] op_sel_hi:[1, 0]
	v_cmp_gt_f32_e32 vcc, s79, v90
	v_pk_mul_f32 v[92:93], v[46:47], v[46:47]
	v_mul_f32_e32 v103, v55, v55
	s_waitcnt vmcnt(1)
	v_mul_f32_e32 v104, v32, v32
	v_mul_f32_e32 v105, v33, v33
	v_mul_f32_e32 v106, v34, v34
	v_mul_f32_e32 v107, v35, v35
	v_pk_mul_f32 v[4:5], v[112:113], v[4:5]
	v_pk_mul_f32 v[6:7], v[114:115], v[6:7]
	s_waitcnt lgkmcnt(0)
	v_pk_fma_f32 v[4:5], v[20:21], v[4:5], v[16:17]
	v_pk_fma_f32 v[6:7], v[22:23], v[6:7], v[18:19]
	v_cvt_pk_bf16_f32 v4, v4, v5
	v_cvt_pk_bf16_f32 v5, v6, v7
	global_store_dwordx2 v200, v[4:5], s[50:51]
	ds_read_b128 v[24:27], v194
	ds_read_b128 v[28:31], v195
	v_pk_mul_f32 v[0:1], v[116:117], v[0:1]
	v_pk_mul_f32 v[2:3], v[118:119], v[2:3]
	s_waitcnt lgkmcnt(0)
	v_pk_fma_f32 v[0:1], v[28:29], v[0:1], v[24:25]
	v_pk_fma_f32 v[2:3], v[30:31], v[2:3], v[26:27]
	v_cvt_pk_bf16_f32 v0, v0, v1
	v_cvt_pk_bf16_f32 v1, v2, v3
	global_store_dwordx2 v201, v[0:1], s[50:51]
	ds_read_b128 v[0:3], v196
	ds_read_b128 v[4:7], v197
	v_pk_mul_f32 v[80:81], v[80:81], v[120:121]
	v_pk_mul_f32 v[82:83], v[82:83], v[122:123]
	s_waitcnt lgkmcnt(0)
	v_pk_fma_f32 v[80:81], v[80:81], v[4:5], v[0:1]
	v_pk_fma_f32 v[82:83], v[82:83], v[6:7], v[2:3]
	v_cvt_pk_bf16_f32 v80, v80, v81
	v_cvt_pk_bf16_f32 v81, v82, v83
	global_store_dwordx2 v210, v[80:81], s[50:51]
	v_mul_f32_e32 v86, 0x4b800000, v90
	v_cndmask_b32_e32 v86, v90, v86, vcc
	v_rsq_f32_e32 v88, v86
	v_lshl_add_u64 v[86:87], v[144:145], 0, s[48:49]
	s_add_u32 s48, s12, s48
	s_addc_u32 s49, s13, s49
	v_mul_f32_e32 v89, 0x45800000, v88
	v_cndmask_b32_e32 v88, v88, v89, vcc
	v_pk_mul_f32 v[78:79], v[78:79], v[88:89] op_sel_hi:[1, 0]
	v_pk_mul_f32 v[76:77], v[76:77], v[88:89] op_sel_hi:[1, 0]
	v_pk_mul_f32 v[70:71], v[70:71], v[88:89] op_sel_hi:[1, 0]
	v_pk_mul_f32 v[68:69], v[68:69], v[88:89] op_sel_hi:[1, 0]
	v_pk_mul_f32 v[66:67], v[66:67], v[88:89] op_sel_hi:[1, 0]
	v_pk_mul_f32 v[64:65], v[64:65], v[88:89] op_sel_hi:[1, 0]
	v_mul_f32_e32 v89, v52, v52
	v_pk_mul_f32 v[38:39], v[38:39], v[88:89] op_sel_hi:[1, 0]
	v_pk_mul_f32 v[36:37], v[36:37], v[88:89] op_sel_hi:[1, 0]
	v_pk_mul_f32 v[90:91], v[48:49], v[48:49]
	s_lshl_b64 s[46:47], s[46:47], 11
	v_pk_mul_f32 v[76:77], v[108:109], v[76:77]
	v_pk_mul_f32 v[78:79], v[110:111], v[78:79]
	v_pk_fma_f32 v[76:77], v[12:13], v[76:77], v[8:9]
	v_pk_fma_f32 v[78:79], v[14:15], v[78:79], v[10:11]
	v_cvt_pk_bf16_f32 v76, v76, v77
	v_cvt_pk_bf16_f32 v77, v78, v79
	global_store_dwordx2 v[86:87], v[76:77], off
	v_mul_f32_e32 v80, v57, v57
	v_mul_f32_e32 v82, v59, v59
	v_pk_mul_f32 v[86:87], v[50:51], v[50:51]
	v_pk_mul_f32 v[68:69], v[112:113], v[68:69]
	v_pk_mul_f32 v[70:71], v[114:115], v[70:71]
	v_pk_fma_f32 v[68:69], v[20:21], v[68:69], v[16:17]
	v_pk_fma_f32 v[70:71], v[22:23], v[70:71], v[18:19]
	v_cvt_pk_bf16_f32 v68, v68, v69
	v_cvt_pk_bf16_f32 v69, v70, v71
	global_store_dwordx2 v200, v[68:69], s[48:49]
	v_pk_mul_f32 v[76:77], v[62:63], v[62:63]
	v_pk_mul_f32 v[78:79], v[60:61], v[60:61]
	v_pk_mul_f32 v[64:65], v[116:117], v[64:65]
	v_pk_mul_f32 v[66:67], v[118:119], v[66:67]
	v_pk_fma_f32 v[64:65], v[28:29], v[64:65], v[24:25]
	v_pk_fma_f32 v[66:67], v[30:31], v[66:67], v[26:27]
	v_cvt_pk_bf16_f32 v64, v64, v65
	v_cvt_pk_bf16_f32 v65, v66, v67
	global_store_dwordx2 v201, v[64:65], s[48:49]
	v_pk_mul_f32 v[68:69], v[74:75], v[74:75]
	v_pk_mul_f32 v[70:71], v[72:73], v[72:73]
	v_pk_mul_f32 v[36:37], v[120:121], v[36:37]
	v_pk_mul_f32 v[38:39], v[122:123], v[38:39]
	v_pk_fma_f32 v[36:37], v[4:5], v[36:37], v[0:1]
	v_pk_fma_f32 v[38:39], v[6:7], v[38:39], v[2:3]
	v_cvt_pk_bf16_f32 v36, v36, v37
	v_cvt_pk_bf16_f32 v37, v38, v39
	global_store_dwordx2 v210, v[36:37], s[48:49]
	v_pk_mov_b32 v[100:101], v[70:71], v[68:69] op_sel:[1, 0]
	v_mov_b32_e32 v71, v69
	v_pk_mov_b32 v[68:69], v[78:79], v[76:77] op_sel:[1, 0]
	v_mov_b32_e32 v79, v77
	v_pk_fma_f32 v[76:77], v[56:57], v[56:57], v[80:81] op_sel_hi:[1, 1, 0]
	v_pk_fma_f32 v[80:81], v[58:59], v[58:59], v[82:83] op_sel_hi:[1, 1, 0]
	v_pk_mov_b32 v[82:83], v[90:91], v[86:87] op_sel:[1, 0]
	v_mov_b32_e32 v91, v87
	v_pk_mov_b32 v[86:87], v[94:95], v[92:93] op_sel:[1, 0]
	v_mov_b32_e32 v95, v93
	v_pk_add_f32 v[70:71], v[100:101], v[70:71]
	v_pk_add_f32 v[64:65], v[68:69], v[78:79]
	v_pk_add_f32 v[66:67], v[82:83], v[90:91]
	v_pk_add_f32 v[68:69], v[86:87], v[94:95]
	v_pk_fma_f32 v[92:93], v[40:41], v[40:41], v[96:97] op_sel_hi:[1, 1, 0]
	v_pk_fma_f32 v[96:97], v[42:43], v[42:43], v[98:99] op_sel_hi:[1, 1, 0]
	v_pk_add_f32 v[70:71], v[70:71], v[70:71] op_sel:[0, 1] op_sel_hi:[1, 0]
	v_pk_add_f32 v[64:65], v[64:65], v[64:65] op_sel:[0, 1] op_sel_hi:[1, 0]
	v_pk_add_f32 v[66:67], v[66:67], v[66:67] op_sel:[0, 1] op_sel_hi:[1, 0]
	v_pk_add_f32 v[68:69], v[68:69], v[68:69] op_sel:[0, 1] op_sel_hi:[1, 0]
	v_mov_b32_e32 v77, v102
	v_mov_b32_e32 v81, v103
	v_mov_b32_e32 v93, v106
	v_mov_b32_e32 v97, v107
	v_mov_b32_e32 v71, v89
	v_mov_b32_e32 v65, v99
	v_mov_b32_e32 v67, v104
	v_mov_b32_e32 v69, v105
	v_pk_add_f32 v[76:77], v[76:77], v[80:81]
	v_pk_add_f32 v[78:79], v[92:93], v[96:97]
	v_pk_add_f32 v[64:65], v[70:71], v[64:65]
	v_pk_add_f32 v[66:67], v[66:67], v[68:69]
	v_pk_add_f32 v[64:65], v[64:65], v[76:77]
	v_pk_add_f32 v[66:67], v[66:67], v[78:79]
	v_mov_b32_e32 v69, v64
	v_mov_b32_e32 v68, v66
	v_mov_b32_e32 v64, v67
	v_pk_add_f32 v[64:65], v[68:69], v[64:65]
	s_waitcnt lgkmcnt(0)
	s_nop 1
	v_add_f32_dpp v64, v64, v64 quad_perm:[1,0,3,2] row_mask:0xf bank_mask:0xf
	v_add_f32_dpp v65, v65, v65 quad_perm:[1,0,3,2] row_mask:0xf bank_mask:0xf
	s_waitcnt lgkmcnt(0)
	s_nop 1
	v_add_f32_dpp v64, v64, v64 quad_perm:[2,3,0,1] row_mask:0xf bank_mask:0xf
	v_add_f32_dpp v65, v65, v65 quad_perm:[2,3,0,1] row_mask:0xf bank_mask:0xf
	s_waitcnt lgkmcnt(0)
	s_nop 1
	v_add_f32_dpp v64, v64, v64 row_half_mirror row_mask:0xf bank_mask:0xf
	v_add_f32_dpp v65, v65, v65 row_half_mirror row_mask:0xf bank_mask:0xf
	s_waitcnt lgkmcnt(0)
	s_nop 1
	v_add_f32_dpp v64, v64, v64 row_mirror row_mask:0xf bank_mask:0xf
	v_add_f32_dpp v65, v65, v65 row_mirror row_mask:0xf bank_mask:0xf
	ds_bpermute_b32 v67, v188, v65
	ds_bpermute_b32 v66, v188, v64
	s_waitcnt lgkmcnt(0)
	v_pk_add_f32 v[64:65], v[64:65], v[66:67]
	s_waitcnt lgkmcnt(0)
	v_mov_b32_e32 v66, v64
	v_mov_b32_e32 v67, v65
	s_nop 1
	v_permlane32_swap_b32_e32 v66, v64
	v_permlane32_swap_b32_e32 v67, v65
	v_pk_add_f32 v[64:65], v[64:65], v[66:67]
	s_nop 0
	v_pk_fma_f32 v[64:65], v[64:65], s[28:29], v[84:85] op_sel_hi:[1, 0, 0]
	s_nop 0
	v_mul_f32_e32 v66, 0x4b800000, v65
	v_cmp_gt_f32_e32 vcc, s79, v65
	s_nop 1
	v_cndmask_b32_e32 v65, v65, v66, vcc
	v_rsq_f32_e32 v65, v65
	v_lshl_add_u64 v[66:67], v[144:145], 0, s[46:47]
	s_add_u32 s46, s12, s46
	s_addc_u32 s47, s13, s47
	v_mul_f32_e32 v68, 0x45800000, v65
	v_cndmask_b32_e32 v68, v65, v68, vcc
	v_pk_mul_f32 v[70:71], v[74:75], v[68:69] op_sel_hi:[1, 0]
	v_pk_mul_f32 v[72:73], v[72:73], v[68:69] op_sel_hi:[1, 0]
	v_pk_mul_f32 v[38:39], v[110:111], v[70:71]
	v_pk_mul_f32 v[36:37], v[108:109], v[72:73]
	v_pk_fma_f32 v[38:39], v[14:15], v[38:39], v[10:11]
	v_pk_fma_f32 v[36:37], v[12:13], v[36:37], v[8:9]
	v_pk_mul_f32 v[62:63], v[62:63], v[68:69] op_sel_hi:[1, 0]
	v_cvt_pk_bf16_f32 v36, v36, v37
	v_cvt_pk_bf16_f32 v37, v38, v39
	global_store_dwordx2 v[66:67], v[36:37], off
	v_pk_mul_f32 v[60:61], v[60:61], v[68:69] op_sel_hi:[1, 0]
	v_pk_mul_f32 v[58:59], v[58:59], v[68:69] op_sel_hi:[1, 0]
	v_pk_mul_f32 v[56:57], v[56:57], v[68:69] op_sel_hi:[1, 0]
	v_pk_mul_f32 v[54:55], v[54:55], v[68:69] op_sel_hi:[1, 0]
	v_pk_mul_f32 v[52:53], v[52:53], v[68:69] op_sel_hi:[1, 0]
	v_cmp_gt_f32_e32 vcc, s79, v64
	s_lshl_b64 s[44:45], s[44:45], 11
	v_pk_mul_f32 v[36:37], v[112:113], v[60:61]
	v_pk_mul_f32 v[38:39], v[114:115], v[62:63]
	v_pk_fma_f32 v[36:37], v[20:21], v[36:37], v[16:17]
	v_pk_fma_f32 v[38:39], v[22:23], v[38:39], v[18:19]
	v_cvt_pk_bf16_f32 v36, v36, v37
	v_cvt_pk_bf16_f32 v37, v38, v39
	global_store_dwordx2 v200, v[36:37], s[46:47]
	v_pk_mul_f32 v[36:37], v[116:117], v[56:57]
	v_pk_mul_f32 v[38:39], v[118:119], v[58:59]
	v_pk_fma_f32 v[36:37], v[28:29], v[36:37], v[24:25]
	v_pk_fma_f32 v[38:39], v[30:31], v[38:39], v[26:27]
	v_cvt_pk_bf16_f32 v36, v36, v37
	v_cvt_pk_bf16_f32 v37, v38, v39
	global_store_dwordx2 v201, v[36:37], s[46:47]
	v_pk_mul_f32 v[36:37], v[120:121], v[52:53]
	v_pk_mul_f32 v[38:39], v[122:123], v[54:55]
	v_pk_fma_f32 v[36:37], v[4:5], v[36:37], v[0:1]
	v_pk_fma_f32 v[38:39], v[6:7], v[38:39], v[2:3]
	v_cvt_pk_bf16_f32 v36, v36, v37
	v_cvt_pk_bf16_f32 v37, v38, v39
	global_store_dwordx2 v210, v[36:37], s[46:47]
	v_mul_f32_e32 v52, 0x4b800000, v64
	v_cndmask_b32_e32 v52, v64, v52, vcc
	v_rsq_f32_e32 v54, v52
	v_lshl_add_u64 v[52:53], v[144:145], 0, s[44:45]
	s_add_u32 s44, s12, s44
	s_addc_u32 s45, s13, s45
	v_mul_f32_e32 v55, 0x45800000, v54
	v_cndmask_b32_e32 v54, v54, v55, vcc
	v_pk_mul_f32 v[50:51], v[50:51], v[54:55] op_sel_hi:[1, 0]
	v_pk_mul_f32 v[48:49], v[48:49], v[54:55] op_sel_hi:[1, 0]
	v_pk_mul_f32 v[46:47], v[46:47], v[54:55] op_sel_hi:[1, 0]
	v_pk_mul_f32 v[44:45], v[44:45], v[54:55] op_sel_hi:[1, 0]
	v_pk_mul_f32 v[42:43], v[42:43], v[54:55] op_sel_hi:[1, 0]
	v_pk_mul_f32 v[40:41], v[40:41], v[54:55] op_sel_hi:[1, 0]
	v_pk_mul_f32 v[34:35], v[34:35], v[54:55] op_sel_hi:[1, 0]
	v_pk_mul_f32 v[32:33], v[32:33], v[54:55] op_sel_hi:[1, 0]
	s_or_b32 s48, s42, 4
	s_ashr_i32 s49, s48, 31
	s_lshl_b64 s[46:47], s[48:49], 12
	s_lshl_b64 s[48:49], s[48:49], 11
	v_lshl_add_u64 v[104:105], v[144:145], 0, s[48:49]
	v_pk_mul_f32 v[36:37], v[108:109], v[48:49]
	v_pk_mul_f32 v[38:39], v[110:111], v[50:51]
	v_pk_fma_f32 v[36:37], v[12:13], v[36:37], v[8:9]
	v_pk_fma_f32 v[38:39], v[14:15], v[38:39], v[10:11]
	v_cvt_pk_bf16_f32 v36, v36, v37
	v_cvt_pk_bf16_f32 v37, v38, v39
	global_store_dwordx2 v[52:53], v[36:37], off
	v_pk_mul_f32 v[36:37], v[112:113], v[44:45]
	v_pk_mul_f32 v[38:39], v[114:115], v[46:47]
	v_pk_fma_f32 v[36:37], v[20:21], v[36:37], v[16:17]
	v_pk_fma_f32 v[38:39], v[22:23], v[38:39], v[18:19]
	v_cvt_pk_bf16_f32 v36, v36, v37
	v_cvt_pk_bf16_f32 v37, v38, v39
	global_store_dwordx2 v200, v[36:37], s[44:45]
	v_pk_mul_f32 v[36:37], v[116:117], v[40:41]
	v_pk_mul_f32 v[38:39], v[118:119], v[42:43]
	v_pk_fma_f32 v[36:37], v[28:29], v[36:37], v[24:25]
	v_pk_fma_f32 v[38:39], v[30:31], v[38:39], v[26:27]
	v_cvt_pk_bf16_f32 v36, v36, v37
	v_cvt_pk_bf16_f32 v37, v38, v39
	global_store_dwordx2 v201, v[36:37], s[44:45]
	v_lshl_add_u64 v[40:41], v[140:141], 0, s[46:47]
	s_or_b32 s46, s42, 5
	s_ashr_i32 s47, s46, 31
	v_pk_mul_f32 v[32:33], v[120:121], v[32:33]
	v_pk_mul_f32 v[34:35], v[122:123], v[34:35]
	v_pk_fma_f32 v[32:33], v[4:5], v[32:33], v[0:1]
	v_pk_fma_f32 v[34:35], v[6:7], v[34:35], v[2:3]
	v_cvt_pk_bf16_f32 v32, v32, v33
	v_cvt_pk_bf16_f32 v33, v34, v35
	global_store_dwordx2 v210, v[32:33], s[44:45]
	global_load_dwordx4 v[86:89], v[40:41], off
	global_load_dwordx4 v[90:93], v[40:41], off offset:1024
	global_load_dwordx4 v[80:83], v[40:41], off offset:3072
	global_load_dwordx4 v[94:97], v[40:41], off offset:2048
	s_lshl_b64 s[44:45], s[46:47], 12
	v_lshl_add_u64 v[32:33], v[140:141], 0, s[44:45]
	global_load_dwordx4 v[76:79], v[32:33], off
	global_load_dwordx4 v[72:75], v[32:33], off offset:1024
	global_load_dwordx4 v[36:39], v[32:33], off offset:3072
	global_load_dwordx4 v[68:71], v[32:33], off offset:2048
	s_or_b32 s44, s42, 6
	s_or_b32 s42, s42, 7
	s_ashr_i32 s45, s44, 31
	s_ashr_i32 s43, s42, 31
	s_lshl_b64 s[50:51], s[44:45], 12
	s_lshl_b64 s[52:53], s[42:43], 12
	s_add_u32 s48, s12, s48
	s_addc_u32 s49, s13, s49
	s_lshl_b64 s[46:47], s[46:47], 11
	s_waitcnt vmcnt(7)
	v_pk_mul_f32 v[32:33], v[88:89], v[88:89]
	v_pk_mul_f32 v[34:35], v[86:87], v[86:87]
	s_waitcnt vmcnt(6)
	v_pk_mul_f32 v[40:41], v[92:93], v[92:93]
	v_pk_mul_f32 v[42:43], v[90:91], v[90:91]
	s_waitcnt vmcnt(4)
	v_mul_f32_e32 v44, v95, v95
	v_mul_f32_e32 v46, v97, v97
	s_waitcnt vmcnt(3)
	v_pk_mul_f32 v[48:49], v[78:79], v[78:79]
	v_pk_mul_f32 v[50:51], v[76:77], v[76:77]
	s_waitcnt vmcnt(2)
	v_pk_mul_f32 v[52:53], v[74:75], v[74:75]
	v_pk_mul_f32 v[54:55], v[72:73], v[72:73]
	v_mul_f32_e32 v63, v82, v82
	v_mul_f32_e32 v64, v83, v83
	v_pk_mov_b32 v[60:61], v[34:35], v[32:33] op_sel:[1, 0]
	v_mov_b32_e32 v35, v33
	v_pk_mov_b32 v[32:33], v[42:43], v[40:41] op_sel:[1, 0]
	v_mov_b32_e32 v43, v41
	v_pk_fma_f32 v[40:41], v[94:95], v[94:95], v[44:45] op_sel_hi:[1, 1, 0]
	v_pk_fma_f32 v[44:45], v[96:97], v[96:97], v[46:47] op_sel_hi:[1, 1, 0]
	v_pk_mov_b32 v[46:47], v[50:51], v[48:49] op_sel:[1, 0]
	v_mov_b32_e32 v51, v49
	v_pk_mov_b32 v[48:49], v[54:55], v[52:53] op_sel:[1, 0]
	v_mov_b32_e32 v55, v53
	v_mul_f32_e32 v59, v80, v80
	s_waitcnt vmcnt(0)
	v_mul_f32_e32 v56, v69, v69
	v_mul_f32_e32 v58, v71, v71
	v_pk_add_f32 v[34:35], v[60:61], v[34:35]
	v_pk_add_f32 v[32:33], v[32:33], v[42:43]
	v_mov_b32_e32 v41, v63
	v_mov_b32_e32 v45, v64
	v_pk_add_f32 v[42:43], v[46:47], v[50:51]
	v_pk_add_f32 v[46:47], v[48:49], v[54:55]
	v_mul_f32_e32 v62, v81, v81
	v_mul_f32_e32 v65, v36, v36
	v_mul_f32_e32 v66, v37, v37
	v_mul_f32_e32 v67, v38, v38
	v_mul_f32_e32 v102, v39, v39
	v_pk_fma_f32 v[52:53], v[68:69], v[68:69], v[56:57] op_sel_hi:[1, 1, 0]
	v_pk_fma_f32 v[56:57], v[70:71], v[70:71], v[58:59] op_sel_hi:[1, 1, 0]
	v_pk_add_f32 v[34:35], v[34:35], v[34:35] op_sel:[0, 1] op_sel_hi:[1, 0]
	v_pk_add_f32 v[32:33], v[32:33], v[32:33] op_sel:[0, 1] op_sel_hi:[1, 0]
	v_pk_add_f32 v[40:41], v[40:41], v[44:45]
	v_pk_add_f32 v[42:43], v[42:43], v[42:43] op_sel:[0, 1] op_sel_hi:[1, 0]
	v_pk_add_f32 v[44:45], v[46:47], v[46:47] op_sel:[0, 1] op_sel_hi:[1, 0]
	v_mov_b32_e32 v53, v67
	v_mov_b32_e32 v57, v102
	v_mov_b32_e32 v35, v59
	v_mov_b32_e32 v33, v62
	v_mov_b32_e32 v43, v65
	v_mov_b32_e32 v45, v66
	v_pk_add_f32 v[46:47], v[52:53], v[56:57]
	v_pk_add_f32 v[32:33], v[34:35], v[32:33]
	v_pk_add_f32 v[34:35], v[42:43], v[44:45]
	v_pk_add_f32 v[32:33], v[32:33], v[40:41]
	v_pk_add_f32 v[34:35], v[34:35], v[46:47]
	v_mov_b32_e32 v41, v32
	v_mov_b32_e32 v40, v34
	v_mov_b32_e32 v32, v35
	v_pk_add_f32 v[32:33], v[40:41], v[32:33]
	v_lshl_add_u64 v[40:41], v[140:141], 0, s[50:51]
	v_lshl_add_u64 v[102:103], v[140:141], 0, s[52:53]
	global_load_dwordx4 v[64:67], v[40:41], off
	global_load_dwordx4 v[60:63], v[40:41], off offset:1024
	global_load_dwordx4 v[56:59], v[40:41], off offset:2048
	global_load_dwordx4 v[52:55], v[40:41], off offset:3072
	s_waitcnt lgkmcnt(0)
	s_nop 1
	v_add_f32_dpp v32, v32, v32 quad_perm:[1,0,3,2] row_mask:0xf bank_mask:0xf
	v_add_f32_dpp v33, v33, v33 quad_perm:[1,0,3,2] row_mask:0xf bank_mask:0xf
	s_waitcnt lgkmcnt(0)
	s_nop 1
	v_add_f32_dpp v32, v32, v32 quad_perm:[2,3,0,1] row_mask:0xf bank_mask:0xf
	v_add_f32_dpp v33, v33, v33 quad_perm:[2,3,0,1] row_mask:0xf bank_mask:0xf
	s_waitcnt lgkmcnt(0)
	s_nop 1
	v_add_f32_dpp v32, v32, v32 row_half_mirror row_mask:0xf bank_mask:0xf
	v_add_f32_dpp v33, v33, v33 row_half_mirror row_mask:0xf bank_mask:0xf
	s_waitcnt lgkmcnt(0)
	s_nop 1
	v_add_f32_dpp v32, v32, v32 row_mirror row_mask:0xf bank_mask:0xf
	v_add_f32_dpp v33, v33, v33 row_mirror row_mask:0xf bank_mask:0xf
	ds_bpermute_b32 v35, v188, v33
	ds_bpermute_b32 v34, v188, v32
	s_waitcnt lgkmcnt(0)
	v_pk_add_f32 v[32:33], v[32:33], v[34:35]
	s_waitcnt lgkmcnt(0)
	v_mov_b32_e32 v34, v32
	v_mov_b32_e32 v35, v33
	s_nop 1
	v_permlane32_swap_b32_e32 v34, v32
	v_permlane32_swap_b32_e32 v35, v33
	v_pk_add_f32 v[32:33], v[32:33], v[34:35]
	s_nop 0
	v_pk_fma_f32 v[106:107], v[32:33], s[28:29], v[84:85] op_sel_hi:[1, 0, 0]
	s_nop 0
	v_mul_f32_e32 v32, 0x4b800000, v107
	v_cmp_gt_f32_e32 vcc, s79, v107
	s_nop 1
	v_cndmask_b32_e32 v32, v107, v32, vcc
	v_rsq_f32_e32 v107, v32
	global_load_dwordx4 v[48:51], v[102:103], off
	global_load_dwordx4 v[44:47], v[102:103], off offset:1024
	global_load_dwordx4 v[40:43], v[102:103], off offset:2048
	global_load_dwordx4 v[32:35], v[102:103], off offset:3072
	v_mul_f32_e32 v102, 0x45800000, v107
	v_cndmask_b32_e32 v102, v107, v102, vcc
	v_pk_mul_f32 v[88:89], v[88:89], v[102:103] op_sel_hi:[1, 0]
	v_pk_mul_f32 v[86:87], v[86:87], v[102:103] op_sel_hi:[1, 0]
	v_pk_mul_f32 v[88:89], v[110:111], v[88:89]
	v_pk_mul_f32 v[86:87], v[108:109], v[86:87]
	v_pk_fma_f32 v[88:89], v[14:15], v[88:89], v[10:11]
	v_pk_fma_f32 v[86:87], v[12:13], v[86:87], v[8:9]
	v_pk_mul_f32 v[92:93], v[92:93], v[102:103] op_sel_hi:[1, 0]
	v_cvt_pk_bf16_f32 v86, v86, v87
	v_cvt_pk_bf16_f32 v87, v88, v89
	global_store_dwordx2 v[104:105], v[86:87], off
	v_pk_mul_f32 v[90:91], v[90:91], v[102:103] op_sel_hi:[1, 0]
	v_pk_mul_f32 v[82:83], v[82:83], v[102:103] op_sel_hi:[1, 0]
	v_pk_mul_f32 v[80:81], v[80:81], v[102:103] op_sel_hi:[1, 0]
	v_cmp_gt_f32_e32 vcc, s79, v106
	s_waitcnt vmcnt(5)
	v_mul_f32_e32 v99, v53, v53
	s_waitcnt vmcnt(2)
	v_mul_f32_e32 v98, v43, v43
	s_waitcnt vmcnt(1)
	v_mul_f32_e32 v104, v32, v32
	v_mul_f32_e32 v105, v33, v33
	v_mul_f32_e32 v107, v35, v35
	v_pk_mul_f32 v[86:87], v[112:113], v[90:91]
	v_pk_mul_f32 v[88:89], v[114:115], v[92:93]
	v_pk_fma_f32 v[86:87], v[20:21], v[86:87], v[16:17]
	v_pk_fma_f32 v[88:89], v[22:23], v[88:89], v[18:19]
	v_cvt_pk_bf16_f32 v86, v86, v87
	v_cvt_pk_bf16_f32 v87, v88, v89
	global_store_dwordx2 v200, v[86:87], s[48:49]
	v_pk_mul_f32 v[90:91], v[96:97], v[102:103] op_sel_hi:[1, 0]
	v_pk_mul_f32 v[92:93], v[94:95], v[102:103] op_sel_hi:[1, 0]
	v_pk_mul_f32 v[94:95], v[44:45], v[44:45]
	v_mul_f32_e32 v96, v41, v41
	v_mul_f32_e32 v102, v54, v54
	v_mul_f32_e32 v103, v55, v55
	v_pk_mul_f32 v[86:87], v[116:117], v[92:93]
	v_pk_mul_f32 v[88:89], v[118:119], v[90:91]
	v_pk_fma_f32 v[86:87], v[28:29], v[86:87], v[24:25]
	v_pk_fma_f32 v[88:89], v[30:31], v[88:89], v[26:27]
	v_cvt_pk_bf16_f32 v86, v86, v87
	v_cvt_pk_bf16_f32 v87, v88, v89
	global_store_dwordx2 v201, v[86:87], s[48:49]
	v_pk_mul_f32 v[90:91], v[48:49], v[48:49]
	v_pk_mul_f32 v[92:93], v[46:47], v[46:47]
	v_pk_mul_f32 v[80:81], v[120:121], v[80:81]
	v_pk_mul_f32 v[82:83], v[122:123], v[82:83]
	v_pk_fma_f32 v[80:81], v[4:5], v[80:81], v[0:1]
	v_pk_fma_f32 v[82:83], v[6:7], v[82:83], v[2:3]
	v_cvt_pk_bf16_f32 v80, v80, v81
	v_cvt_pk_bf16_f32 v81, v82, v83
	global_store_dwordx2 v210, v[80:81], s[48:49]
	v_mul_f32_e32 v86, 0x4b800000, v106
	v_cndmask_b32_e32 v86, v106, v86, vcc
	v_rsq_f32_e32 v88, v86
	v_lshl_add_u64 v[86:87], v[144:145], 0, s[46:47]
	s_add_u32 s46, s12, s46
	s_addc_u32 s47, s13, s47
	v_mul_f32_e32 v89, 0x45800000, v88
	v_cndmask_b32_e32 v88, v88, v89, vcc
	v_pk_mul_f32 v[78:79], v[78:79], v[88:89] op_sel_hi:[1, 0]
	v_pk_mul_f32 v[76:77], v[76:77], v[88:89] op_sel_hi:[1, 0]
	v_pk_mul_f32 v[74:75], v[74:75], v[88:89] op_sel_hi:[1, 0]
	v_pk_mul_f32 v[72:73], v[72:73], v[88:89] op_sel_hi:[1, 0]
	v_pk_mul_f32 v[70:71], v[70:71], v[88:89] op_sel_hi:[1, 0]
	v_pk_mul_f32 v[68:69], v[68:69], v[88:89] op_sel_hi:[1, 0]
	v_mul_f32_e32 v89, v52, v52
	v_pk_mul_f32 v[38:39], v[38:39], v[88:89] op_sel_hi:[1, 0]
	v_pk_mul_f32 v[36:37], v[36:37], v[88:89] op_sel_hi:[1, 0]
	v_mul_f32_e32 v106, v34, v34
	s_lshl_b64 s[44:45], s[44:45], 11
	v_pk_mul_f32 v[76:77], v[108:109], v[76:77]
	v_pk_mul_f32 v[78:79], v[110:111], v[78:79]
	v_pk_fma_f32 v[76:77], v[12:13], v[76:77], v[8:9]
	v_pk_fma_f32 v[78:79], v[14:15], v[78:79], v[10:11]
	v_cvt_pk_bf16_f32 v76, v76, v77
	v_cvt_pk_bf16_f32 v77, v78, v79
	global_store_dwordx2 v[86:87], v[76:77], off
	v_mul_f32_e32 v80, v57, v57
	v_mul_f32_e32 v82, v59, v59
	v_pk_mul_f32 v[86:87], v[50:51], v[50:51]
	v_pk_mul_f32 v[72:73], v[112:113], v[72:73]
	v_pk_mul_f32 v[74:75], v[114:115], v[74:75]
	v_pk_fma_f32 v[72:73], v[20:21], v[72:73], v[16:17]
	v_pk_fma_f32 v[74:75], v[22:23], v[74:75], v[18:19]
	v_cvt_pk_bf16_f32 v72, v72, v73
	v_cvt_pk_bf16_f32 v73, v74, v75
	global_store_dwordx2 v200, v[72:73], s[46:47]
	v_pk_mul_f32 v[76:77], v[62:63], v[62:63]
	v_pk_mul_f32 v[78:79], v[60:61], v[60:61]
	v_pk_mul_f32 v[68:69], v[116:117], v[68:69]
	v_pk_mul_f32 v[70:71], v[118:119], v[70:71]
	v_pk_fma_f32 v[68:69], v[28:29], v[68:69], v[24:25]
	v_pk_fma_f32 v[70:71], v[30:31], v[70:71], v[26:27]
	v_cvt_pk_bf16_f32 v68, v68, v69
	v_cvt_pk_bf16_f32 v69, v70, v71
	global_store_dwordx2 v201, v[68:69], s[46:47]
	v_pk_mul_f32 v[72:73], v[66:67], v[66:67]
	v_pk_mul_f32 v[74:75], v[64:65], v[64:65]
	v_pk_mul_f32 v[36:37], v[120:121], v[36:37]
	v_pk_mul_f32 v[38:39], v[122:123], v[38:39]
	v_pk_fma_f32 v[36:37], v[4:5], v[36:37], v[0:1]
	v_pk_fma_f32 v[38:39], v[6:7], v[38:39], v[2:3]
	v_cvt_pk_bf16_f32 v36, v36, v37
	v_cvt_pk_bf16_f32 v37, v38, v39
	global_store_dwordx2 v210, v[36:37], s[46:47]
	v_pk_mov_b32 v[100:101], v[74:75], v[72:73] op_sel:[1, 0]
	v_mov_b32_e32 v75, v73
	v_pk_mov_b32 v[72:73], v[78:79], v[76:77] op_sel:[1, 0]
	v_mov_b32_e32 v79, v77
	v_pk_fma_f32 v[76:77], v[56:57], v[56:57], v[80:81] op_sel_hi:[1, 1, 0]
	v_pk_fma_f32 v[80:81], v[58:59], v[58:59], v[82:83] op_sel_hi:[1, 1, 0]
	v_pk_mov_b32 v[82:83], v[90:91], v[86:87] op_sel:[1, 0]
	v_mov_b32_e32 v91, v87
	v_pk_mov_b32 v[86:87], v[94:95], v[92:93] op_sel:[1, 0]
	v_mov_b32_e32 v95, v93
	v_pk_add_f32 v[74:75], v[100:101], v[74:75]
	v_pk_add_f32 v[68:69], v[72:73], v[78:79]
	v_pk_add_f32 v[70:71], v[82:83], v[90:91]
	v_pk_add_f32 v[72:73], v[86:87], v[94:95]
	v_pk_fma_f32 v[92:93], v[40:41], v[40:41], v[96:97] op_sel_hi:[1, 1, 0]
	v_pk_fma_f32 v[96:97], v[42:43], v[42:43], v[98:99] op_sel_hi:[1, 1, 0]
	v_pk_add_f32 v[74:75], v[74:75], v[74:75] op_sel:[0, 1] op_sel_hi:[1, 0]
	v_pk_add_f32 v[68:69], v[68:69], v[68:69] op_sel:[0, 1] op_sel_hi:[1, 0]
	v_pk_add_f32 v[70:71], v[70:71], v[70:71] op_sel:[0, 1] op_sel_hi:[1, 0]
	v_pk_add_f32 v[72:73], v[72:73], v[72:73] op_sel:[0, 1] op_sel_hi:[1, 0]
	v_mov_b32_e32 v77, v102
	v_mov_b32_e32 v81, v103
	v_mov_b32_e32 v93, v106
	v_mov_b32_e32 v97, v107
	v_mov_b32_e32 v75, v89
	v_mov_b32_e32 v69, v99
	v_mov_b32_e32 v71, v104
	v_mov_b32_e32 v73, v105
	v_pk_add_f32 v[76:77], v[76:77], v[80:81]
	v_pk_add_f32 v[78:79], v[92:93], v[96:97]
	v_pk_add_f32 v[68:69], v[74:75], v[68:69]
	v_pk_add_f32 v[70:71], v[70:71], v[72:73]
	v_pk_add_f32 v[68:69], v[68:69], v[76:77]
	v_pk_add_f32 v[70:71], v[70:71], v[78:79]
	v_mov_b32_e32 v73, v68
	v_mov_b32_e32 v72, v70
	v_mov_b32_e32 v68, v71
	v_pk_add_f32 v[68:69], v[72:73], v[68:69]
	s_waitcnt lgkmcnt(0)
	s_nop 1
	v_add_f32_dpp v68, v68, v68 quad_perm:[1,0,3,2] row_mask:0xf bank_mask:0xf
	v_add_f32_dpp v69, v69, v69 quad_perm:[1,0,3,2] row_mask:0xf bank_mask:0xf
	s_waitcnt lgkmcnt(0)
	s_nop 1
	v_add_f32_dpp v68, v68, v68 quad_perm:[2,3,0,1] row_mask:0xf bank_mask:0xf
	v_add_f32_dpp v69, v69, v69 quad_perm:[2,3,0,1] row_mask:0xf bank_mask:0xf
	s_waitcnt lgkmcnt(0)
	s_nop 1
	v_add_f32_dpp v68, v68, v68 row_half_mirror row_mask:0xf bank_mask:0xf
	v_add_f32_dpp v69, v69, v69 row_half_mirror row_mask:0xf bank_mask:0xf
	s_waitcnt lgkmcnt(0)
	s_nop 1
	v_add_f32_dpp v68, v68, v68 row_mirror row_mask:0xf bank_mask:0xf
	v_add_f32_dpp v69, v69, v69 row_mirror row_mask:0xf bank_mask:0xf
	ds_bpermute_b32 v71, v188, v69
	ds_bpermute_b32 v70, v188, v68
	s_waitcnt lgkmcnt(0)
	v_pk_add_f32 v[68:69], v[68:69], v[70:71]
	s_waitcnt lgkmcnt(0)
	v_mov_b32_e32 v70, v68
	v_mov_b32_e32 v71, v69
	s_nop 1
	v_permlane32_swap_b32_e32 v70, v68
	v_permlane32_swap_b32_e32 v71, v69
	v_pk_add_f32 v[68:69], v[68:69], v[70:71]
	s_nop 0
	v_pk_fma_f32 v[68:69], v[68:69], s[28:29], v[84:85] op_sel_hi:[1, 0, 0]
	s_nop 0
	v_mul_f32_e32 v70, 0x4b800000, v69
	v_cmp_gt_f32_e32 vcc, s79, v69
	s_nop 1
	v_cndmask_b32_e32 v69, v69, v70, vcc
	v_rsq_f32_e32 v69, v69
	v_lshl_add_u64 v[70:71], v[144:145], 0, s[44:45]
	s_add_u32 s44, s12, s44
	s_addc_u32 s45, s13, s45
	v_mul_f32_e32 v72, 0x45800000, v69
	v_cndmask_b32_e32 v72, v69, v72, vcc
	v_pk_mul_f32 v[66:67], v[66:67], v[72:73] op_sel_hi:[1, 0]
	v_pk_mul_f32 v[64:65], v[64:65], v[72:73] op_sel_hi:[1, 0]
	v_pk_mul_f32 v[38:39], v[110:111], v[66:67]
	v_pk_mul_f32 v[36:37], v[108:109], v[64:65]
	v_pk_fma_f32 v[38:39], v[14:15], v[38:39], v[10:11]
	v_pk_fma_f32 v[36:37], v[12:13], v[36:37], v[8:9]
	v_pk_mul_f32 v[62:63], v[62:63], v[72:73] op_sel_hi:[1, 0]
	v_cvt_pk_bf16_f32 v36, v36, v37
	v_cvt_pk_bf16_f32 v37, v38, v39
	global_store_dwordx2 v[70:71], v[36:37], off
	v_pk_mul_f32 v[60:61], v[60:61], v[72:73] op_sel_hi:[1, 0]
	v_pk_mul_f32 v[58:59], v[58:59], v[72:73] op_sel_hi:[1, 0]
	v_pk_mul_f32 v[56:57], v[56:57], v[72:73] op_sel_hi:[1, 0]
	v_pk_mul_f32 v[54:55], v[54:55], v[72:73] op_sel_hi:[1, 0]
	v_pk_mul_f32 v[52:53], v[52:53], v[72:73] op_sel_hi:[1, 0]
	v_cmp_gt_f32_e32 vcc, s79, v68
	s_lshl_b64 s[42:43], s[42:43], 11
	v_pk_mul_f32 v[36:37], v[112:113], v[60:61]
	v_pk_mul_f32 v[38:39], v[114:115], v[62:63]
	v_pk_fma_f32 v[36:37], v[20:21], v[36:37], v[16:17]
	v_pk_fma_f32 v[38:39], v[22:23], v[38:39], v[18:19]
	v_cvt_pk_bf16_f32 v36, v36, v37
	v_cvt_pk_bf16_f32 v37, v38, v39
	global_store_dwordx2 v200, v[36:37], s[44:45]
	v_pk_mul_f32 v[36:37], v[116:117], v[56:57]
	v_pk_mul_f32 v[38:39], v[118:119], v[58:59]
	v_pk_fma_f32 v[36:37], v[28:29], v[36:37], v[24:25]
	v_pk_fma_f32 v[38:39], v[30:31], v[38:39], v[26:27]
	v_cvt_pk_bf16_f32 v36, v36, v37
	v_cvt_pk_bf16_f32 v37, v38, v39
	global_store_dwordx2 v201, v[36:37], s[44:45]
	v_pk_mul_f32 v[36:37], v[120:121], v[52:53]
	v_pk_mul_f32 v[38:39], v[122:123], v[54:55]
	v_pk_fma_f32 v[36:37], v[4:5], v[36:37], v[0:1]
	v_pk_fma_f32 v[38:39], v[6:7], v[38:39], v[2:3]
	v_cvt_pk_bf16_f32 v36, v36, v37
	v_cvt_pk_bf16_f32 v37, v38, v39
	global_store_dwordx2 v210, v[36:37], s[44:45]
	v_mul_f32_e32 v52, 0x4b800000, v68
	v_cndmask_b32_e32 v52, v68, v52, vcc
	v_rsq_f32_e32 v54, v52
	v_lshl_add_u64 v[52:53], v[144:145], 0, s[42:43]
	s_add_u32 s42, s12, s42
	s_addc_u32 s43, s13, s43
	v_mul_f32_e32 v55, 0x45800000, v54
	v_cndmask_b32_e32 v54, v54, v55, vcc
	v_pk_mul_f32 v[50:51], v[50:51], v[54:55] op_sel_hi:[1, 0]
	v_pk_mul_f32 v[48:49], v[48:49], v[54:55] op_sel_hi:[1, 0]
	s_andn2_b64 vcc, exec, s[8:9]
	s_mov_b64 s[8:9], -1
	v_pk_mul_f32 v[36:37], v[108:109], v[48:49]
	v_pk_mul_f32 v[38:39], v[110:111], v[50:51]
	v_pk_fma_f32 v[8:9], v[12:13], v[36:37], v[8:9]
	v_pk_fma_f32 v[10:11], v[14:15], v[38:39], v[10:11]
	v_cvt_pk_bf16_f32 v8, v8, v9
	v_cvt_pk_bf16_f32 v9, v10, v11
	global_store_dwordx2 v[52:53], v[8:9], off
	v_pk_mul_f32 v[12:13], v[46:47], v[54:55] op_sel_hi:[1, 0]
	v_pk_mul_f32 v[14:15], v[44:45], v[54:55] op_sel_hi:[1, 0]
	v_pk_mul_f32 v[10:11], v[114:115], v[12:13]
	v_pk_mul_f32 v[8:9], v[112:113], v[14:15]
	v_pk_fma_f32 v[10:11], v[22:23], v[10:11], v[18:19]
	v_pk_fma_f32 v[8:9], v[20:21], v[8:9], v[16:17]
	v_pk_mul_f32 v[12:13], v[42:43], v[54:55] op_sel_hi:[1, 0]
	v_cvt_pk_bf16_f32 v8, v8, v9
	v_cvt_pk_bf16_f32 v9, v10, v11
	global_store_dwordx2 v200, v[8:9], s[42:43]
	v_pk_mul_f32 v[14:15], v[40:41], v[54:55] op_sel_hi:[1, 0]
	v_pk_mul_f32 v[10:11], v[118:119], v[12:13]
	v_pk_mul_f32 v[8:9], v[116:117], v[14:15]
	v_pk_fma_f32 v[10:11], v[30:31], v[10:11], v[26:27]
	v_pk_fma_f32 v[8:9], v[28:29], v[8:9], v[24:25]
	v_pk_mul_f32 v[12:13], v[34:35], v[54:55] op_sel_hi:[1, 0]
	v_cvt_pk_bf16_f32 v8, v8, v9
	v_cvt_pk_bf16_f32 v9, v10, v11
	global_store_dwordx2 v201, v[8:9], s[42:43]
	v_pk_mul_f32 v[14:15], v[32:33], v[54:55] op_sel_hi:[1, 0]
	v_pk_mul_f32 v[10:11], v[122:123], v[12:13]
	v_pk_mul_f32 v[8:9], v[120:121], v[14:15]
	v_pk_fma_f32 v[2:3], v[6:7], v[10:11], v[2:3]
	v_pk_fma_f32 v[0:1], v[4:5], v[8:9], v[0:1]
	s_nop 0
	v_cvt_pk_bf16_f32 v0, v0, v1
	v_cvt_pk_bf16_f32 v1, v2, v3
	global_store_dwordx2 v210, v[0:1], s[42:43]
	s_cbranch_vccnz .LBB0_2350
	s_andn2_b64 vcc, exec, s[10:11]
	s_cbranch_vccnz .LBB0_2349
	s_barrier
	s_branch .LBB0_2349

.LBB0_2536:
	s_or_b64 exec, exec, s[30:31]
	s_lshl_b32 s30, s60, 6
	s_ashr_i32 s31, s63, 3
	s_add_i32 s30, s62, s30
	s_and_b32 s31, s31, -8
	s_add_i32 s30, s30, s31
	s_ashr_i32 s31, s30, 31
	s_lshl_b64 s[34:35], s[30:31], 12
	v_lshl_add_u64 v[16:17], v[132:133], 0, s[34:35]
	s_barrier
	global_load_dwordx4 v[18:21], v[16:17], off
	global_load_dwordx4 v[30:33], v[16:17], off offset:1024
	global_load_dwordx4 v[34:37], v[16:17], off offset:3072
	global_load_dwordx4 v[38:41], v[16:17], off offset:2048
	s_or_b32 s34, s30, 1
	s_ashr_i32 s35, s34, 31
	s_lshl_b64 s[34:35], s[34:35], 12
	v_lshl_add_u64 v[28:29], v[132:133], 0, s[34:35]
	global_load_dwordx4 v[8:11], v[28:29], off
	global_load_dwordx4 v[0:3], v[28:29], off offset:1024
	global_load_dwordx4 v[4:7], v[28:29], off offset:3072
	global_load_dwordx4 v[12:15], v[28:29], off offset:2048
	global_load_dwordx4 v[42:45], v[134:135], off
	s_or_b32 s34, s30, 2
	s_ashr_i32 s35, s34, 31
	s_lshl_b64 s[34:35], s[34:35], 12
	s_waitcnt vmcnt(8)
	v_pk_mul_f32 v[22:23], v[20:21], v[20:21]
	v_pk_mul_f32 v[24:25], v[18:19], v[18:19]
	s_waitcnt vmcnt(7)
	v_pk_mul_f32 v[26:27], v[32:33], v[32:33]
	v_pk_mul_f32 v[46:47], v[30:31], v[30:31]
	s_waitcnt vmcnt(5)
	v_mul_f32_e32 v48, v39, v39
	v_mul_f32_e32 v50, v41, v41
	v_mul_f32_e32 v64, v36, v36
	v_mul_f32_e32 v65, v37, v37
	v_pk_mov_b32 v[52:53], v[24:25], v[22:23] op_sel:[1,0]
	v_mov_b32_e32 v25, v23
	v_pk_mov_b32 v[22:23], v[46:47], v[26:27] op_sel:[1,0]
	v_mov_b32_e32 v47, v27
	v_pk_fma_f32 v[26:27], v[38:39], v[38:39], v[48:49] op_sel_hi:[1,1,0]
	v_pk_fma_f32 v[48:49], v[40:41], v[40:41], v[50:51] op_sel_hi:[1,1,0]
	s_waitcnt vmcnt(4)
	v_pk_mul_f32 v[50:51], v[10:11], v[10:11]
	v_pk_mul_f32 v[54:55], v[8:9], v[8:9]
	s_waitcnt vmcnt(3)
	v_pk_mul_f32 v[56:57], v[2:3], v[2:3]
	v_pk_mul_f32 v[58:59], v[0:1], v[0:1]
	v_pk_add_f32 v[22:23], v[22:23], v[46:47]
	v_mov_b32_e32 v27, v64
	v_mov_b32_e32 v49, v65
	v_pk_mov_b32 v[46:47], v[54:55], v[50:51] op_sel:[1,0]
	v_mov_b32_e32 v55, v51
	v_pk_mov_b32 v[50:51], v[58:59], v[56:57] op_sel:[1,0]
	v_mov_b32_e32 v59, v57
	v_mul_f32_e32 v61, v34, v34
	v_mul_f32_e32 v63, v35, v35
	s_waitcnt vmcnt(1)
	v_mul_f32_e32 v60, v13, v13
	v_mul_f32_e32 v62, v15, v15
	v_pk_add_f32 v[24:25], v[52:53], v[24:25]
	v_pk_add_f32 v[26:27], v[26:27], v[48:49]
	v_pk_add_f32 v[46:47], v[46:47], v[54:55]
	v_pk_add_f32 v[48:49], v[50:51], v[58:59]
	v_mul_f32_e32 v66, v4, v4
	v_mul_f32_e32 v67, v5, v5
	v_mul_f32_e32 v68, v6, v6
	v_mul_f32_e32 v69, v7, v7
	v_pk_fma_f32 v[52:53], v[12:13], v[12:13], v[60:61] op_sel_hi:[1,1,0]
	v_pk_fma_f32 v[56:57], v[14:15], v[14:15], v[62:63] op_sel_hi:[1,1,0]
	v_pk_add_f32 v[24:25], v[24:25], v[24:25] op_sel:[0,1] op_sel_hi:[1,0]
	v_pk_add_f32 v[22:23], v[22:23], v[22:23] op_sel:[0,1] op_sel_hi:[1,0]
	v_pk_add_f32 v[46:47], v[46:47], v[46:47] op_sel:[0,1] op_sel_hi:[1,0]
	v_pk_add_f32 v[48:49], v[48:49], v[48:49] op_sel:[0,1] op_sel_hi:[1,0]
	v_mov_b32_e32 v53, v68
	v_mov_b32_e32 v57, v69
	v_mov_b32_e32 v25, v61
	v_mov_b32_e32 v23, v63
	v_mov_b32_e32 v47, v66
	v_mov_b32_e32 v49, v67
	v_pk_add_f32 v[50:51], v[52:53], v[56:57]
	v_pk_add_f32 v[22:23], v[24:25], v[22:23]
	v_pk_add_f32 v[24:25], v[46:47], v[48:49]
	v_pk_add_f32 v[22:23], v[22:23], v[26:27]
	v_pk_add_f32 v[24:25], v[24:25], v[50:51]
	v_mov_b32_e32 v27, v22
	v_mov_b32_e32 v26, v24
	v_mov_b32_e32 v22, v25
	v_pk_add_f32 v[22:23], v[26:27], v[22:23]
	v_lshl_add_u64 v[52:53], v[132:133], 0, s[34:35]
	s_or_b32 s34, s30, 3
	s_ashr_i32 s35, s34, 31
	s_lshl_b64 s[34:35], s[34:35], 12
	s_waitcnt lgkmcnt(0)
	s_nop 1
	v_add_f32_dpp v22, v22, v22 quad_perm:[1,0,3,2] row_mask:0xf bank_mask:0xf
	v_add_f32_dpp v23, v23, v23 quad_perm:[1,0,3,2] row_mask:0xf bank_mask:0xf
	s_waitcnt lgkmcnt(0)
	s_nop 1
	v_add_f32_dpp v22, v22, v22 quad_perm:[2,3,0,1] row_mask:0xf bank_mask:0xf
	v_add_f32_dpp v23, v23, v23 quad_perm:[2,3,0,1] row_mask:0xf bank_mask:0xf
	s_waitcnt lgkmcnt(0)
	s_nop 1
	v_add_f32_dpp v22, v22, v22 row_half_mirror row_mask:0xf bank_mask:0xf
	v_add_f32_dpp v23, v23, v23 row_half_mirror row_mask:0xf bank_mask:0xf
	s_waitcnt lgkmcnt(0)
	s_nop 1
	v_add_f32_dpp v22, v22, v22 row_mirror row_mask:0xf bank_mask:0xf
	v_add_f32_dpp v23, v23, v23 row_mirror row_mask:0xf bank_mask:0xf
	ds_bpermute_b32 v25, v175, v23
	ds_bpermute_b32 v24, v175, v22
	s_waitcnt lgkmcnt(0)
	v_pk_add_f32 v[22:23], v[22:23], v[24:25]
	v_mov_b64_e32 v[24:25], s[26:27]
	s_waitcnt lgkmcnt(0)
	v_mov_b32_e32 v26, v22
	v_mov_b32_e32 v27, v23
	s_nop 1
	v_permlane32_swap_b32_e32 v26, v22
	v_permlane32_swap_b32_e32 v27, v23
	v_pk_add_f32 v[22:23], v[22:23], v[26:27]
	s_nop 0
	v_pk_fma_f32 v[22:23], v[22:23], s[24:25], v[24:25] op_sel_hi:[1,0,0]
	s_nop 0
	v_mul_f32_e32 v26, 0x4b800000, v23
	v_cmp_gt_f32_e32 vcc, s57, v23
	s_nop 1
	v_cndmask_b32_e32 v23, v23, v26, vcc
	v_rsq_f32_e32 v23, v23
	s_nop 0
	v_mul_f32_e32 v26, 0x45800000, v23
	v_cndmask_b32_e32 v26, v23, v26, vcc
	v_pk_mul_f32 v[18:19], v[18:19], v[26:27] op_sel_hi:[1,0]
	v_pk_mul_f32 v[20:21], v[20:21], v[26:27] op_sel_hi:[1,0]
	s_waitcnt vmcnt(0)
	v_pk_mul_f32 v[18:19], v[42:43], v[18:19]
	v_pk_mul_f32 v[20:21], v[44:45], v[20:21]
	global_store_dwordx4 v[16:17], v[18:21], off
	global_load_dwordx4 v[18:21], v[134:135], off offset:1024
	v_pk_mul_f32 v[32:33], v[32:33], v[26:27] op_sel_hi:[1,0]
	v_pk_mul_f32 v[30:31], v[30:31], v[26:27] op_sel_hi:[1,0]
	v_cmp_gt_f32_e32 vcc, s57, v22
	s_waitcnt vmcnt(0)
	v_pk_mul_f32 v[18:19], v[18:19], v[30:31]
	v_pk_mul_f32 v[20:21], v[20:21], v[32:33]
	global_store_dwordx4 v[16:17], v[18:21], off offset:1024
	global_load_dwordx4 v[18:21], v[134:135], off offset:2048
	v_pk_mul_f32 v[30:31], v[40:41], v[26:27] op_sel_hi:[1,0]
	v_pk_mul_f32 v[32:33], v[38:39], v[26:27] op_sel_hi:[1,0]
	s_waitcnt vmcnt(0)
	v_pk_mul_f32 v[20:21], v[20:21], v[30:31]
	v_pk_mul_f32 v[18:19], v[18:19], v[32:33]
	global_store_dwordx4 v[16:17], v[18:21], off offset:2048
	global_load_dwordx4 v[18:21], v[134:135], off offset:3072
	v_pk_mul_f32 v[30:31], v[36:37], v[26:27] op_sel_hi:[1,0]
	v_pk_mul_f32 v[26:27], v[34:35], v[26:27] op_sel_hi:[1,0]
	s_waitcnt vmcnt(0)
	v_pk_mul_f32 v[20:21], v[20:21], v[30:31]
	v_pk_mul_f32 v[18:19], v[18:19], v[26:27]
	global_store_dwordx4 v[16:17], v[18:21], off offset:3072
	global_load_dwordx4 v[16:19], v[134:135], off
	v_lshl_add_u64 v[26:27], v[132:133], 0, s[34:35]
	v_mul_f32_e32 v20, 0x4b800000, v22
	v_cndmask_b32_e32 v20, v22, v20, vcc
	v_rsq_f32_e32 v20, v20
	s_or_b32 s34, s30, 4
	s_ashr_i32 s35, s34, 31
	s_lshl_b64 s[34:35], s[34:35], 12
	v_mul_f32_e32 v21, 0x45800000, v20
	v_cndmask_b32_e32 v50, v20, v21, vcc
	v_pk_mul_f32 v[10:11], v[10:11], v[50:51] op_sel_hi:[1,0]
	v_pk_mul_f32 v[8:9], v[8:9], v[50:51] op_sel_hi:[1,0]
	v_pk_mul_f32 v[2:3], v[2:3], v[50:51] op_sel_hi:[1,0]
	v_pk_mul_f32 v[0:1], v[0:1], v[50:51] op_sel_hi:[1,0]
	v_pk_mul_f32 v[14:15], v[14:15], v[50:51] op_sel_hi:[1,0]
	v_pk_mul_f32 v[12:13], v[12:13], v[50:51] op_sel_hi:[1,0]
	s_waitcnt vmcnt(0)
	v_pk_mul_f32 v[8:9], v[16:17], v[8:9]
	v_pk_mul_f32 v[10:11], v[18:19], v[10:11]
	global_store_dwordx4 v[28:29], v[8:11], off
	global_load_dwordx4 v[8:11], v[134:135], off offset:1024
	s_waitcnt vmcnt(0)
	v_pk_mul_f32 v[0:1], v[8:9], v[0:1]
	v_pk_mul_f32 v[2:3], v[10:11], v[2:3]
	global_store_dwordx4 v[28:29], v[0:3], off offset:1024
	global_load_dwordx4 v[30:33], v[134:135], off offset:2048
	global_load_dwordx4 v[34:37], v[52:53], off
	global_load_dwordx4 v[38:41], v[52:53], off offset:1024
	global_load_dwordx4 v[42:45], v[52:53], off offset:3072
	global_load_dwordx4 v[46:49], v[52:53], off offset:2048
	global_load_dwordx4 v[20:23], v[26:27], off
	global_load_dwordx4 v[16:19], v[26:27], off offset:1024
	global_load_dwordx4 v[0:3], v[26:27], off offset:3072
	global_load_dwordx4 v[8:11], v[26:27], off offset:2048
	s_waitcnt vmcnt(3)
	v_pk_mul_f32 v[62:63], v[22:23], v[22:23]
	v_pk_mul_f32 v[12:13], v[30:31], v[12:13]
	v_pk_mul_f32 v[14:15], v[32:33], v[14:15]
	global_store_dwordx4 v[28:29], v[12:15], off offset:2048
	global_load_dwordx4 v[12:15], v[134:135], off offset:3072
	v_mul_f32_e32 v51, v44, v44
	v_pk_mul_f32 v[6:7], v[6:7], v[50:51] op_sel_hi:[1,0]
	v_pk_mul_f32 v[4:5], v[4:5], v[50:51] op_sel_hi:[1,0]
	v_pk_mul_f32 v[30:31], v[36:37], v[36:37]
	v_pk_mul_f32 v[32:33], v[34:35], v[34:35]
	v_pk_mul_f32 v[54:55], v[40:41], v[40:41]
	v_pk_mul_f32 v[56:57], v[38:39], v[38:39]
	v_mul_f32_e32 v58, v47, v47
	v_mul_f32_e32 v60, v49, v49
	v_pk_mul_f32 v[64:65], v[20:21], v[20:21]
	s_waitcnt vmcnt(4)
	v_pk_mul_f32 v[66:67], v[18:19], v[18:19]
	v_pk_mul_f32 v[68:69], v[16:17], v[16:17]
	v_pk_mov_b32 v[74:75], v[32:33], v[30:31] op_sel:[1,0]
	v_mov_b32_e32 v33, v31
	v_pk_mov_b32 v[30:31], v[56:57], v[54:55] op_sel:[1,0]
	v_mov_b32_e32 v57, v55
	v_pk_fma_f32 v[54:55], v[46:47], v[46:47], v[58:59] op_sel_hi:[1,1,0]
	v_pk_fma_f32 v[58:59], v[48:49], v[48:49], v[60:61] op_sel_hi:[1,1,0]
	v_pk_mov_b32 v[60:61], v[64:65], v[62:63] op_sel:[1,0]
	v_mov_b32_e32 v65, v63
	v_pk_mov_b32 v[62:63], v[68:69], v[66:67] op_sel:[1,0]
	v_mov_b32_e32 v69, v67
	v_mul_f32_e32 v73, v42, v42
	s_waitcnt vmcnt(2)
	v_mul_f32_e32 v70, v9, v9
	v_mul_f32_e32 v72, v11, v11
	v_pk_add_f32 v[32:33], v[74:75], v[32:33]
	v_mul_f32_e32 v76, v43, v43
	v_mul_f32_e32 v77, v45, v45
	v_mul_f32_e32 v78, v0, v0
	v_mul_f32_e32 v79, v1, v1
	v_mul_f32_e32 v80, v2, v2
	v_mul_f32_e32 v81, v3, v3
	v_pk_fma_f32 v[66:67], v[8:9], v[8:9], v[70:71] op_sel_hi:[1,1,0]
	v_pk_fma_f32 v[70:71], v[10:11], v[10:11], v[72:73] op_sel_hi:[1,1,0]
	v_mov_b32_e32 v55, v51
	v_mov_b32_e32 v59, v77
	v_mov_b32_e32 v67, v80
	v_mov_b32_e32 v71, v81
	v_pk_add_f32 v[50:51], v[66:67], v[70:71]
	s_waitcnt vmcnt(0)
	v_pk_mul_f32 v[4:5], v[12:13], v[4:5]
	v_pk_mul_f32 v[6:7], v[14:15], v[6:7]
	global_store_dwordx4 v[28:29], v[4:7], off offset:3072
	global_load_dwordx4 v[4:7], v[134:135], off
	v_pk_add_f32 v[12:13], v[30:31], v[56:57]
	v_pk_add_f32 v[14:15], v[60:61], v[64:65]
	v_pk_add_f32 v[28:29], v[62:63], v[68:69]
	v_pk_add_f32 v[30:31], v[32:33], v[32:33] op_sel:[0,1] op_sel_hi:[1,0]
	v_pk_add_f32 v[12:13], v[12:13], v[12:13] op_sel:[0,1] op_sel_hi:[1,0]
	v_pk_add_f32 v[14:15], v[14:15], v[14:15] op_sel:[0,1] op_sel_hi:[1,0]
	v_pk_add_f32 v[28:29], v[28:29], v[28:29] op_sel:[0,1] op_sel_hi:[1,0]
	v_mov_b32_e32 v31, v73
	v_mov_b32_e32 v13, v76
	v_mov_b32_e32 v15, v78
	v_mov_b32_e32 v29, v79
	v_pk_add_f32 v[32:33], v[54:55], v[58:59]
	v_pk_add_f32 v[12:13], v[30:31], v[12:13]
	v_pk_add_f32 v[14:15], v[14:15], v[28:29]
	v_pk_add_f32 v[12:13], v[12:13], v[32:33]
	v_pk_add_f32 v[14:15], v[14:15], v[50:51]
	v_mov_b32_e32 v29, v12
	v_mov_b32_e32 v28, v14
	v_mov_b32_e32 v12, v15
	v_pk_add_f32 v[12:13], v[28:29], v[12:13]
	s_waitcnt lgkmcnt(0)
	s_nop 1
	v_add_f32_dpp v12, v12, v12 quad_perm:[1,0,3,2] row_mask:0xf bank_mask:0xf
	v_add_f32_dpp v13, v13, v13 quad_perm:[1,0,3,2] row_mask:0xf bank_mask:0xf
	s_waitcnt lgkmcnt(0)
	s_nop 1
	v_add_f32_dpp v12, v12, v12 quad_perm:[2,3,0,1] row_mask:0xf bank_mask:0xf
	v_add_f32_dpp v13, v13, v13 quad_perm:[2,3,0,1] row_mask:0xf bank_mask:0xf
	s_waitcnt lgkmcnt(0)
	s_nop 1
	v_add_f32_dpp v12, v12, v12 row_half_mirror row_mask:0xf bank_mask:0xf
	v_add_f32_dpp v13, v13, v13 row_half_mirror row_mask:0xf bank_mask:0xf
	s_waitcnt lgkmcnt(0)
	s_nop 1
	v_add_f32_dpp v12, v12, v12 row_mirror row_mask:0xf bank_mask:0xf
	v_add_f32_dpp v13, v13, v13 row_mirror row_mask:0xf bank_mask:0xf
	ds_bpermute_b32 v15, v175, v13
	ds_bpermute_b32 v14, v175, v12
	s_waitcnt lgkmcnt(0)
	v_pk_add_f32 v[12:13], v[12:13], v[14:15]
	s_waitcnt lgkmcnt(0)
	v_mov_b32_e32 v14, v12
	v_mov_b32_e32 v15, v13
	s_nop 1
	v_permlane32_swap_b32_e32 v14, v12
	v_permlane32_swap_b32_e32 v15, v13
	v_pk_add_f32 v[12:13], v[12:13], v[14:15]
	s_nop 0
	v_pk_fma_f32 v[12:13], v[12:13], s[24:25], v[24:25] op_sel_hi:[1,0,0]
	s_nop 0
	v_mul_f32_e32 v14, 0x4b800000, v13
	v_cmp_gt_f32_e32 vcc, s57, v13
	s_nop 1
	v_cndmask_b32_e32 v13, v13, v14, vcc
	v_rsq_f32_e32 v13, v13
	s_nop 0
	v_mul_f32_e32 v14, 0x45800000, v13
	v_cndmask_b32_e32 v14, v13, v14, vcc
	v_pk_mul_f32 v[28:29], v[36:37], v[14:15] op_sel_hi:[1,0]
	v_pk_mul_f32 v[30:31], v[34:35], v[14:15] op_sel_hi:[1,0]
	v_mul_f32_e32 v13, 0x4b800000, v12
	v_cmp_gt_f32_e32 vcc, s57, v12
	s_waitcnt vmcnt(0)
	v_pk_mul_f32 v[4:5], v[4:5], v[30:31]
	v_pk_mul_f32 v[6:7], v[6:7], v[28:29]
	global_store_dwordx4 v[52:53], v[4:7], off
	global_load_dwordx4 v[4:7], v[134:135], off offset:1024
	v_pk_mul_f32 v[28:29], v[40:41], v[14:15] op_sel_hi:[1,0]
	v_pk_mul_f32 v[30:31], v[38:39], v[14:15] op_sel_hi:[1,0]
	v_cndmask_b32_e32 v12, v12, v13, vcc
	v_rsq_f32_e32 v12, v12
	s_waitcnt vmcnt(0)
	v_pk_mul_f32 v[4:5], v[4:5], v[30:31]
	v_pk_mul_f32 v[6:7], v[6:7], v[28:29]
	global_store_dwordx4 v[52:53], v[4:7], off offset:1024
	global_load_dwordx4 v[4:7], v[134:135], off offset:2048
	v_pk_mul_f32 v[28:29], v[48:49], v[14:15] op_sel_hi:[1,0]
	v_pk_mul_f32 v[30:31], v[46:47], v[14:15] op_sel_hi:[1,0]
	v_mul_f32_e32 v13, 0x45800000, v12
	s_waitcnt vmcnt(0)
	v_pk_mul_f32 v[4:5], v[4:5], v[30:31]
	v_pk_mul_f32 v[6:7], v[6:7], v[28:29]
	global_store_dwordx4 v[52:53], v[4:7], off offset:2048
	global_load_dwordx4 v[4:7], v[134:135], off offset:3072
	v_pk_mul_f32 v[28:29], v[44:45], v[14:15] op_sel_hi:[1,0]
	v_pk_mul_f32 v[14:15], v[42:43], v[14:15] op_sel_hi:[1,0]
	v_lshl_add_u64 v[30:31], v[132:133], 0, s[34:35]
	s_or_b32 s34, s30, 5
	s_ashr_i32 s35, s34, 31
	s_lshl_b64 s[34:35], s[34:35], 12
	s_waitcnt vmcnt(0)
	v_pk_mul_f32 v[4:5], v[4:5], v[14:15]
	v_pk_mul_f32 v[6:7], v[6:7], v[28:29]
	global_store_dwordx4 v[52:53], v[4:7], off offset:3072
	global_load_dwordx4 v[4:7], v[134:135], off
	v_cndmask_b32_e32 v52, v12, v13, vcc
	v_pk_mul_f32 v[12:13], v[22:23], v[52:53] op_sel_hi:[1,0]
	v_pk_mul_f32 v[14:15], v[20:21], v[52:53] op_sel_hi:[1,0]
	v_pk_mul_f32 v[10:11], v[10:11], v[52:53] op_sel_hi:[1,0]
	v_pk_mul_f32 v[8:9], v[8:9], v[52:53] op_sel_hi:[1,0]
	v_lshl_add_u64 v[28:29], v[132:133], 0, s[34:35]
	s_or_b32 s34, s30, 6
	s_or_b32 s30, s30, 7
	s_ashr_i32 s35, s34, 31
	s_ashr_i32 s31, s30, 31
	s_lshl_b64 s[34:35], s[34:35], 12
	s_lshl_b64 s[30:31], s[30:31], 12
	s_waitcnt vmcnt(0)
	v_pk_mul_f32 v[4:5], v[4:5], v[14:15]
	v_pk_mul_f32 v[6:7], v[6:7], v[12:13]
	global_store_dwordx4 v[26:27], v[4:7], off
	global_load_dwordx4 v[4:7], v[134:135], off offset:1024
	v_pk_mul_f32 v[12:13], v[18:19], v[52:53] op_sel_hi:[1,0]
	v_pk_mul_f32 v[14:15], v[16:17], v[52:53] op_sel_hi:[1,0]
	s_waitcnt vmcnt(0)
	v_pk_mul_f32 v[6:7], v[6:7], v[12:13]
	v_pk_mul_f32 v[4:5], v[4:5], v[14:15]
	global_store_dwordx4 v[26:27], v[4:7], off offset:1024
	global_load_dwordx4 v[32:35], v[134:135], off offset:2048
	global_load_dwordx4 v[36:39], v[30:31], off
	global_load_dwordx4 v[40:43], v[30:31], off offset:1024
	global_load_dwordx4 v[44:47], v[30:31], off offset:3072
	global_load_dwordx4 v[48:51], v[30:31], off offset:2048
	global_load_dwordx4 v[20:23], v[28:29], off
	global_load_dwordx4 v[16:19], v[28:29], off offset:1024
	global_load_dwordx4 v[4:7], v[28:29], off offset:3072
	global_load_dwordx4 v[12:15], v[28:29], off offset:2048
	s_waitcnt vmcnt(6)
	v_pk_mul_f32 v[54:55], v[42:43], v[42:43]
	v_pk_mul_f32 v[8:9], v[32:33], v[8:9]
	v_pk_mul_f32 v[10:11], v[34:35], v[10:11]
	global_store_dwordx4 v[26:27], v[8:11], off offset:2048
	global_load_dwordx4 v[8:11], v[134:135], off offset:3072
	s_waitcnt vmcnt(7)
	v_mul_f32_e32 v53, v46, v46
	v_pk_mul_f32 v[2:3], v[2:3], v[52:53] op_sel_hi:[1,0]
	v_pk_mul_f32 v[0:1], v[0:1], v[52:53] op_sel_hi:[1,0]
	v_pk_mul_f32 v[32:33], v[38:39], v[38:39]
	v_pk_mul_f32 v[34:35], v[36:37], v[36:37]
	v_pk_mul_f32 v[56:57], v[40:41], v[40:41]
	s_waitcnt vmcnt(6)
	v_mul_f32_e32 v58, v49, v49
	v_mul_f32_e32 v60, v51, v51
	s_waitcnt vmcnt(5)
	v_pk_mul_f32 v[62:63], v[22:23], v[22:23]
	v_pk_mul_f32 v[64:65], v[20:21], v[20:21]
	s_waitcnt vmcnt(4)
	v_pk_mul_f32 v[66:67], v[18:19], v[18:19]
	v_pk_mul_f32 v[68:69], v[16:17], v[16:17]
	v_pk_mov_b32 v[74:75], v[34:35], v[32:33] op_sel:[1,0]
	v_mov_b32_e32 v35, v33
	v_pk_mov_b32 v[32:33], v[56:57], v[54:55] op_sel:[1,0]
	v_mov_b32_e32 v57, v55
	v_pk_fma_f32 v[54:55], v[48:49], v[48:49], v[58:59] op_sel_hi:[1,1,0]
	v_pk_fma_f32 v[58:59], v[50:51], v[50:51], v[60:61] op_sel_hi:[1,1,0]
	v_pk_mov_b32 v[60:61], v[64:65], v[62:63] op_sel:[1,0]
	v_mov_b32_e32 v65, v63
	v_pk_mov_b32 v[62:63], v[68:69], v[66:67] op_sel:[1,0]
	v_mov_b32_e32 v69, v67
	v_mul_f32_e32 v73, v44, v44
	s_waitcnt vmcnt(2)
	v_mul_f32_e32 v70, v13, v13
	v_mul_f32_e32 v72, v15, v15
	v_pk_add_f32 v[34:35], v[74:75], v[34:35]
	v_mul_f32_e32 v76, v45, v45
	v_mul_f32_e32 v77, v47, v47
	v_mul_f32_e32 v78, v4, v4
	v_mul_f32_e32 v79, v5, v5
	v_mul_f32_e32 v80, v6, v6
	v_mul_f32_e32 v81, v7, v7
	v_pk_fma_f32 v[66:67], v[12:13], v[12:13], v[70:71] op_sel_hi:[1,1,0]
	v_pk_fma_f32 v[70:71], v[14:15], v[14:15], v[72:73] op_sel_hi:[1,1,0]
	v_mov_b32_e32 v55, v53
	v_mov_b32_e32 v59, v77
	v_mov_b32_e32 v67, v80
	v_mov_b32_e32 v71, v81
	v_pk_add_f32 v[52:53], v[66:67], v[70:71]
	s_waitcnt vmcnt(0)
	v_pk_mul_f32 v[0:1], v[8:9], v[0:1]
	v_pk_mul_f32 v[2:3], v[10:11], v[2:3]
	global_store_dwordx4 v[26:27], v[0:3], off offset:3072
	global_load_dwordx4 v[0:3], v[134:135], off
	v_pk_add_f32 v[8:9], v[32:33], v[56:57]
	v_pk_add_f32 v[10:11], v[60:61], v[64:65]
	v_pk_add_f32 v[26:27], v[62:63], v[68:69]
	v_pk_add_f32 v[32:33], v[34:35], v[34:35] op_sel:[0,1] op_sel_hi:[1,0]
	v_pk_add_f32 v[8:9], v[8:9], v[8:9] op_sel:[0,1] op_sel_hi:[1,0]
	v_pk_add_f32 v[10:11], v[10:11], v[10:11] op_sel:[0,1] op_sel_hi:[1,0]
	v_pk_add_f32 v[26:27], v[26:27], v[26:27] op_sel:[0,1] op_sel_hi:[1,0]
	v_mov_b32_e32 v33, v73
	v_mov_b32_e32 v9, v76
	v_mov_b32_e32 v11, v78
	v_mov_b32_e32 v27, v79
	v_pk_add_f32 v[34:35], v[54:55], v[58:59]
	v_pk_add_f32 v[8:9], v[32:33], v[8:9]
	v_pk_add_f32 v[10:11], v[10:11], v[26:27]
	v_pk_add_f32 v[8:9], v[8:9], v[34:35]
	v_pk_add_f32 v[10:11], v[10:11], v[52:53]
	v_mov_b32_e32 v27, v8
	v_mov_b32_e32 v26, v10
	v_mov_b32_e32 v8, v11
	v_pk_add_f32 v[8:9], v[26:27], v[8:9]
	v_lshl_add_u64 v[52:53], v[132:133], 0, s[34:35]
	s_waitcnt lgkmcnt(0)
	s_nop 1
	v_add_f32_dpp v8, v8, v8 quad_perm:[1,0,3,2] row_mask:0xf bank_mask:0xf
	v_add_f32_dpp v9, v9, v9 quad_perm:[1,0,3,2] row_mask:0xf bank_mask:0xf
	s_waitcnt lgkmcnt(0)
	s_nop 1
	v_add_f32_dpp v8, v8, v8 quad_perm:[2,3,0,1] row_mask:0xf bank_mask:0xf
	v_add_f32_dpp v9, v9, v9 quad_perm:[2,3,0,1] row_mask:0xf bank_mask:0xf
	s_waitcnt lgkmcnt(0)
	s_nop 1
	v_add_f32_dpp v8, v8, v8 row_half_mirror row_mask:0xf bank_mask:0xf
	v_add_f32_dpp v9, v9, v9 row_half_mirror row_mask:0xf bank_mask:0xf
	s_waitcnt lgkmcnt(0)
	s_nop 1
	v_add_f32_dpp v8, v8, v8 row_mirror row_mask:0xf bank_mask:0xf
	v_add_f32_dpp v9, v9, v9 row_mirror row_mask:0xf bank_mask:0xf
	ds_bpermute_b32 v11, v175, v9
	ds_bpermute_b32 v10, v175, v8
	s_waitcnt lgkmcnt(0)
	v_pk_add_f32 v[8:9], v[8:9], v[10:11]
	s_waitcnt lgkmcnt(0)
	v_mov_b32_e32 v10, v8
	v_mov_b32_e32 v11, v9
	s_nop 1
	v_permlane32_swap_b32_e32 v10, v8
	v_permlane32_swap_b32_e32 v11, v9
	v_pk_add_f32 v[8:9], v[8:9], v[10:11]
	s_nop 0
	v_pk_fma_f32 v[8:9], v[8:9], s[24:25], v[24:25] op_sel_hi:[1,0,0]
	s_nop 0
	v_mul_f32_e32 v10, 0x4b800000, v9
	v_cmp_gt_f32_e32 vcc, s57, v9
	s_nop 1
	v_cndmask_b32_e32 v9, v9, v10, vcc
	v_rsq_f32_e32 v9, v9
	s_nop 0
	v_mul_f32_e32 v10, 0x45800000, v9
	v_cndmask_b32_e32 v10, v9, v10, vcc
	v_pk_mul_f32 v[26:27], v[36:37], v[10:11] op_sel_hi:[1,0]
	v_pk_mul_f32 v[32:33], v[38:39], v[10:11] op_sel_hi:[1,0]
	v_mul_f32_e32 v9, 0x4b800000, v8
	v_cmp_gt_f32_e32 vcc, s57, v8
	s_waitcnt vmcnt(0)
	v_pk_mul_f32 v[2:3], v[2:3], v[32:33]
	v_pk_mul_f32 v[0:1], v[0:1], v[26:27]
	global_store_dwordx4 v[30:31], v[0:3], off
	global_load_dwordx4 v[0:3], v[134:135], off offset:1024
	v_pk_mul_f32 v[26:27], v[42:43], v[10:11] op_sel_hi:[1,0]
	v_pk_mul_f32 v[32:33], v[40:41], v[10:11] op_sel_hi:[1,0]
	v_cndmask_b32_e32 v8, v8, v9, vcc
	v_rsq_f32_e32 v8, v8
	s_waitcnt vmcnt(0)
	v_pk_mul_f32 v[0:1], v[0:1], v[32:33]
	v_pk_mul_f32 v[2:3], v[2:3], v[26:27]
	global_store_dwordx4 v[30:31], v[0:3], off offset:1024
	global_load_dwordx4 v[0:3], v[134:135], off offset:2048
	v_pk_mul_f32 v[26:27], v[50:51], v[10:11] op_sel_hi:[1,0]
	v_pk_mul_f32 v[32:33], v[48:49], v[10:11] op_sel_hi:[1,0]
	v_mul_f32_e32 v9, 0x45800000, v8
	v_cndmask_b32_e32 v50, v8, v9, vcc
	v_pk_mul_f32 v[8:9], v[22:23], v[50:51] op_sel_hi:[1,0]
	v_pk_mul_f32 v[14:15], v[14:15], v[50:51] op_sel_hi:[1,0]
	v_pk_mul_f32 v[12:13], v[12:13], v[50:51] op_sel_hi:[1,0]
	s_waitcnt vmcnt(0)
	v_pk_mul_f32 v[0:1], v[0:1], v[32:33]
	v_pk_mul_f32 v[2:3], v[2:3], v[26:27]
	global_store_dwordx4 v[30:31], v[0:3], off offset:2048
	global_load_dwordx4 v[0:3], v[134:135], off offset:3072
	v_pk_mul_f32 v[26:27], v[46:47], v[10:11] op_sel_hi:[1,0]
	v_pk_mul_f32 v[10:11], v[44:45], v[10:11] op_sel_hi:[1,0]
	s_waitcnt vmcnt(0)
	v_pk_mul_f32 v[2:3], v[2:3], v[26:27]
	v_pk_mul_f32 v[0:1], v[0:1], v[10:11]
	global_store_dwordx4 v[30:31], v[0:3], off offset:3072
	global_load_dwordx4 v[0:3], v[134:135], off
	v_pk_mul_f32 v[10:11], v[20:21], v[50:51] op_sel_hi:[1,0]
	v_lshl_add_u64 v[26:27], v[132:133], 0, s[30:31]
	s_waitcnt vmcnt(0)
	v_pk_mul_f32 v[0:1], v[0:1], v[10:11]
	v_pk_mul_f32 v[2:3], v[2:3], v[8:9]
	global_store_dwordx4 v[28:29], v[0:3], off
	global_load_dwordx4 v[0:3], v[134:135], off offset:1024
	v_pk_mul_f32 v[8:9], v[18:19], v[50:51] op_sel_hi:[1,0]
	v_pk_mul_f32 v[10:11], v[16:17], v[50:51] op_sel_hi:[1,0]
	s_waitcnt vmcnt(0)
	v_pk_mul_f32 v[2:3], v[2:3], v[8:9]
	v_pk_mul_f32 v[0:1], v[0:1], v[10:11]
	global_store_dwordx4 v[28:29], v[0:3], off offset:1024
	global_load_dwordx4 v[30:33], v[134:135], off offset:2048
	global_load_dwordx4 v[34:37], v[52:53], off
	global_load_dwordx4 v[38:41], v[52:53], off offset:1024
	global_load_dwordx4 v[42:45], v[52:53], off offset:3072
	global_load_dwordx4 v[46:49], v[52:53], off offset:2048
	global_load_dwordx4 v[20:23], v[26:27], off
	global_load_dwordx4 v[16:19], v[26:27], off offset:1024
	global_load_dwordx4 v[0:3], v[26:27], off offset:3072
	global_load_dwordx4 v[8:11], v[26:27], off offset:2048
	s_waitcnt vmcnt(6)
	v_pk_mul_f32 v[54:55], v[40:41], v[40:41]
	v_pk_mul_f32 v[12:13], v[30:31], v[12:13]
	v_pk_mul_f32 v[14:15], v[32:33], v[14:15]
	global_store_dwordx4 v[28:29], v[12:15], off offset:2048
	global_load_dwordx4 v[12:15], v[134:135], off offset:3072
	s_waitcnt vmcnt(7)
	v_mul_f32_e32 v51, v44, v44
	v_pk_mul_f32 v[6:7], v[6:7], v[50:51] op_sel_hi:[1,0]
	v_pk_mul_f32 v[4:5], v[4:5], v[50:51] op_sel_hi:[1,0]
	v_pk_mul_f32 v[30:31], v[36:37], v[36:37]
	v_pk_mul_f32 v[32:33], v[34:35], v[34:35]
	v_pk_mul_f32 v[56:57], v[38:39], v[38:39]
	s_waitcnt vmcnt(6)
	v_mul_f32_e32 v58, v47, v47
	v_mul_f32_e32 v60, v49, v49
	s_waitcnt vmcnt(5)
	v_pk_mul_f32 v[62:63], v[22:23], v[22:23]
	v_pk_mul_f32 v[64:65], v[20:21], v[20:21]
	s_waitcnt vmcnt(4)
	v_pk_mul_f32 v[66:67], v[18:19], v[18:19]
	v_pk_mul_f32 v[68:69], v[16:17], v[16:17]
	v_pk_mov_b32 v[74:75], v[32:33], v[30:31] op_sel:[1,0]
	v_mov_b32_e32 v33, v31
	v_pk_mov_b32 v[30:31], v[56:57], v[54:55] op_sel:[1,0]
	v_mov_b32_e32 v57, v55
	v_pk_fma_f32 v[54:55], v[46:47], v[46:47], v[58:59] op_sel_hi:[1,1,0]
	v_pk_fma_f32 v[58:59], v[48:49], v[48:49], v[60:61] op_sel_hi:[1,1,0]
	v_pk_mov_b32 v[60:61], v[64:65], v[62:63] op_sel:[1,0]
	v_mov_b32_e32 v65, v63
	v_pk_mov_b32 v[62:63], v[68:69], v[66:67] op_sel:[1,0]
	v_mov_b32_e32 v69, v67
	v_mul_f32_e32 v73, v42, v42
	s_waitcnt vmcnt(2)
	v_mul_f32_e32 v70, v9, v9
	v_mul_f32_e32 v72, v11, v11
	v_pk_add_f32 v[32:33], v[74:75], v[32:33]
	v_mul_f32_e32 v76, v43, v43
	v_mul_f32_e32 v77, v45, v45
	v_mul_f32_e32 v78, v0, v0
	v_mul_f32_e32 v79, v1, v1
	v_mul_f32_e32 v80, v2, v2
	v_mul_f32_e32 v81, v3, v3
	v_pk_fma_f32 v[66:67], v[8:9], v[8:9], v[70:71] op_sel_hi:[1,1,0]
	v_pk_fma_f32 v[70:71], v[10:11], v[10:11], v[72:73] op_sel_hi:[1,1,0]
	v_mov_b32_e32 v55, v51
	v_mov_b32_e32 v59, v77
	v_mov_b32_e32 v67, v80
	v_mov_b32_e32 v71, v81
	v_pk_add_f32 v[50:51], v[66:67], v[70:71]
	s_waitcnt vmcnt(0)
	v_pk_mul_f32 v[4:5], v[12:13], v[4:5]
	v_pk_mul_f32 v[6:7], v[14:15], v[6:7]
	global_store_dwordx4 v[28:29], v[4:7], off offset:3072
	global_load_dwordx4 v[4:7], v[134:135], off
	v_pk_add_f32 v[12:13], v[30:31], v[56:57]
	v_pk_add_f32 v[14:15], v[60:61], v[64:65]
	v_pk_add_f32 v[28:29], v[62:63], v[68:69]
	v_pk_add_f32 v[30:31], v[32:33], v[32:33] op_sel:[0,1] op_sel_hi:[1,0]
	v_pk_add_f32 v[12:13], v[12:13], v[12:13] op_sel:[0,1] op_sel_hi:[1,0]
	v_pk_add_f32 v[14:15], v[14:15], v[14:15] op_sel:[0,1] op_sel_hi:[1,0]
	v_pk_add_f32 v[28:29], v[28:29], v[28:29] op_sel:[0,1] op_sel_hi:[1,0]
	v_mov_b32_e32 v31, v73
	v_mov_b32_e32 v13, v76
	v_mov_b32_e32 v15, v78
	v_mov_b32_e32 v29, v79
	v_pk_add_f32 v[32:33], v[54:55], v[58:59]
	v_pk_add_f32 v[12:13], v[30:31], v[12:13]
	v_pk_add_f32 v[14:15], v[14:15], v[28:29]
	v_pk_add_f32 v[12:13], v[12:13], v[32:33]
	v_pk_add_f32 v[14:15], v[14:15], v[50:51]
	v_mov_b32_e32 v29, v12
	v_mov_b32_e32 v28, v14
	v_mov_b32_e32 v12, v15
	v_pk_add_f32 v[12:13], v[28:29], v[12:13]
	s_waitcnt lgkmcnt(0)
	s_nop 1
	v_add_f32_dpp v12, v12, v12 quad_perm:[1,0,3,2] row_mask:0xf bank_mask:0xf
	v_add_f32_dpp v13, v13, v13 quad_perm:[1,0,3,2] row_mask:0xf bank_mask:0xf
	s_waitcnt lgkmcnt(0)
	s_nop 1
	v_add_f32_dpp v12, v12, v12 quad_perm:[2,3,0,1] row_mask:0xf bank_mask:0xf
	v_add_f32_dpp v13, v13, v13 quad_perm:[2,3,0,1] row_mask:0xf bank_mask:0xf
	s_waitcnt lgkmcnt(0)
	s_nop 1
	v_add_f32_dpp v12, v12, v12 row_half_mirror row_mask:0xf bank_mask:0xf
	v_add_f32_dpp v13, v13, v13 row_half_mirror row_mask:0xf bank_mask:0xf
	s_waitcnt lgkmcnt(0)
	s_nop 1
	v_add_f32_dpp v12, v12, v12 row_mirror row_mask:0xf bank_mask:0xf
	v_add_f32_dpp v13, v13, v13 row_mirror row_mask:0xf bank_mask:0xf
	ds_bpermute_b32 v15, v175, v13
	ds_bpermute_b32 v14, v175, v12
	s_waitcnt lgkmcnt(0)
	v_pk_add_f32 v[12:13], v[12:13], v[14:15]
	s_waitcnt lgkmcnt(0)
	v_mov_b32_e32 v14, v12
	v_mov_b32_e32 v15, v13
	s_nop 1
	v_permlane32_swap_b32_e32 v14, v12
	v_permlane32_swap_b32_e32 v15, v13
	v_pk_add_f32 v[12:13], v[12:13], v[14:15]
	s_nop 0
	v_pk_fma_f32 v[12:13], v[12:13], s[24:25], v[24:25] op_sel_hi:[1,0,0]
	s_nop 0
	v_mul_f32_e32 v14, 0x4b800000, v13
	v_cmp_gt_f32_e32 vcc, s57, v13
	s_nop 1
	v_cndmask_b32_e32 v13, v13, v14, vcc
	v_rsq_f32_e32 v13, v13
	s_nop 0
	v_mul_f32_e32 v14, 0x45800000, v13
	v_cndmask_b32_e32 v14, v13, v14, vcc
	v_pk_mul_f32 v[24:25], v[36:37], v[14:15] op_sel_hi:[1,0]
	v_pk_mul_f32 v[28:29], v[34:35], v[14:15] op_sel_hi:[1,0]
	v_mul_f32_e32 v13, 0x4b800000, v12
	v_cmp_gt_f32_e32 vcc, s57, v12
	s_waitcnt vmcnt(0)
	v_pk_mul_f32 v[4:5], v[4:5], v[28:29]
	v_pk_mul_f32 v[6:7], v[6:7], v[24:25]
	global_store_dwordx4 v[52:53], v[4:7], off
	global_load_dwordx4 v[4:7], v[134:135], off offset:1024
	v_pk_mul_f32 v[24:25], v[40:41], v[14:15] op_sel_hi:[1,0]
	v_pk_mul_f32 v[28:29], v[38:39], v[14:15] op_sel_hi:[1,0]
	v_cndmask_b32_e32 v12, v12, v13, vcc
	v_rsq_f32_e32 v12, v12
	s_waitcnt vmcnt(0)
	v_pk_mul_f32 v[4:5], v[4:5], v[28:29]
	v_pk_mul_f32 v[6:7], v[6:7], v[24:25]
	global_store_dwordx4 v[52:53], v[4:7], off offset:1024
	global_load_dwordx4 v[4:7], v[134:135], off offset:2048
	v_pk_mul_f32 v[24:25], v[48:49], v[14:15] op_sel_hi:[1,0]
	v_pk_mul_f32 v[28:29], v[46:47], v[14:15] op_sel_hi:[1,0]
	v_mul_f32_e32 v13, 0x45800000, v12
	v_cndmask_b32_e32 v12, v12, v13, vcc
	v_pk_mul_f32 v[20:21], v[20:21], v[12:13] op_sel_hi:[1,0]
	v_pk_mul_f32 v[16:17], v[16:17], v[12:13] op_sel_hi:[1,0]
	v_pk_mul_f32 v[10:11], v[10:11], v[12:13] op_sel_hi:[1,0]
	v_pk_mul_f32 v[8:9], v[8:9], v[12:13] op_sel_hi:[1,0]
	v_pk_mul_f32 v[2:3], v[2:3], v[12:13] op_sel_hi:[1,0]
	v_pk_mul_f32 v[0:1], v[0:1], v[12:13] op_sel_hi:[1,0]
	s_and_b64 vcc, exec, s[6:7]
	s_mov_b64 s[6:7], -1
	s_waitcnt vmcnt(0)
	v_pk_mul_f32 v[4:5], v[4:5], v[28:29]
	v_pk_mul_f32 v[6:7], v[6:7], v[24:25]
	global_store_dwordx4 v[52:53], v[4:7], off offset:2048
	global_load_dwordx4 v[4:7], v[134:135], off offset:3072
	v_pk_mul_f32 v[24:25], v[44:45], v[14:15] op_sel_hi:[1,0]
	v_pk_mul_f32 v[14:15], v[42:43], v[14:15] op_sel_hi:[1,0]
	s_waitcnt vmcnt(0)
	v_pk_mul_f32 v[6:7], v[6:7], v[24:25]
	v_pk_mul_f32 v[4:5], v[4:5], v[14:15]
	global_store_dwordx4 v[52:53], v[4:7], off offset:3072
	global_load_dwordx4 v[4:7], v[134:135], off
	v_pk_mul_f32 v[14:15], v[22:23], v[12:13] op_sel_hi:[1,0]
	s_waitcnt vmcnt(0)
	v_pk_mul_f32 v[4:5], v[4:5], v[20:21]
	v_pk_mul_f32 v[6:7], v[6:7], v[14:15]
	global_store_dwordx4 v[26:27], v[4:7], off
	global_load_dwordx4 v[4:7], v[134:135], off offset:1024
	v_pk_mul_f32 v[14:15], v[18:19], v[12:13] op_sel_hi:[1,0]
	s_waitcnt vmcnt(0)
	v_pk_mul_f32 v[4:5], v[4:5], v[16:17]
	v_pk_mul_f32 v[6:7], v[6:7], v[14:15]
	global_store_dwordx4 v[26:27], v[4:7], off offset:1024
	global_load_dwordx4 v[4:7], v[134:135], off offset:2048
	s_waitcnt vmcnt(0)
	v_pk_mul_f32 v[4:5], v[4:5], v[8:9]
	v_pk_mul_f32 v[6:7], v[6:7], v[10:11]
	global_store_dwordx4 v[26:27], v[4:7], off offset:2048
	global_load_dwordx4 v[4:7], v[134:135], off offset:3072
	s_waitcnt vmcnt(0)
	v_pk_mul_f32 v[0:1], v[4:5], v[0:1]
	v_pk_mul_f32 v[2:3], v[6:7], v[2:3]
	global_store_dwordx4 v[26:27], v[0:3], off offset:3072
	s_cbranch_vccnz .LBB0_2507
	s_andn2_b64 vcc, exec, s[12:13]
	s_cbranch_vccnz .LBB0_2506
	s_barrier
	s_branch .LBB0_2506
